# all of: EpiGates load hoists incl. group starts, XCD barrier instead of cg sync, K-loop fragment-read software pipelining, gates+local-scan barrier removed, k_rope epilogue load hoists
# baseline (speedup 1.0000x reference)
;   DI bf16_t* xc() const { return (bf16_t*)(ws + OFF_Q1); }
;   DI float* cf() const { return (float*)(ws + OFF_CF); }
; DI float bflo(unsigned u) { return __uint_as_float(u << 16); }
; DI float bfhi(unsigned u) { return __uint_as_float(u & 0xffff0000u); }
;   DI void operator()(const f32x16 (&acc)[2][4], int mbase, int nbase, int l32, int g) const {
;     ...
;     for (int j = 0; j < 4; ++j) {
;       const int ch = ch0 + 8 * j + 4 * g;
;       const f32x4 bx = *(const f32x4*)(p->gx_b + ch), ba = *(const f32x4*)(p->ga_b + ch), cf = *(const f32x4*)(p->cf() + ch);
; #pragma unroll
;       for (int mb = 0; mb < 4; ++mb) {
;         const size_t tok = mbase + 32 * mb + l32;
;         const u32x2 xr = *(const u32x2*)(p->xc() + tok * 1024 + ch);
;         const float xv[4] = {bflo(xr.x), bfhi(xr.x), bflo(xr.y), bfhi(xr.y)};
;         f32x4 av, uv;
; #pragma unroll
;         for (int i = 0; i < 4; ++i) {
;           const float gi = __builtin_amdgcn_rcpf(1.f + __expf(-(acc[0][mb][4 * j + i] + bx[i])));
;           const float gr = __builtin_amdgcn_rcpf(1.f + __expf(-(acc[1][mb][4 * j + i] + ba[i])));
;           const float la = cf[i] * gr;
;           const float x2 = 2.f * la;
;           const float ser = -x2 * (1.f + x2 * (0.5f + x2 * (0.16666667f + x2 * (0.041666668f + x2 * 0.0083333333f))));
;           const float m2 = (x2 > -0.3f) ? ser : (1.f - __expf(x2));
;           av[i] = __expf(la);
;           uv[i] = sqrtf(fmaxf(m2, 0.f)) * gi * xv[i];
;         }
;         *(f32x4*)(p->av() + tok * 1024 + ch) = av;
;         *(f32x4*)(p->uv() + tok * 1024 + ch) = uv;
;       }
.LBB0_312:
	s_lshr_b32 s1, s46, 1
	s_and_b32 s1, s1, 0x60
	v_lshrrev_b32_e32 v160, 3, v186
	v_and_or_b32 v160, v160, 4, s1
	v_or_b32_e32 v172, s0, v160
	v_ashrrev_i32_e32 v173, 31, v172
	v_readlane_b32 s48, v252, 4
	v_lshlrev_b64 v[180:181], 2, v[172:173]
	v_readlane_b32 s50, v252, 6
	v_readlane_b32 s51, v252, 7
	s_ashr_i32 s0, s46, 1
	s_and_b32 s0, s0, 0xffffff80
	v_lshl_add_u64 v[174:175], s[50:51], 0, v[180:181]
	global_load_dwordx4 v[164:167], v[174:175], off
	s_add_i32 s0, s0, s33
	v_and_or_b32 v182, v186, 31, s0
	v_lshl_add_u64 v[168:169], s[10:11], 0, v[180:181]
	v_ashrrev_i32_e32 v183, 31, v182
	global_load_dwordx4 v[168:171], v[168:169], off
	v_lshlrev_b64 v[178:179], 11, v[182:183]
	v_lshl_add_u64 v[178:179], s[8:9], 0, v[178:179]
	v_lshl_add_u64 v[176:177], s[82:83], 0, v[180:181]
	v_lshl_add_u64 v[178:179], v[172:173], 1, v[178:179]
	global_load_dwordx4 v[160:163], v[176:177], off
	global_load_dwordx2 v[186:187], v[178:179], off
	v_readlane_b32 s49, v252, 5
	v_readlane_b32 s52, v252, 8
	v_readlane_b32 s53, v252, 9
	v_readlane_b32 s54, v252, 10
	v_readlane_b32 s55, v252, 11
	v_readlane_b32 s56, v252, 12
	v_readlane_b32 s57, v252, 13
	v_readlane_b32 s58, v252, 14
	v_readlane_b32 s59, v252, 15
	v_readlane_b32 s60, v252, 16
	v_readlane_b32 s61, v252, 17
	v_readlane_b32 s62, v252, 18
	v_readlane_b32 s63, v252, 19
	s_waitcnt vmcnt(3)
	v_add_f32_e32 v112, v112, v164
	v_mul_f32_e32 v112, 0xbfb8aa3b, v112
	v_exp_f32_e32 v112, v112
	s_nop 0
	v_add_f32_e32 v112, 1.0, v112
	v_rcp_f32_e32 v112, v112
	s_waitcnt vmcnt(2)
	v_mul_f32_e32 v112, v168, v112
	v_add_f32_e32 v190, v112, v112
	v_cmp_nlt_f32_e32 vcc, s43, v190
	s_and_saveexec_b64 s[0:1], vcc
	s_xor_b64 s[0:1], exec, s[0:1]
	v_mul_f32_e32 v184, 0x3fb8aa3b, v190
	v_exp_f32_e32 v184, v184
	s_nop 0
	v_sub_f32_e32 v184, 1.0, v184
	s_andn2_saveexec_b64 s[0:1], s[0:1]
	v_fmamk_f32 v184, v190, 0x3c088888, v188
	v_fmaak_f32 v184, v190, v184, 0x3e2aaaab
	v_fma_f32 v184, v190, v184, 0.5
	v_fma_f32 v184, v190, v184, 1.0
	v_mul_f32_e64 v184, v184, -v190
	s_or_b64 exec, exec, s[0:1]
	v_add_f32_e32 v113, v113, v165
	v_mul_f32_e32 v113, 0xbfb8aa3b, v113
	v_exp_f32_e32 v113, v113
	s_nop 0
	v_add_f32_e32 v113, 1.0, v113
	v_rcp_f32_e32 v113, v113
	s_nop 0
	v_mul_f32_e32 v113, v169, v113
	v_add_f32_e32 v191, v113, v113
	v_cmp_nlt_f32_e32 vcc, s43, v191
	s_and_saveexec_b64 s[0:1], vcc
	s_xor_b64 s[0:1], exec, s[0:1]
	v_mul_f32_e32 v190, 0x3fb8aa3b, v191
	v_exp_f32_e32 v190, v190
	s_nop 0
	v_sub_f32_e32 v190, 1.0, v190
	s_andn2_saveexec_b64 s[0:1], s[0:1]
	v_fmamk_f32 v190, v191, 0x3c088888, v188
	v_fmaak_f32 v190, v191, v190, 0x3e2aaaab
	v_fma_f32 v190, v191, v190, 0.5
	v_fma_f32 v190, v191, v190, 1.0
	v_mul_f32_e64 v190, v190, -v191
	s_or_b64 exec, exec, s[0:1]
	v_add_f32_e32 v114, v114, v166
	v_mul_f32_e32 v114, 0xbfb8aa3b, v114
	v_exp_f32_e32 v114, v114
	s_nop 0
	v_add_f32_e32 v114, 1.0, v114
	v_rcp_f32_e32 v114, v114
	s_nop 0
	v_mul_f32_e32 v114, v170, v114
	v_add_f32_e32 v192, v114, v114
	v_cmp_nlt_f32_e32 vcc, s43, v192
	s_and_saveexec_b64 s[0:1], vcc
	s_xor_b64 s[0:1], exec, s[0:1]
	v_mul_f32_e32 v191, 0x3fb8aa3b, v192
	v_exp_f32_e32 v191, v191
	s_nop 0
	v_sub_f32_e32 v191, 1.0, v191
	s_andn2_saveexec_b64 s[0:1], s[0:1]
	v_fmamk_f32 v191, v192, 0x3c088888, v188
	v_fmaak_f32 v191, v192, v191, 0x3e2aaaab
	v_fma_f32 v191, v192, v191, 0.5
	v_fma_f32 v191, v192, v191, 1.0
	v_mul_f32_e64 v191, v191, -v192
	s_or_b64 exec, exec, s[0:1]
	v_add_f32_e32 v115, v115, v167
	v_mul_f32_e32 v115, 0xbfb8aa3b, v115
	v_exp_f32_e32 v115, v115
	s_nop 0
	v_add_f32_e32 v115, 1.0, v115
	v_rcp_f32_e32 v115, v115
	s_nop 0
	v_mul_f32_e32 v115, v171, v115
	v_add_f32_e32 v193, v115, v115
	v_cmp_nlt_f32_e32 vcc, s43, v193
	s_and_saveexec_b64 s[0:1], vcc
	s_xor_b64 s[0:1], exec, s[0:1]
	v_mul_f32_e32 v192, 0x3fb8aa3b, v193
	v_exp_f32_e32 v192, v192
	s_nop 0
	v_sub_f32_e32 v192, 1.0, v192
	s_andn2_saveexec_b64 s[0:1], s[0:1]
	v_fmamk_f32 v192, v193, 0x3c088888, v188
	v_fmaak_f32 v192, v193, v192, 0x3e2aaaab
	v_fma_f32 v192, v193, v192, 0.5
	v_fma_f32 v192, v193, v192, 1.0
	v_mul_f32_e64 v192, v192, -v193
	s_or_b64 exec, exec, s[0:1]
	v_max_f32_e32 v184, v184, v184
	v_max_f32_e32 v184, 0, v184
	v_mul_f32_e32 v193, 0x4f800000, v184
	v_cmp_gt_f32_e32 vcc, s44, v184
	s_waitcnt vmcnt(1)
	v_add_f32_e32 v96, v96, v160
	v_mul_f32_e32 v96, 0xbfb8aa3b, v96
	v_cndmask_b32_e32 v184, v184, v193, vcc
	v_sqrt_f32_e32 v193, v184
	v_exp_f32_e32 v96, v96
	v_add_f32_e32 v97, v97, v161
	v_mul_f32_e32 v97, 0xbfb8aa3b, v97
	v_add_u32_e32 v194, -1, v193
	v_fma_f32 v195, -v194, v193, v184
	v_cmp_ge_f32_e64 s[0:1], 0, v195
	v_add_u32_e32 v195, 1, v193
	v_add_f32_e32 v96, 1.0, v96
	v_cndmask_b32_e64 v194, v193, v194, s[0:1]
	v_fma_f32 v193, -v195, v193, v184
	v_cmp_lt_f32_e64 s[0:1], 0, v193
	v_rcp_f32_e32 v96, v96
	v_exp_f32_e32 v97, v97
	v_cndmask_b32_e64 v193, v194, v195, s[0:1]
	v_mul_f32_e32 v194, 0x37800000, v193
	v_cndmask_b32_e32 v193, v193, v194, vcc
	v_cmp_class_f32_e32 vcc, v184, v189
	v_lshlrev_b64 v[198:199], 10, v[182:183]
	s_waitcnt vmcnt(0)
;   DI bf16_t* xc() const { return (bf16_t*)(ws + OFF_Q1); }
;   DI float* cf() const { return (float*)(ws + OFF_CF); }
; DI float bflo(unsigned u) { return __uint_as_float(u << 16); }
; DI float bfhi(unsigned u) { return __uint_as_float(u & 0xffff0000u); }
;   DI void operator()(const f32x16 (&acc)[2][4], int mbase, int nbase, int l32, int g) const {
;     ...
;       const f32x4 bx = *(const f32x4*)(p->gx_b + ch), ba = *(const f32x4*)(p->ga_b + ch), cf = *(const f32x4*)(p->cf() + ch);
; #pragma unroll
;       for (int mb = 0; mb < 4; ++mb) {
;         const size_t tok = mbase + 32 * mb + l32;
;         const u32x2 xr = *(const u32x2*)(p->xc() + tok * 1024 + ch);
;         const float xv[4] = {bflo(xr.x), bfhi(xr.x), bflo(xr.y), bfhi(xr.y)};
;         f32x4 av, uv;
; #pragma unroll
;         for (int i = 0; i < 4; ++i) {
;           const float gi = __builtin_amdgcn_rcpf(1.f + __expf(-(acc[0][mb][4 * j + i] + bx[i])));
;           const float gr = __builtin_amdgcn_rcpf(1.f + __expf(-(acc[1][mb][4 * j + i] + ba[i])));
;           const float la = cf[i] * gr;
;           const float x2 = 2.f * la;
;           const float ser = -x2 * (1.f + x2 * (0.5f + x2 * (0.16666667f + x2 * (0.041666668f + x2 * 0.0083333333f))));
;           const float m2 = (x2 > -0.3f) ? ser : (1.f - __expf(x2));
;           av[i] = __expf(la);
;           uv[i] = sqrtf(fmaxf(m2, 0.f)) * gi * xv[i];
;         }
;         *(f32x4*)(p->av() + tok * 1024 + ch) = av;
;         *(f32x4*)(p->uv() + tok * 1024 + ch) = uv;
;       }
	v_lshlrev_b32_e32 v183, 16, v186
	v_cndmask_b32_e32 v184, v193, v184, vcc
	v_mul_f32_e32 v96, v96, v184
	v_mul_f32_e32 v194, v96, v183
	v_add_f32_e32 v96, 1.0, v97
	v_max_f32_e32 v97, v190, v190
	v_max_f32_e32 v97, 0, v97
	v_mul_f32_e32 v183, 0x4f800000, v97
	v_cmp_gt_f32_e32 vcc, s44, v97
	v_and_b32_e32 v184, 0xffff0000, v186
	v_rcp_f32_e32 v96, v96
	v_cndmask_b32_e32 v97, v97, v183, vcc
	v_sqrt_f32_e32 v183, v97
	v_add_f32_e32 v98, v98, v162
	v_mul_f32_e32 v98, 0xbfb8aa3b, v98
	v_exp_f32_e32 v98, v98
	v_add_u32_e32 v186, -1, v183
	v_fma_f32 v190, -v186, v183, v97
	v_cmp_ge_f32_e64 s[0:1], 0, v190
	v_add_u32_e32 v190, 1, v183
	v_add_f32_e32 v99, v99, v163
	v_cndmask_b32_e64 v186, v183, v186, s[0:1]
	v_fma_f32 v183, -v190, v183, v97
	v_cmp_lt_f32_e64 s[0:1], 0, v183
	v_mul_f32_e32 v99, 0xbfb8aa3b, v99
	v_exp_f32_e32 v99, v99
	v_cndmask_b32_e64 v183, v186, v190, s[0:1]
	v_mul_f32_e32 v186, 0x37800000, v183
	v_cndmask_b32_e32 v183, v183, v186, vcc
	v_cmp_class_f32_e32 vcc, v97, v189
	v_mul_f32_e32 v112, 0x3fb8aa3b, v112
	v_mul_f32_e32 v113, 0x3fb8aa3b, v113
	v_cndmask_b32_e32 v97, v183, v97, vcc
	v_mul_f32_e32 v96, v96, v97
	v_max_f32_e32 v97, v191, v191
	v_max_f32_e32 v97, 0, v97
	v_mul_f32_e32 v195, v96, v184
	v_add_f32_e32 v96, 1.0, v98
	v_mul_f32_e32 v98, 0x4f800000, v97
	v_cmp_gt_f32_e32 vcc, s44, v97
	v_rcp_f32_e32 v96, v96
	v_lshlrev_b32_e32 v183, 16, v187
	v_cndmask_b32_e32 v97, v97, v98, vcc
	v_sqrt_f32_e32 v98, v97
	v_mul_f32_e32 v114, 0x3fb8aa3b, v114
	v_mul_f32_e32 v115, 0x3fb8aa3b, v115
	v_exp_f32_e32 v112, v112
	v_add_u32_e32 v184, -1, v98
	v_fma_f32 v186, -v184, v98, v97
	v_cmp_ge_f32_e64 s[0:1], 0, v186
	v_add_u32_e32 v186, 1, v98
	v_exp_f32_e32 v113, v113
	v_cndmask_b32_e64 v184, v98, v184, s[0:1]
	v_fma_f32 v98, -v186, v98, v97
	v_cmp_lt_f32_e64 s[0:1], 0, v98
	v_exp_f32_e32 v114, v114
	v_exp_f32_e32 v115, v115
	v_cndmask_b32_e64 v98, v184, v186, s[0:1]
	v_mul_f32_e32 v184, 0x37800000, v98
	v_cndmask_b32_e32 v98, v98, v184, vcc
	v_cmp_class_f32_e32 vcc, v97, v189
	v_or_b32_e32 v186, 32, v182
	v_add_f32_e32 v80, v80, v164
	v_cndmask_b32_e32 v97, v98, v97, vcc
	v_mul_f32_e32 v96, v96, v97
	v_max_f32_e32 v97, v192, v192
	v_max_f32_e32 v97, 0, v97
	v_mul_f32_e32 v98, 0x4f800000, v97
	v_cmp_gt_f32_e32 vcc, s44, v97
	v_mul_f32_e32 v196, v96, v183
	v_add_f32_e32 v96, 1.0, v99
	v_cndmask_b32_e32 v97, v97, v98, vcc
	v_sqrt_f32_e32 v98, v97
	v_rcp_f32_e32 v96, v96
	v_and_b32_e32 v99, 0xffff0000, v187
	v_ashrrev_i32_e32 v187, 31, v186
	v_add_u32_e32 v183, -1, v98
	v_fma_f32 v184, -v183, v98, v97
	v_cmp_ge_f32_e64 s[0:1], 0, v184
	v_add_u32_e32 v184, 1, v98
	v_mul_f32_e32 v80, 0xbfb8aa3b, v80
	v_cndmask_b32_e64 v183, v98, v183, s[0:1]
	v_fma_f32 v98, -v184, v98, v97
	v_cmp_lt_f32_e64 s[0:1], 0, v98
	v_exp_f32_e32 v80, v80
	s_nop 0
	v_cndmask_b32_e64 v98, v183, v184, s[0:1]
	v_mul_f32_e32 v183, 0x37800000, v98
	v_cndmask_b32_e32 v98, v98, v183, vcc
	v_cmp_class_f32_e32 vcc, v97, v189
	v_add_f32_e32 v80, 1.0, v80
	v_rcp_f32_e32 v80, v80
	v_cndmask_b32_e32 v97, v98, v97, vcc
	v_mul_f32_e32 v96, v96, v97
	v_mul_f32_e32 v197, v96, v99
	v_lshlrev_b64 v[98:99], 2, v[198:199]
	v_lshl_add_u64 v[96:97], s[20:21], 0, v[98:99]
	v_lshl_add_u64 v[96:97], v[96:97], 0, v[180:181]
	v_or_b32_e32 v208, 32, v182
	v_ashrrev_i32_e32 v209, 31, v208
	v_lshlrev_b64 v[208:209], 11, v[208:209]
	v_lshl_add_u64 v[208:209], s[8:9], 0, v[208:209]
	v_lshl_add_u64 v[208:209], v[172:173], 1, v[208:209]
	global_load_dwordx2 v[210:211], v[208:209], off
	global_store_dwordx4 v[96:97], v[112:115], off
	v_lshl_add_u64 v[98:99], s[12:13], 0, v[98:99]
	v_lshl_add_u64 v[98:99], v[98:99], 0, v[180:181]
	v_lshlrev_b64 v[112:113], 11, v[186:187]
	v_lshl_add_u64 v[112:113], s[8:9], 0, v[112:113]
	global_store_dwordx4 v[98:99], v[194:197], off
	v_lshl_add_u64 v[112:113], v[172:173], 1, v[112:113]
	v_mul_f32_e32 v80, v168, v80
	v_add_f32_e32 v184, v80, v80
	v_cmp_nlt_f32_e32 vcc, s43, v184
	s_and_saveexec_b64 s[0:1], vcc
	s_xor_b64 s[0:1], exec, s[0:1]
	v_mul_f32_e32 v183, 0x3fb8aa3b, v184
	v_exp_f32_e32 v183, v183
	s_nop 0
	v_sub_f32_e32 v183, 1.0, v183
	s_andn2_saveexec_b64 s[0:1], s[0:1]
	v_fmamk_f32 v183, v184, 0x3c088888, v188
	v_fmaak_f32 v183, v184, v183, 0x3e2aaaab
	v_fma_f32 v183, v184, v183, 0.5
	v_fma_f32 v183, v184, v183, 1.0
	v_mul_f32_e64 v183, v183, -v184
	s_or_b64 exec, exec, s[0:1]
	v_add_f32_e32 v81, v81, v165
	v_mul_f32_e32 v81, 0xbfb8aa3b, v81
	v_exp_f32_e32 v81, v81
	s_nop 0
	v_add_f32_e32 v81, 1.0, v81
	v_rcp_f32_e32 v81, v81
	s_nop 0
	v_mul_f32_e32 v81, v169, v81
	v_add_f32_e32 v190, v81, v81
	v_cmp_nlt_f32_e32 vcc, s43, v190
	s_and_saveexec_b64 s[0:1], vcc
	s_xor_b64 s[0:1], exec, s[0:1]
	v_mul_f32_e32 v184, 0x3fb8aa3b, v190
	v_exp_f32_e32 v184, v184
	s_nop 0
	v_sub_f32_e32 v184, 1.0, v184
	s_andn2_saveexec_b64 s[0:1], s[0:1]
	v_fmamk_f32 v184, v190, 0x3c088888, v188
	v_fmaak_f32 v184, v190, v184, 0x3e2aaaab
	v_fma_f32 v184, v190, v184, 0.5
	v_fma_f32 v184, v190, v184, 1.0
	v_mul_f32_e64 v184, v184, -v190
	s_or_b64 exec, exec, s[0:1]
	v_add_f32_e32 v82, v82, v166
	v_mul_f32_e32 v82, 0xbfb8aa3b, v82
	v_exp_f32_e32 v82, v82
	s_nop 0
	v_add_f32_e32 v82, 1.0, v82
	v_rcp_f32_e32 v82, v82
	s_nop 0
	v_mul_f32_e32 v82, v170, v82
	v_add_f32_e32 v191, v82, v82
	v_cmp_nlt_f32_e32 vcc, s43, v191
	s_and_saveexec_b64 s[0:1], vcc
	s_xor_b64 s[0:1], exec, s[0:1]
	v_mul_f32_e32 v190, 0x3fb8aa3b, v191
	v_exp_f32_e32 v190, v190
	s_nop 0
	v_sub_f32_e32 v190, 1.0, v190
	s_andn2_saveexec_b64 s[0:1], s[0:1]
	v_fmamk_f32 v190, v191, 0x3c088888, v188
	v_fmaak_f32 v190, v191, v190, 0x3e2aaaab
	v_fma_f32 v190, v191, v190, 0.5
	v_fma_f32 v190, v191, v190, 1.0
	v_mul_f32_e64 v190, v190, -v191
;   DI bf16_t* xc() const { return (bf16_t*)(ws + OFF_Q1); }
;   DI float* cf() const { return (float*)(ws + OFF_CF); }
; DI float bflo(unsigned u) { return __uint_as_float(u << 16); }
; DI float bfhi(unsigned u) { return __uint_as_float(u & 0xffff0000u); }
;   DI void operator()(const f32x16 (&acc)[2][4], int mbase, int nbase, int l32, int g) const {
;     ...
;       const f32x4 bx = *(const f32x4*)(p->gx_b + ch), ba = *(const f32x4*)(p->ga_b + ch), cf = *(const f32x4*)(p->cf() + ch);
; #pragma unroll
;       for (int mb = 0; mb < 4; ++mb) {
;         const size_t tok = mbase + 32 * mb + l32;
;         const u32x2 xr = *(const u32x2*)(p->xc() + tok * 1024 + ch);
;         const float xv[4] = {bflo(xr.x), bfhi(xr.x), bflo(xr.y), bfhi(xr.y)};
;         f32x4 av, uv;
; #pragma unroll
;         for (int i = 0; i < 4; ++i) {
;           const float gi = __builtin_amdgcn_rcpf(1.f + __expf(-(acc[0][mb][4 * j + i] + bx[i])));
;           const float gr = __builtin_amdgcn_rcpf(1.f + __expf(-(acc[1][mb][4 * j + i] + ba[i])));
;           const float la = cf[i] * gr;
;           const float x2 = 2.f * la;
;           const float ser = -x2 * (1.f + x2 * (0.5f + x2 * (0.16666667f + x2 * (0.041666668f + x2 * 0.0083333333f))));
;           const float m2 = (x2 > -0.3f) ? ser : (1.f - __expf(x2));
;           av[i] = __expf(la);
;           uv[i] = sqrtf(fmaxf(m2, 0.f)) * gi * xv[i];
;         }
;         *(f32x4*)(p->av() + tok * 1024 + ch) = av;
;         *(f32x4*)(p->uv() + tok * 1024 + ch) = uv;
;       }
	s_or_b64 exec, exec, s[0:1]
	v_add_f32_e32 v83, v83, v167
	v_mul_f32_e32 v83, 0xbfb8aa3b, v83
	v_exp_f32_e32 v83, v83
	s_nop 0
	v_add_f32_e32 v83, 1.0, v83
	v_rcp_f32_e32 v83, v83
	s_nop 0
	v_mul_f32_e32 v83, v171, v83
	v_add_f32_e32 v192, v83, v83
	v_cmp_nlt_f32_e32 vcc, s43, v192
	s_and_saveexec_b64 s[0:1], vcc
	s_xor_b64 s[0:1], exec, s[0:1]
	v_mul_f32_e32 v191, 0x3fb8aa3b, v192
	v_exp_f32_e32 v191, v191
	s_nop 0
	v_sub_f32_e32 v191, 1.0, v191
	s_andn2_saveexec_b64 s[0:1], s[0:1]
	v_fmamk_f32 v191, v192, 0x3c088888, v188
	v_fmaak_f32 v191, v192, v191, 0x3e2aaaab
	v_fma_f32 v191, v192, v191, 0.5
	v_fma_f32 v191, v192, v191, 1.0
	v_mul_f32_e64 v191, v191, -v192
	s_or_b64 exec, exec, s[0:1]
	v_max_f32_e32 v183, v183, v183
	v_max_f32_e32 v183, 0, v183
	v_mul_f32_e32 v193, 0x4f800000, v183
	v_cmp_gt_f32_e32 vcc, s44, v183
	v_add_f32_e32 v64, v64, v160
	v_mul_f32_e32 v64, 0xbfb8aa3b, v64
	v_cndmask_b32_e32 v183, v183, v193, vcc
	v_sqrt_f32_e32 v193, v183
	v_exp_f32_e32 v64, v64
	v_add_f32_e32 v65, v65, v161
	v_mul_f32_e32 v65, 0xbfb8aa3b, v65
	v_add_u32_e32 v194, -1, v193
	v_fma_f32 v195, -v194, v193, v183
	v_cmp_ge_f32_e64 s[0:1], 0, v195
	v_add_u32_e32 v195, 1, v193
	v_add_f32_e32 v64, 1.0, v64
	v_cndmask_b32_e64 v194, v193, v194, s[0:1]
	v_fma_f32 v193, -v195, v193, v183
	v_cmp_lt_f32_e64 s[0:1], 0, v193
	v_rcp_f32_e32 v64, v64
	v_exp_f32_e32 v65, v65
	v_cndmask_b32_e64 v193, v194, v195, s[0:1]
	v_mul_f32_e32 v194, 0x37800000, v193
	v_cndmask_b32_e32 v193, v193, v194, vcc
	v_cmp_class_f32_e32 vcc, v183, v189
	s_waitcnt vmcnt(2)
	v_mov_b32_e32 v114, v210
	v_mov_b32_e32 v115, v211
	v_lshlrev_b32_e32 v192, 16, v114
	v_add_f32_e32 v66, v66, v162
	v_cndmask_b32_e32 v183, v193, v183, vcc
	v_mul_f32_e32 v64, v64, v183
	v_mul_f32_e32 v192, v64, v192
	v_add_f32_e32 v64, 1.0, v65
	v_max_f32_e32 v65, v184, v184
	v_max_f32_e32 v65, 0, v65
	v_mul_f32_e32 v183, 0x4f800000, v65
	v_cmp_gt_f32_e32 vcc, s44, v65
	v_rcp_f32_e32 v64, v64
	v_mul_f32_e32 v66, 0xbfb8aa3b, v66
	v_cndmask_b32_e32 v65, v65, v183, vcc
	v_sqrt_f32_e32 v183, v65
	v_exp_f32_e32 v66, v66
	v_and_b32_e32 v114, 0xffff0000, v114
	v_add_f32_e32 v67, v67, v163
	v_add_u32_e32 v184, -1, v183
	v_fma_f32 v193, -v184, v183, v65
	v_cmp_ge_f32_e64 s[0:1], 0, v193
	v_add_u32_e32 v193, 1, v183
	v_mul_f32_e32 v67, 0xbfb8aa3b, v67
	v_cndmask_b32_e64 v184, v183, v184, s[0:1]
	v_fma_f32 v183, -v193, v183, v65
	v_cmp_lt_f32_e64 s[0:1], 0, v183
	v_exp_f32_e32 v67, v67
	v_mul_f32_e32 v80, 0x3fb8aa3b, v80
	v_cndmask_b32_e64 v183, v184, v193, s[0:1]
	v_mul_f32_e32 v184, 0x37800000, v183
	v_cndmask_b32_e32 v183, v183, v184, vcc
	v_cmp_class_f32_e32 vcc, v65, v189
	v_mul_f32_e32 v81, 0x3fb8aa3b, v81
	v_mul_f32_e32 v82, 0x3fb8aa3b, v82
	v_cndmask_b32_e32 v65, v183, v65, vcc
	v_mul_f32_e32 v64, v64, v65
	v_max_f32_e32 v65, v190, v190
	v_max_f32_e32 v65, 0, v65
	v_mul_f32_e32 v193, v64, v114
	v_add_f32_e32 v64, 1.0, v66
	v_mul_f32_e32 v66, 0x4f800000, v65
	v_cmp_gt_f32_e32 vcc, s44, v65
	v_rcp_f32_e32 v64, v64
	v_lshlrev_b32_e32 v114, 16, v115
	v_cndmask_b32_e32 v65, v65, v66, vcc
	v_sqrt_f32_e32 v66, v65
	v_mul_f32_e32 v83, 0x3fb8aa3b, v83
	v_lshlrev_b64 v[186:187], 10, v[186:187]
	v_exp_f32_e32 v80, v80
	v_add_u32_e32 v183, -1, v66
	v_fma_f32 v184, -v183, v66, v65
	v_cmp_ge_f32_e64 s[0:1], 0, v184
	v_add_u32_e32 v184, 1, v66
	v_exp_f32_e32 v81, v81
	v_cndmask_b32_e64 v183, v66, v183, s[0:1]
	v_fma_f32 v66, -v184, v66, v65
	v_cmp_lt_f32_e64 s[0:1], 0, v66
	v_exp_f32_e32 v82, v82
	v_exp_f32_e32 v83, v83
	v_cndmask_b32_e64 v66, v183, v184, s[0:1]
	v_mul_f32_e32 v183, 0x37800000, v66
	v_cndmask_b32_e32 v66, v66, v183, vcc
	v_cmp_class_f32_e32 vcc, v65, v189
	v_add_f32_e32 v48, v48, v164
	v_mul_f32_e32 v48, 0xbfb8aa3b, v48
	v_cndmask_b32_e32 v65, v66, v65, vcc
	v_mul_f32_e32 v64, v64, v65
	v_max_f32_e32 v65, v191, v191
	v_max_f32_e32 v65, 0, v65
	v_mul_f32_e32 v66, 0x4f800000, v65
	v_cmp_gt_f32_e32 vcc, s44, v65
	v_mul_f32_e32 v194, v64, v114
	v_add_f32_e32 v64, 1.0, v67
	v_cndmask_b32_e32 v65, v65, v66, vcc
	v_sqrt_f32_e32 v66, v65
	v_and_b32_e32 v67, 0xffff0000, v115
	v_rcp_f32_e32 v64, v64
	v_exp_f32_e32 v48, v48
	v_add_u32_e32 v114, -1, v66
	v_fma_f32 v115, -v114, v66, v65
	v_cmp_ge_f32_e64 s[0:1], 0, v115
	v_add_u32_e32 v115, 1, v66
	v_add_f32_e32 v48, 1.0, v48
	v_cndmask_b32_e64 v114, v66, v114, s[0:1]
	v_fma_f32 v66, -v115, v66, v65
	v_cmp_lt_f32_e64 s[0:1], 0, v66
	v_rcp_f32_e32 v48, v48
	s_nop 0
	v_cndmask_b32_e64 v66, v114, v115, s[0:1]
	v_mul_f32_e32 v114, 0x37800000, v66
	v_cndmask_b32_e32 v66, v66, v114, vcc
	v_cmp_class_f32_e32 vcc, v65, v189
	v_or_b32_e32 v114, 64, v182
	v_ashrrev_i32_e32 v115, 31, v114
	v_cndmask_b32_e32 v65, v66, v65, vcc
	v_mul_f32_e32 v64, v64, v65
	v_mul_f32_e32 v195, v64, v67
	v_lshlrev_b64 v[66:67], 2, v[186:187]
	v_lshl_add_u64 v[64:65], s[20:21], 0, v[66:67]
	v_lshl_add_u64 v[64:65], v[64:65], 0, v[180:181]
	v_or_b32_e32 v208, 64, v182
	v_ashrrev_i32_e32 v209, 31, v208
	v_lshlrev_b64 v[208:209], 11, v[208:209]
	v_lshl_add_u64 v[208:209], s[8:9], 0, v[208:209]
	v_lshl_add_u64 v[208:209], v[172:173], 1, v[208:209]
	global_load_dwordx2 v[210:211], v[208:209], off
	global_store_dwordx4 v[64:65], v[80:83], off
	v_lshl_add_u64 v[66:67], s[12:13], 0, v[66:67]
	v_lshl_add_u64 v[66:67], v[66:67], 0, v[180:181]
	v_lshlrev_b64 v[80:81], 11, v[114:115]
	v_lshl_add_u64 v[80:81], s[8:9], 0, v[80:81]
	global_store_dwordx4 v[66:67], v[192:195], off
	v_lshl_add_u64 v[80:81], v[172:173], 1, v[80:81]
	v_mul_f32_e32 v48, v168, v48
	v_add_f32_e32 v184, v48, v48
	v_cmp_nlt_f32_e32 vcc, s43, v184
	s_and_saveexec_b64 s[0:1], vcc
	s_xor_b64 s[0:1], exec, s[0:1]
	v_mul_f32_e32 v183, 0x3fb8aa3b, v184
;   DI bf16_t* xc() const { return (bf16_t*)(ws + OFF_Q1); }
;   DI float* cf() const { return (float*)(ws + OFF_CF); }
; DI float bflo(unsigned u) { return __uint_as_float(u << 16); }
; DI float bfhi(unsigned u) { return __uint_as_float(u & 0xffff0000u); }
;   DI void operator()(const f32x16 (&acc)[2][4], int mbase, int nbase, int l32, int g) const {
;     ...
;       const f32x4 bx = *(const f32x4*)(p->gx_b + ch), ba = *(const f32x4*)(p->ga_b + ch), cf = *(const f32x4*)(p->cf() + ch);
; #pragma unroll
;       for (int mb = 0; mb < 4; ++mb) {
;         const size_t tok = mbase + 32 * mb + l32;
;         const u32x2 xr = *(const u32x2*)(p->xc() + tok * 1024 + ch);
;         const float xv[4] = {bflo(xr.x), bfhi(xr.x), bflo(xr.y), bfhi(xr.y)};
;         f32x4 av, uv;
; #pragma unroll
;         for (int i = 0; i < 4; ++i) {
;           const float gi = __builtin_amdgcn_rcpf(1.f + __expf(-(acc[0][mb][4 * j + i] + bx[i])));
;           const float gr = __builtin_amdgcn_rcpf(1.f + __expf(-(acc[1][mb][4 * j + i] + ba[i])));
;           const float la = cf[i] * gr;
;           const float x2 = 2.f * la;
;           const float ser = -x2 * (1.f + x2 * (0.5f + x2 * (0.16666667f + x2 * (0.041666668f + x2 * 0.0083333333f))));
;           const float m2 = (x2 > -0.3f) ? ser : (1.f - __expf(x2));
;           av[i] = __expf(la);
;           uv[i] = sqrtf(fmaxf(m2, 0.f)) * gi * xv[i];
;         }
;         *(f32x4*)(p->av() + tok * 1024 + ch) = av;
;         *(f32x4*)(p->uv() + tok * 1024 + ch) = uv;
;       }
	v_exp_f32_e32 v183, v183
	s_nop 0
	v_sub_f32_e32 v183, 1.0, v183
	s_andn2_saveexec_b64 s[0:1], s[0:1]
	v_fmamk_f32 v183, v184, 0x3c088888, v188
	v_fmaak_f32 v183, v184, v183, 0x3e2aaaab
	v_fma_f32 v183, v184, v183, 0.5
	v_fma_f32 v183, v184, v183, 1.0
	v_mul_f32_e64 v183, v183, -v184
	s_or_b64 exec, exec, s[0:1]
	v_add_f32_e32 v49, v49, v165
	v_mul_f32_e32 v49, 0xbfb8aa3b, v49
	v_exp_f32_e32 v49, v49
	s_nop 0
	v_add_f32_e32 v49, 1.0, v49
	v_rcp_f32_e32 v49, v49
	s_nop 0
	v_mul_f32_e32 v49, v169, v49
	v_add_f32_e32 v186, v49, v49
	v_cmp_nlt_f32_e32 vcc, s43, v186
	s_and_saveexec_b64 s[0:1], vcc
	s_xor_b64 s[0:1], exec, s[0:1]
	v_mul_f32_e32 v184, 0x3fb8aa3b, v186
	v_exp_f32_e32 v184, v184
	s_nop 0
	v_sub_f32_e32 v184, 1.0, v184
	s_andn2_saveexec_b64 s[0:1], s[0:1]
	v_fmamk_f32 v184, v186, 0x3c088888, v188
	v_fmaak_f32 v184, v186, v184, 0x3e2aaaab
	v_fma_f32 v184, v186, v184, 0.5
	v_fma_f32 v184, v186, v184, 1.0
	v_mul_f32_e64 v184, v184, -v186
	s_or_b64 exec, exec, s[0:1]
	v_add_f32_e32 v50, v50, v166
	v_mul_f32_e32 v50, 0xbfb8aa3b, v50
	v_exp_f32_e32 v50, v50
	s_nop 0
	v_add_f32_e32 v50, 1.0, v50
	v_rcp_f32_e32 v50, v50
	s_nop 0
	v_mul_f32_e32 v50, v170, v50
	v_add_f32_e32 v187, v50, v50
	v_cmp_nlt_f32_e32 vcc, s43, v187
	s_and_saveexec_b64 s[0:1], vcc
	s_xor_b64 s[0:1], exec, s[0:1]
	v_mul_f32_e32 v186, 0x3fb8aa3b, v187
	v_exp_f32_e32 v186, v186
	s_nop 0
	v_sub_f32_e32 v186, 1.0, v186
	s_andn2_saveexec_b64 s[0:1], s[0:1]
	v_fmamk_f32 v186, v187, 0x3c088888, v188
	v_fmaak_f32 v186, v187, v186, 0x3e2aaaab
	v_fma_f32 v186, v187, v186, 0.5
	v_fma_f32 v186, v187, v186, 1.0
	v_mul_f32_e64 v186, v186, -v187
	s_or_b64 exec, exec, s[0:1]
	v_add_f32_e32 v51, v51, v167
	v_mul_f32_e32 v51, 0xbfb8aa3b, v51
	v_exp_f32_e32 v51, v51
	s_nop 0
	v_add_f32_e32 v51, 1.0, v51
	v_rcp_f32_e32 v51, v51
	s_nop 0
	v_mul_f32_e32 v51, v171, v51
	v_add_f32_e32 v190, v51, v51
	v_cmp_nlt_f32_e32 vcc, s43, v190
	s_and_saveexec_b64 s[0:1], vcc
	s_xor_b64 s[0:1], exec, s[0:1]
	v_mul_f32_e32 v187, 0x3fb8aa3b, v190
	v_exp_f32_e32 v187, v187
	s_nop 0
	v_sub_f32_e32 v187, 1.0, v187
	s_andn2_saveexec_b64 s[0:1], s[0:1]
	v_fmamk_f32 v187, v190, 0x3c088888, v188
	v_fmaak_f32 v187, v190, v187, 0x3e2aaaab
	v_fma_f32 v187, v190, v187, 0.5
	v_fma_f32 v187, v190, v187, 1.0
	v_mul_f32_e64 v187, v187, -v190
	s_or_b64 exec, exec, s[0:1]
	v_max_f32_e32 v183, v183, v183
	v_add_f32_e32 v32, v32, v160
	v_max_f32_e32 v183, 0, v183
	v_mul_f32_e32 v32, 0xbfb8aa3b, v32
	v_mul_f32_e32 v191, 0x4f800000, v183
	v_cmp_gt_f32_e32 vcc, s44, v183
	v_exp_f32_e32 v32, v32
	v_add_f32_e32 v33, v33, v161
	v_cndmask_b32_e32 v183, v183, v191, vcc
	v_sqrt_f32_e32 v191, v183
	v_add_f32_e32 v32, 1.0, v32
	v_rcp_f32_e32 v192, v32
	v_mul_f32_e32 v32, 0x3fb8aa3b, v48
	v_add_u32_e32 v48, -1, v191
	v_fma_f32 v193, -v48, v191, v183
	v_cmp_ge_f32_e64 s[0:1], 0, v193
	v_add_u32_e32 v193, 1, v191
	v_mul_f32_e32 v33, 0xbfb8aa3b, v33
	v_cndmask_b32_e64 v48, v191, v48, s[0:1]
	v_fma_f32 v191, -v193, v191, v183
	v_cmp_lt_f32_e64 s[0:1], 0, v191
	v_exp_f32_e32 v33, v33
	s_waitcnt vmcnt(2)
	v_mov_b32_e32 v82, v210
	v_mov_b32_e32 v83, v211
	v_lshlrev_b32_e32 v190, 16, v82
	v_cndmask_b32_e64 v48, v48, v193, s[0:1]
	v_mul_f32_e32 v191, 0x37800000, v48
	v_cndmask_b32_e32 v48, v48, v191, vcc
	v_cmp_class_f32_e32 vcc, v183, v189
	v_add_f32_e32 v33, 1.0, v33
	v_add_f32_e32 v34, v34, v162
	v_cndmask_b32_e32 v48, v48, v183, vcc
	v_mul_f32_e32 v48, v192, v48
	v_mul_f32_e32 v190, v48, v190
	v_rcp_f32_e32 v48, v33
	v_max_f32_e32 v33, v184, v184
	v_max_f32_e32 v33, 0, v33
	v_mul_f32_e32 v183, 0x4f800000, v33
	v_cmp_gt_f32_e32 vcc, s44, v33
	v_mul_f32_e32 v34, 0xbfb8aa3b, v34
	v_exp_f32_e32 v34, v34
	v_cndmask_b32_e32 v183, v33, v183, vcc
	v_sqrt_f32_e32 v184, v183
	v_mul_f32_e32 v33, 0x3fb8aa3b, v49
	v_and_b32_e32 v82, 0xffff0000, v82
	v_add_f32_e32 v34, 1.0, v34
	v_add_u32_e32 v49, -1, v184
	v_fma_f32 v191, -v49, v184, v183
	v_cmp_ge_f32_e64 s[0:1], 0, v191
	v_add_u32_e32 v191, 1, v184
	v_add_f32_e32 v35, v35, v163
	v_cndmask_b32_e64 v49, v184, v49, s[0:1]
	v_fma_f32 v184, -v191, v184, v183
	v_cmp_lt_f32_e64 s[0:1], 0, v184
	v_mul_f32_e32 v35, 0xbfb8aa3b, v35
	v_exp_f32_e32 v35, v35
	v_cndmask_b32_e64 v49, v49, v191, s[0:1]
	v_mul_f32_e32 v184, 0x37800000, v49
	v_cndmask_b32_e32 v49, v49, v184, vcc
	v_cmp_class_f32_e32 vcc, v183, v189
	v_add_f32_e32 v35, 1.0, v35
	v_lshlrev_b64 v[114:115], 10, v[114:115]
	v_cndmask_b32_e32 v49, v49, v183, vcc
	v_mul_f32_e32 v48, v48, v49
	v_mul_f32_e32 v191, v48, v82
	v_rcp_f32_e32 v48, v34
	v_max_f32_e32 v34, v186, v186
	v_max_f32_e32 v34, 0, v34
	v_mul_f32_e32 v49, 0x4f800000, v34
	v_cmp_gt_f32_e32 vcc, s44, v34
	v_lshlrev_b32_e32 v183, 16, v83
	v_exp_f32_e32 v32, v32
	v_cndmask_b32_e32 v49, v34, v49, vcc
	v_sqrt_f32_e32 v82, v49
	v_mul_f32_e32 v34, 0x3fb8aa3b, v50
	v_exp_f32_e32 v33, v33
	v_exp_f32_e32 v34, v34
	v_add_u32_e32 v50, -1, v82
	v_fma_f32 v184, -v50, v82, v49
	v_cmp_ge_f32_e64 s[0:1], 0, v184
	v_add_u32_e32 v184, 1, v82
	v_add_f32_e32 v16, v16, v164
	v_cndmask_b32_e64 v50, v82, v50, s[0:1]
	v_fma_f32 v82, -v184, v82, v49
	v_cmp_lt_f32_e64 s[0:1], 0, v82
	v_mul_f32_e32 v16, 0xbfb8aa3b, v16
	v_exp_f32_e32 v16, v16
	v_cndmask_b32_e64 v50, v50, v184, s[0:1]
	v_mul_f32_e32 v82, 0x37800000, v50
	v_cndmask_b32_e32 v50, v50, v82, vcc
	v_cmp_class_f32_e32 vcc, v49, v189
	v_and_b32_e32 v82, 0xffff0000, v83
	v_add_f32_e32 v16, 1.0, v16
	v_cndmask_b32_e32 v49, v50, v49, vcc
	v_mul_f32_e32 v48, v48, v49
	v_mul_f32_e32 v192, v48, v183
	v_rcp_f32_e32 v48, v35
	v_max_f32_e32 v35, v187, v187
	v_max_f32_e32 v35, 0, v35
	v_mul_f32_e32 v49, 0x4f800000, v35
	v_cmp_gt_f32_e32 vcc, s44, v35
	v_rcp_f32_e32 v16, v16
;   DI bf16_t* xc() const { return (bf16_t*)(ws + OFF_Q1); }
;   DI float* cf() const { return (float*)(ws + OFF_CF); }
; DI float bflo(unsigned u) { return __uint_as_float(u << 16); }
; DI float bfhi(unsigned u) { return __uint_as_float(u & 0xffff0000u); }
;   DI void operator()(const f32x16 (&acc)[2][4], int mbase, int nbase, int l32, int g) const {
;     ...
;       const f32x4 bx = *(const f32x4*)(p->gx_b + ch), ba = *(const f32x4*)(p->ga_b + ch), cf = *(const f32x4*)(p->cf() + ch);
; #pragma unroll
;       for (int mb = 0; mb < 4; ++mb) {
;         const size_t tok = mbase + 32 * mb + l32;
;         const u32x2 xr = *(const u32x2*)(p->xc() + tok * 1024 + ch);
;         const float xv[4] = {bflo(xr.x), bfhi(xr.x), bflo(xr.y), bfhi(xr.y)};
;         f32x4 av, uv;
; #pragma unroll
;         for (int i = 0; i < 4; ++i) {
;           const float gi = __builtin_amdgcn_rcpf(1.f + __expf(-(acc[0][mb][4 * j + i] + bx[i])));
;           const float gr = __builtin_amdgcn_rcpf(1.f + __expf(-(acc[1][mb][4 * j + i] + ba[i])));
;           const float la = cf[i] * gr;
;           const float x2 = 2.f * la;
;           const float ser = -x2 * (1.f + x2 * (0.5f + x2 * (0.16666667f + x2 * (0.041666668f + x2 * 0.0083333333f))));
;           const float m2 = (x2 > -0.3f) ? ser : (1.f - __expf(x2));
;           av[i] = __expf(la);
;           uv[i] = sqrtf(fmaxf(m2, 0.f)) * gi * xv[i];
;         }
;         *(f32x4*)(p->av() + tok * 1024 + ch) = av;
;         *(f32x4*)(p->uv() + tok * 1024 + ch) = uv;
;       }
	s_nop 0
	v_cndmask_b32_e32 v49, v35, v49, vcc
	v_sqrt_f32_e32 v50, v49
	v_mul_f32_e32 v35, 0x3fb8aa3b, v51
	v_exp_f32_e32 v35, v35
	v_mul_f32_e32 v16, v168, v16
	v_add_u32_e32 v51, -1, v50
	v_fma_f32 v83, -v51, v50, v49
	v_cmp_ge_f32_e64 s[0:1], 0, v83
	v_add_u32_e32 v83, 1, v50
	s_nop 0
	v_cndmask_b32_e64 v51, v50, v51, s[0:1]
	v_fma_f32 v50, -v83, v50, v49
	v_cmp_lt_f32_e64 s[0:1], 0, v50
	s_nop 1
	v_cndmask_b32_e64 v50, v51, v83, s[0:1]
	v_mul_f32_e32 v51, 0x37800000, v50
	v_cndmask_b32_e32 v50, v50, v51, vcc
	v_cmp_class_f32_e32 vcc, v49, v189
	s_nop 1
	v_cndmask_b32_e32 v49, v50, v49, vcc
	v_mul_f32_e32 v48, v48, v49
	v_lshlrev_b64 v[50:51], 2, v[114:115]
	v_mul_f32_e32 v193, v48, v82
	v_lshl_add_u64 v[48:49], s[20:21], 0, v[50:51]
	v_lshl_add_u64 v[48:49], v[48:49], 0, v[180:181]
	v_or_b32_e32 v208, 0x60, v182
	v_ashrrev_i32_e32 v209, 31, v208
	v_lshlrev_b64 v[208:209], 11, v[208:209]
	v_lshl_add_u64 v[208:209], s[8:9], 0, v[208:209]
	v_lshl_add_u64 v[208:209], v[172:173], 1, v[208:209]
	global_load_dwordx2 v[210:211], v[208:209], off
	global_store_dwordx4 v[48:49], v[32:35], off
	v_add_f32_e32 v115, v16, v16
	v_cmp_nlt_f32_e32 vcc, s43, v115
	v_or_b32_e32 v34, 0x60, v182
	v_lshl_add_u64 v[32:33], s[12:13], 0, v[50:51]
	v_ashrrev_i32_e32 v35, 31, v34
	v_lshl_add_u64 v[50:51], v[32:33], 0, v[180:181]
	v_lshlrev_b64 v[32:33], 11, v[34:35]
	v_lshl_add_u64 v[32:33], s[8:9], 0, v[32:33]
	global_store_dwordx4 v[50:51], v[190:193], off
	v_lshl_add_u64 v[82:83], v[172:173], 1, v[32:33]
	s_and_saveexec_b64 s[0:1], vcc
	s_xor_b64 s[0:1], exec, s[0:1]
	v_mul_f32_e32 v114, 0x3fb8aa3b, v115
	v_exp_f32_e32 v114, v114
	s_nop 0
	v_sub_f32_e32 v114, 1.0, v114
	s_andn2_saveexec_b64 s[0:1], s[0:1]
	v_fmamk_f32 v114, v115, 0x3c088888, v188
	v_fmaak_f32 v114, v115, v114, 0x3e2aaaab
	v_fma_f32 v114, v115, v114, 0.5
	v_fma_f32 v114, v115, v114, 1.0
	v_mul_f32_e64 v114, v114, -v115
	s_or_b64 exec, exec, s[0:1]
	v_add_f32_e32 v17, v17, v165
	v_mul_f32_e32 v17, 0xbfb8aa3b, v17
	v_exp_f32_e32 v17, v17
	s_nop 0
	v_add_f32_e32 v17, 1.0, v17
	v_rcp_f32_e32 v17, v17
	s_nop 0
	v_mul_f32_e32 v17, v169, v17
	v_add_f32_e32 v164, v17, v17
	v_cmp_nlt_f32_e32 vcc, s43, v164
	s_and_saveexec_b64 s[0:1], vcc
	s_xor_b64 s[0:1], exec, s[0:1]
	v_mul_f32_e32 v115, 0x3fb8aa3b, v164
	v_exp_f32_e32 v115, v115
	s_nop 0
	v_sub_f32_e32 v115, 1.0, v115
	s_andn2_saveexec_b64 s[0:1], s[0:1]
	v_fmamk_f32 v115, v164, 0x3c088888, v188
	v_fmaak_f32 v115, v164, v115, 0x3e2aaaab
	v_fma_f32 v115, v164, v115, 0.5
	v_fma_f32 v115, v164, v115, 1.0
	v_mul_f32_e64 v115, v115, -v164
	s_or_b64 exec, exec, s[0:1]
	v_add_f32_e32 v18, v18, v166
	v_mul_f32_e32 v18, 0xbfb8aa3b, v18
	v_exp_f32_e32 v18, v18
	s_nop 0
	v_add_f32_e32 v18, 1.0, v18
	v_rcp_f32_e32 v18, v18
	s_nop 0
	v_mul_f32_e32 v18, v170, v18
	v_add_f32_e32 v165, v18, v18
	v_cmp_nlt_f32_e32 vcc, s43, v165
	s_and_saveexec_b64 s[0:1], vcc
	s_xor_b64 s[0:1], exec, s[0:1]
	v_mul_f32_e32 v164, 0x3fb8aa3b, v165
	v_exp_f32_e32 v164, v164
	s_nop 0
	v_sub_f32_e32 v164, 1.0, v164
	s_andn2_saveexec_b64 s[0:1], s[0:1]
	v_fmamk_f32 v164, v165, 0x3c088888, v188
	v_fmaak_f32 v164, v165, v164, 0x3e2aaaab
	v_fma_f32 v164, v165, v164, 0.5
	v_fma_f32 v164, v165, v164, 1.0
	v_mul_f32_e64 v164, v164, -v165
	s_or_b64 exec, exec, s[0:1]
	v_add_f32_e32 v19, v19, v167
	v_mul_f32_e32 v19, 0xbfb8aa3b, v19
	v_exp_f32_e32 v19, v19
	s_nop 0
	v_add_f32_e32 v19, 1.0, v19
	v_rcp_f32_e32 v19, v19
	s_nop 0
	v_mul_f32_e32 v19, v171, v19
	v_add_f32_e32 v166, v19, v19
	v_cmp_nlt_f32_e32 vcc, s43, v166
	s_and_saveexec_b64 s[0:1], vcc
	s_xor_b64 s[0:1], exec, s[0:1]
	v_mul_f32_e32 v165, 0x3fb8aa3b, v166
	v_exp_f32_e32 v165, v165
	s_nop 0
	v_sub_f32_e32 v165, 1.0, v165
	s_andn2_saveexec_b64 s[0:1], s[0:1]
	v_fmamk_f32 v165, v166, 0x3c088888, v188
	v_fmaak_f32 v165, v166, v165, 0x3e2aaaab
	v_fma_f32 v165, v166, v165, 0.5
	v_fma_f32 v165, v166, v165, 1.0
	v_mul_f32_e64 v165, v165, -v166
	s_or_b64 exec, exec, s[0:1]
	v_max_f32_e32 v114, v114, v114
	v_add_f32_e32 v0, v0, v160
	v_max_f32_e32 v114, 0, v114
	v_mul_f32_e32 v0, 0xbfb8aa3b, v0
	v_mul_f32_e32 v166, 0x4f800000, v114
	v_cmp_gt_f32_e32 vcc, s44, v114
	v_exp_f32_e32 v0, v0
	v_add_f32_e32 v1, v1, v161
	v_cndmask_b32_e32 v114, v114, v166, vcc
	v_sqrt_f32_e32 v166, v114
	v_add_f32_e32 v0, 1.0, v0
	v_rcp_f32_e32 v167, v0
	v_mul_f32_e32 v0, 0x3fb8aa3b, v16
	v_add_u32_e32 v16, -1, v166
	v_fma_f32 v168, -v16, v166, v114
	v_cmp_ge_f32_e64 s[0:1], 0, v168
	v_add_u32_e32 v168, 1, v166
	v_mul_f32_e32 v1, 0xbfb8aa3b, v1
	v_cndmask_b32_e64 v16, v166, v16, s[0:1]
	v_fma_f32 v166, -v168, v166, v114
	v_exp_f32_e32 v1, v1
	v_cmp_lt_f32_e64 s[0:1], 0, v166
	s_waitcnt vmcnt(2)
;   DI bf16_t* xc() const { return (bf16_t*)(ws + OFF_Q1); }
;   DI float* cf() const { return (float*)(ws + OFF_CF); }
; DI float bflo(unsigned u) { return __uint_as_float(u << 16); }
; DI float bfhi(unsigned u) { return __uint_as_float(u & 0xffff0000u); }
;   DI void operator()(const f32x16 (&acc)[2][4], int mbase, int nbase, int l32, int g) const {
;     ...
;     for (int j = 0; j < 4; ++j) {
;       const int ch = ch0 + 8 * j + 4 * g;
;       const f32x4 bx = *(const f32x4*)(p->gx_b + ch), ba = *(const f32x4*)(p->ga_b + ch), cf = *(const f32x4*)(p->cf() + ch);
; #pragma unroll
;       for (int mb = 0; mb < 4; ++mb) {
;         const size_t tok = mbase + 32 * mb + l32;
;         const u32x2 xr = *(const u32x2*)(p->xc() + tok * 1024 + ch);
;         const float xv[4] = {bflo(xr.x), bfhi(xr.x), bflo(xr.y), bfhi(xr.y)};
;         f32x4 av, uv;
; #pragma unroll
;         for (int i = 0; i < 4; ++i) {
;           const float gi = __builtin_amdgcn_rcpf(1.f + __expf(-(acc[0][mb][4 * j + i] + bx[i])));
;           const float gr = __builtin_amdgcn_rcpf(1.f + __expf(-(acc[1][mb][4 * j + i] + ba[i])));
;           const float la = cf[i] * gr;
;           const float x2 = 2.f * la;
;           const float ser = -x2 * (1.f + x2 * (0.5f + x2 * (0.16666667f + x2 * (0.041666668f + x2 * 0.0083333333f))));
;           const float m2 = (x2 > -0.3f) ? ser : (1.f - __expf(x2));
;           av[i] = __expf(la);
;           uv[i] = sqrtf(fmaxf(m2, 0.f)) * gi * xv[i];
;         }
;         *(f32x4*)(p->av() + tok * 1024 + ch) = av;
;         *(f32x4*)(p->uv() + tok * 1024 + ch) = uv;
;       }
	v_mov_b32_e32 v32, v210
	v_mov_b32_e32 v33, v211
	v_lshlrev_b32_e32 v160, 16, v32
	v_add_f32_e32 v2, v2, v162
	v_cndmask_b32_e64 v16, v16, v168, s[0:1]
	v_mul_f32_e32 v166, 0x37800000, v16
	v_cndmask_b32_e32 v16, v16, v166, vcc
	v_cmp_class_f32_e32 vcc, v114, v189
	v_add_f32_e32 v1, 1.0, v1
	v_mul_f32_e32 v2, 0xbfb8aa3b, v2
	v_cndmask_b32_e32 v16, v16, v114, vcc
	v_rcp_f32_e32 v114, v1
	v_max_f32_e32 v1, v115, v115
	v_max_f32_e32 v1, 0, v1
	v_mul_f32_e32 v115, 0x4f800000, v1
	v_cmp_gt_f32_e32 vcc, s44, v1
	v_mul_f32_e32 v16, v167, v16
	v_mul_f32_e32 v16, v16, v160
	v_cndmask_b32_e32 v115, v1, v115, vcc
	v_sqrt_f32_e32 v160, v115
	v_mul_f32_e32 v1, 0x3fb8aa3b, v17
	v_exp_f32_e32 v2, v2
	v_and_b32_e32 v32, 0xffff0000, v32
	v_add_u32_e32 v17, -1, v160
	v_fma_f32 v161, -v17, v160, v115
	v_cmp_ge_f32_e64 s[0:1], 0, v161
	v_add_u32_e32 v161, 1, v160
	v_add_f32_e32 v2, 1.0, v2
	v_cndmask_b32_e64 v17, v160, v17, s[0:1]
	v_fma_f32 v160, -v161, v160, v115
	v_cmp_lt_f32_e64 s[0:1], 0, v160
	v_add_f32_e32 v3, v3, v163
	v_mul_f32_e32 v3, 0xbfb8aa3b, v3
	v_cndmask_b32_e64 v17, v17, v161, s[0:1]
	v_mul_f32_e32 v160, 0x37800000, v17
	v_cndmask_b32_e32 v17, v17, v160, vcc
	v_cmp_class_f32_e32 vcc, v115, v189
	v_exp_f32_e32 v3, v3
	v_lshlrev_b32_e32 v160, 16, v33
	v_cndmask_b32_e32 v17, v17, v115, vcc
	v_mul_f32_e32 v17, v114, v17
	v_mul_f32_e32 v17, v17, v32
	v_rcp_f32_e32 v32, v2
	v_max_f32_e32 v2, v164, v164
	v_max_f32_e32 v2, 0, v2
	v_mul_f32_e32 v114, 0x4f800000, v2
	v_cmp_gt_f32_e32 vcc, s44, v2
	v_add_f32_e32 v3, 1.0, v3
	v_lshlrev_b64 v[34:35], 10, v[34:35]
	v_cndmask_b32_e32 v114, v2, v114, vcc
	v_sqrt_f32_e32 v115, v114
	v_mul_f32_e32 v2, 0x3fb8aa3b, v18
	v_exp_f32_e32 v0, v0
	v_exp_f32_e32 v1, v1
	v_add_u32_e32 v18, -1, v115
	v_fma_f32 v161, -v18, v115, v114
	v_cmp_ge_f32_e64 s[0:1], 0, v161
	v_add_u32_e32 v161, 1, v115
	v_exp_f32_e32 v2, v2
	v_cndmask_b32_e64 v18, v115, v18, s[0:1]
	v_fma_f32 v115, -v161, v115, v114
	v_cmp_lt_f32_e64 s[0:1], 0, v115
	v_and_b32_e32 v33, 0xffff0000, v33
	s_nop 0
	v_cndmask_b32_e64 v18, v18, v161, s[0:1]
	v_mul_f32_e32 v115, 0x37800000, v18
	v_cndmask_b32_e32 v18, v18, v115, vcc
	v_cmp_class_f32_e32 vcc, v114, v189
	s_nop 1
	v_cndmask_b32_e32 v18, v18, v114, vcc
	v_mul_f32_e32 v18, v32, v18
	v_rcp_f32_e32 v32, v3
	v_max_f32_e32 v3, v165, v165
	v_max_f32_e32 v3, 0, v3
	v_mul_f32_e32 v114, 0x4f800000, v3
	v_cmp_gt_f32_e32 vcc, s44, v3
	v_mul_f32_e32 v18, v18, v160
	s_nop 0
	v_cndmask_b32_e32 v114, v3, v114, vcc
	v_sqrt_f32_e32 v115, v114
	v_mul_f32_e32 v3, 0x3fb8aa3b, v19
	v_exp_f32_e32 v3, v3
	v_add_u32_e32 v19, -1, v115
	v_fma_f32 v160, -v19, v115, v114
	v_cmp_ge_f32_e64 s[0:1], 0, v160
	v_add_u32_e32 v160, 1, v115
	s_nop 0
	v_cndmask_b32_e64 v19, v115, v19, s[0:1]
	v_fma_f32 v115, -v160, v115, v114
	v_cmp_lt_f32_e64 s[0:1], 0, v115
	s_nop 1
	v_cndmask_b32_e64 v19, v19, v160, s[0:1]
	v_mul_f32_e32 v115, 0x37800000, v19
	v_cndmask_b32_e32 v19, v19, v115, vcc
	v_cmp_class_f32_e32 vcc, v114, v189
	s_nop 1
	v_cndmask_b32_e32 v19, v19, v114, vcc
	v_mul_f32_e32 v19, v32, v19
	v_mul_f32_e32 v19, v19, v33
	v_lshlrev_b64 v[32:33], 2, v[34:35]
	v_lshl_add_u64 v[34:35], s[20:21], 0, v[32:33]
	v_lshl_add_u64 v[114:115], v[34:35], 0, v[180:181]
	global_store_dwordx4 v[114:115], v[0:3], off
	s_nop 1
	v_lshl_add_u64 v[0:1], s[12:13], 0, v[32:33]
	v_lshl_add_u64 v[160:161], v[0:1], 0, v[180:181]
	global_store_dwordx4 v[160:161], v[16:19], off
	global_load_dwordx4 v[32:35], v[174:175], off offset:32
	v_or_b32_e32 v0, 8, v172
	v_ashrrev_i32_e32 v1, 31, v0
	v_lshl_add_u64 v[0:1], v[0:1], 2, s[10:11]
	global_load_dwordx4 v[16:19], v[0:1], off
	s_nop 0
	global_load_dwordx4 v[0:3], v[176:177], off offset:32
	global_load_dwordx2 v[162:163], v[178:179], off offset:16
	s_waitcnt vmcnt(3)
	v_add_f32_e32 v116, v116, v32
	v_mul_f32_e32 v116, 0xbfb8aa3b, v116
	v_exp_f32_e32 v116, v116
	s_nop 0
	v_add_f32_e32 v116, 1.0, v116
	v_rcp_f32_e32 v116, v116
	s_waitcnt vmcnt(2)
	v_mul_f32_e32 v116, v16, v116
	v_add_f32_e32 v165, v116, v116
	v_cmp_nlt_f32_e32 vcc, s43, v165
	s_and_saveexec_b64 s[0:1], vcc
	s_xor_b64 s[0:1], exec, s[0:1]
	v_mul_f32_e32 v164, 0x3fb8aa3b, v165
	v_exp_f32_e32 v164, v164
	s_nop 0
	v_sub_f32_e32 v164, 1.0, v164
	s_andn2_saveexec_b64 s[0:1], s[0:1]
	v_fmamk_f32 v164, v165, 0x3c088888, v188
	v_fmaak_f32 v164, v165, v164, 0x3e2aaaab
	v_fma_f32 v164, v165, v164, 0.5
	v_fma_f32 v164, v165, v164, 1.0
	v_mul_f32_e64 v164, v164, -v165
	s_or_b64 exec, exec, s[0:1]
	v_add_f32_e32 v117, v117, v33
	v_mul_f32_e32 v117, 0xbfb8aa3b, v117
	v_exp_f32_e32 v117, v117
	s_nop 0
	v_add_f32_e32 v117, 1.0, v117
	v_rcp_f32_e32 v117, v117
	s_nop 0
	v_mul_f32_e32 v117, v17, v117
	v_add_f32_e32 v166, v117, v117
	v_cmp_nlt_f32_e32 vcc, s43, v166
	s_and_saveexec_b64 s[0:1], vcc
	s_xor_b64 s[0:1], exec, s[0:1]
	v_mul_f32_e32 v165, 0x3fb8aa3b, v166
	v_exp_f32_e32 v165, v165
	s_nop 0
	v_sub_f32_e32 v165, 1.0, v165
	s_andn2_saveexec_b64 s[0:1], s[0:1]
	v_fmamk_f32 v165, v166, 0x3c088888, v188
	v_fmaak_f32 v165, v166, v165, 0x3e2aaaab
	v_fma_f32 v165, v166, v165, 0.5
	v_fma_f32 v165, v166, v165, 1.0
	v_mul_f32_e64 v165, v165, -v166
	s_or_b64 exec, exec, s[0:1]
	v_add_f32_e32 v118, v118, v34
	v_mul_f32_e32 v118, 0xbfb8aa3b, v118
	v_exp_f32_e32 v118, v118
	s_nop 0
	v_add_f32_e32 v118, 1.0, v118
	v_rcp_f32_e32 v118, v118
	s_nop 0
	v_mul_f32_e32 v118, v18, v118
	v_add_f32_e32 v167, v118, v118
	v_cmp_nlt_f32_e32 vcc, s43, v167
	s_and_saveexec_b64 s[0:1], vcc
	s_xor_b64 s[0:1], exec, s[0:1]
	v_mul_f32_e32 v166, 0x3fb8aa3b, v167
	v_exp_f32_e32 v166, v166
	s_nop 0
	v_sub_f32_e32 v166, 1.0, v166
	s_andn2_saveexec_b64 s[0:1], s[0:1]
	v_fmamk_f32 v166, v167, 0x3c088888, v188
	v_fmaak_f32 v166, v167, v166, 0x3e2aaaab
	v_fma_f32 v166, v167, v166, 0.5
	v_fma_f32 v166, v167, v166, 1.0
	v_mul_f32_e64 v166, v166, -v167
	s_or_b64 exec, exec, s[0:1]
	v_add_f32_e32 v119, v119, v35
	v_mul_f32_e32 v119, 0xbfb8aa3b, v119
	v_exp_f32_e32 v119, v119
	s_nop 0
	v_add_f32_e32 v119, 1.0, v119
	v_rcp_f32_e32 v119, v119
	s_nop 0
	v_mul_f32_e32 v119, v19, v119
	v_add_f32_e32 v168, v119, v119
	v_cmp_nlt_f32_e32 vcc, s43, v168
	s_and_saveexec_b64 s[0:1], vcc
	s_xor_b64 s[0:1], exec, s[0:1]
	v_mul_f32_e32 v167, 0x3fb8aa3b, v168
	v_exp_f32_e32 v167, v167
	s_nop 0
	v_sub_f32_e32 v167, 1.0, v167
	s_andn2_saveexec_b64 s[0:1], s[0:1]
	v_fmamk_f32 v167, v168, 0x3c088888, v188
	v_fmaak_f32 v167, v168, v167, 0x3e2aaaab
	v_fma_f32 v167, v168, v167, 0.5
	v_fma_f32 v167, v168, v167, 1.0
	v_mul_f32_e64 v167, v167, -v168
	s_or_b64 exec, exec, s[0:1]
	v_max_f32_e32 v164, v164, v164
	s_waitcnt vmcnt(1)
;   DI float* cf() const { return (float*)(ws + OFF_CF); }
;   DI void operator()(const f32x16 (&acc)[2][4], int mbase, int nbase, int l32, int g) const {
;     ...
;           const float gi = __builtin_amdgcn_rcpf(1.f + __expf(-(acc[0][mb][4 * j + i] + bx[i])));
;           const float gr = __builtin_amdgcn_rcpf(1.f + __expf(-(acc[1][mb][4 * j + i] + ba[i])));
;           const float la = cf[i] * gr;
;           const float x2 = 2.f * la;
;           const float ser = -x2 * (1.f + x2 * (0.5f + x2 * (0.16666667f + x2 * (0.041666668f + x2 * 0.0083333333f))));
;           const float m2 = (x2 > -0.3f) ? ser : (1.f - __expf(x2));
;           av[i] = __expf(la);
;           uv[i] = sqrtf(fmaxf(m2, 0.f)) * gi * xv[i];
;         }
;         *(f32x4*)(p->av() + tok * 1024 + ch) = av;
;         *(f32x4*)(p->uv() + tok * 1024 + ch) = uv;
	v_add_f32_e32 v100, v100, v0
	v_max_f32_e32 v164, 0, v164
	v_mul_f32_e32 v100, 0xbfb8aa3b, v100
	v_mul_f32_e32 v169, 0x4f800000, v164
	v_cmp_gt_f32_e32 vcc, s44, v164
	v_exp_f32_e32 v100, v100
	v_add_f32_e32 v101, v101, v1
	v_cndmask_b32_e32 v164, v164, v169, vcc
	v_sqrt_f32_e32 v169, v164
	v_add_f32_e32 v100, 1.0, v100
	v_rcp_f32_e32 v170, v100
	v_mul_f32_e32 v100, 0x3fb8aa3b, v116
	v_add_u32_e32 v116, -1, v169
	v_fma_f32 v171, -v116, v169, v164
	v_cmp_ge_f32_e64 s[0:1], 0, v171
	v_add_u32_e32 v171, 1, v169
	v_mul_f32_e32 v101, 0xbfb8aa3b, v101
	v_cndmask_b32_e64 v116, v169, v116, s[0:1]
	v_fma_f32 v169, -v171, v169, v164
	v_exp_f32_e32 v101, v101
	v_cmp_lt_f32_e64 s[0:1], 0, v169
	s_waitcnt vmcnt(0)
	v_lshlrev_b32_e32 v168, 16, v162
	v_add_f32_e32 v102, v102, v2
	v_cndmask_b32_e64 v116, v116, v171, s[0:1]
	v_mul_f32_e32 v169, 0x37800000, v116
	v_cndmask_b32_e32 v116, v116, v169, vcc
	v_cmp_class_f32_e32 vcc, v164, v189
	v_add_f32_e32 v101, 1.0, v101
	v_mul_f32_e32 v102, 0xbfb8aa3b, v102
	v_cndmask_b32_e32 v116, v116, v164, vcc
	v_rcp_f32_e32 v164, v101
	v_max_f32_e32 v101, v165, v165
	v_max_f32_e32 v101, 0, v101
	v_mul_f32_e32 v165, 0x4f800000, v101
	v_cmp_gt_f32_e32 vcc, s44, v101
	v_mul_f32_e32 v116, v170, v116
	v_mul_f32_e32 v116, v116, v168
	v_cndmask_b32_e32 v165, v101, v165, vcc
	v_sqrt_f32_e32 v168, v165
	v_mul_f32_e32 v101, 0x3fb8aa3b, v117
	v_exp_f32_e32 v102, v102
	v_and_b32_e32 v162, 0xffff0000, v162
	v_add_u32_e32 v117, -1, v168
	v_fma_f32 v169, -v117, v168, v165
	v_cmp_ge_f32_e64 s[0:1], 0, v169
	v_add_u32_e32 v169, 1, v168
	v_add_f32_e32 v102, 1.0, v102
	v_cndmask_b32_e64 v117, v168, v117, s[0:1]
	v_fma_f32 v168, -v169, v168, v165
	v_cmp_lt_f32_e64 s[0:1], 0, v168
	v_add_f32_e32 v103, v103, v3
	v_mul_f32_e32 v103, 0xbfb8aa3b, v103
	v_cndmask_b32_e64 v117, v117, v169, s[0:1]
	v_mul_f32_e32 v168, 0x37800000, v117
	v_cndmask_b32_e32 v117, v117, v168, vcc
	v_cmp_class_f32_e32 vcc, v165, v189
	v_exp_f32_e32 v103, v103
	v_exp_f32_e32 v100, v100
	v_cndmask_b32_e32 v117, v117, v165, vcc
	v_mul_f32_e32 v117, v164, v117
	v_mul_f32_e32 v117, v117, v162
	v_rcp_f32_e32 v162, v102
	v_max_f32_e32 v102, v166, v166
	v_max_f32_e32 v102, 0, v102
	v_mul_f32_e32 v164, 0x4f800000, v102
	v_cmp_gt_f32_e32 vcc, s44, v102
	v_add_f32_e32 v103, 1.0, v103
	v_lshlrev_b32_e32 v166, 16, v163
	v_cndmask_b32_e32 v164, v102, v164, vcc
	v_sqrt_f32_e32 v165, v164
	v_mul_f32_e32 v102, 0x3fb8aa3b, v118
	v_exp_f32_e32 v101, v101
	v_exp_f32_e32 v102, v102
	v_add_u32_e32 v118, -1, v165
	v_fma_f32 v168, -v118, v165, v164
	v_cmp_ge_f32_e64 s[0:1], 0, v168
	v_add_u32_e32 v168, 1, v165
	v_and_b32_e32 v163, 0xffff0000, v163
	v_cndmask_b32_e64 v118, v165, v118, s[0:1]
	v_fma_f32 v165, -v168, v165, v164
	v_cmp_lt_f32_e64 s[0:1], 0, v165
	v_add_f32_e32 v84, v84, v32
	v_mul_f32_e32 v84, 0xbfb8aa3b, v84
	v_cndmask_b32_e64 v118, v118, v168, s[0:1]
	v_mul_f32_e32 v165, 0x37800000, v118
	v_cndmask_b32_e32 v118, v118, v165, vcc
	v_cmp_class_f32_e32 vcc, v164, v189
	v_exp_f32_e32 v84, v84
	s_nop 0
	v_cndmask_b32_e32 v118, v118, v164, vcc
	v_mul_f32_e32 v118, v162, v118
	v_rcp_f32_e32 v162, v103
	v_max_f32_e32 v103, v167, v167
	v_max_f32_e32 v103, 0, v103
	v_mul_f32_e32 v164, 0x4f800000, v103
	v_cmp_gt_f32_e32 vcc, s44, v103
	v_mul_f32_e32 v118, v118, v166
	v_add_f32_e32 v84, 1.0, v84
	v_cndmask_b32_e32 v164, v103, v164, vcc
	v_sqrt_f32_e32 v165, v164
	v_mul_f32_e32 v103, 0x3fb8aa3b, v119
	v_exp_f32_e32 v103, v103
	v_rcp_f32_e32 v84, v84
	v_add_u32_e32 v119, -1, v165
	v_fma_f32 v166, -v119, v165, v164
	v_cmp_ge_f32_e64 s[0:1], 0, v166
	v_add_u32_e32 v166, 1, v165
	v_mul_f32_e32 v84, v16, v84
	v_cndmask_b32_e64 v119, v165, v119, s[0:1]
	v_fma_f32 v165, -v166, v165, v164
	v_cmp_lt_f32_e64 s[0:1], 0, v165
	s_nop 1
	v_cndmask_b32_e64 v119, v119, v166, s[0:1]
	v_mul_f32_e32 v165, 0x37800000, v119
	v_cndmask_b32_e32 v119, v119, v165, vcc
	v_cmp_class_f32_e32 vcc, v164, v189
	s_nop 1
	v_cndmask_b32_e32 v119, v119, v164, vcc
	v_mul_f32_e32 v119, v162, v119
	v_mul_f32_e32 v119, v119, v163
	global_load_dwordx2 v[210:211], v[112:113], off offset:16
	global_store_dwordx4 v[96:97], v[100:103], off offset:32
	global_store_dwordx4 v[98:99], v[116:119], off offset:32
	v_add_f32_e32 v103, v84, v84
	v_cmp_nlt_f32_e32 vcc, s43, v103
	s_and_saveexec_b64 s[0:1], vcc
	s_xor_b64 s[0:1], exec, s[0:1]
	v_mul_f32_e32 v102, 0x3fb8aa3b, v103
	v_exp_f32_e32 v102, v102
	s_nop 0
	v_sub_f32_e32 v102, 1.0, v102
	s_andn2_saveexec_b64 s[0:1], s[0:1]
	v_fmamk_f32 v102, v103, 0x3c088888, v188
	v_fmaak_f32 v102, v103, v102, 0x3e2aaaab
	v_fma_f32 v102, v103, v102, 0.5
	v_fma_f32 v102, v103, v102, 1.0
	v_mul_f32_e64 v102, v102, -v103
	s_or_b64 exec, exec, s[0:1]
	v_add_f32_e32 v85, v85, v33
	v_mul_f32_e32 v85, 0xbfb8aa3b, v85
	v_exp_f32_e32 v85, v85
	s_nop 0
	v_add_f32_e32 v85, 1.0, v85
	v_rcp_f32_e32 v85, v85
	s_nop 0
	v_mul_f32_e32 v85, v17, v85
	v_add_f32_e32 v116, v85, v85
	v_cmp_nlt_f32_e32 vcc, s43, v116
	s_and_saveexec_b64 s[0:1], vcc
	s_xor_b64 s[0:1], exec, s[0:1]
	v_mul_f32_e32 v103, 0x3fb8aa3b, v116
	v_exp_f32_e32 v103, v103
	s_nop 0
	v_sub_f32_e32 v103, 1.0, v103
	s_andn2_saveexec_b64 s[0:1], s[0:1]
	v_fmamk_f32 v103, v116, 0x3c088888, v188
	v_fmaak_f32 v103, v116, v103, 0x3e2aaaab
	v_fma_f32 v103, v116, v103, 0.5
	v_fma_f32 v103, v116, v103, 1.0
	v_mul_f32_e64 v103, v103, -v116
	s_or_b64 exec, exec, s[0:1]
	v_add_f32_e32 v86, v86, v34
	v_mul_f32_e32 v86, 0xbfb8aa3b, v86
	v_exp_f32_e32 v86, v86
	s_nop 0
	v_add_f32_e32 v86, 1.0, v86
	v_rcp_f32_e32 v86, v86
	s_nop 0
	v_mul_f32_e32 v86, v18, v86
	v_add_f32_e32 v117, v86, v86
	v_cmp_nlt_f32_e32 vcc, s43, v117
	s_and_saveexec_b64 s[0:1], vcc
;   DI float* cf() const { return (float*)(ws + OFF_CF); }
;   DI void operator()(const f32x16 (&acc)[2][4], int mbase, int nbase, int l32, int g) const {
;     ...
;           const float gi = __builtin_amdgcn_rcpf(1.f + __expf(-(acc[0][mb][4 * j + i] + bx[i])));
;           const float gr = __builtin_amdgcn_rcpf(1.f + __expf(-(acc[1][mb][4 * j + i] + ba[i])));
;           const float la = cf[i] * gr;
;           const float x2 = 2.f * la;
;           const float ser = -x2 * (1.f + x2 * (0.5f + x2 * (0.16666667f + x2 * (0.041666668f + x2 * 0.0083333333f))));
;           const float m2 = (x2 > -0.3f) ? ser : (1.f - __expf(x2));
;           av[i] = __expf(la);
;           uv[i] = sqrtf(fmaxf(m2, 0.f)) * gi * xv[i];
;         }
;         *(f32x4*)(p->av() + tok * 1024 + ch) = av;
;         *(f32x4*)(p->uv() + tok * 1024 + ch) = uv;
	s_xor_b64 s[0:1], exec, s[0:1]
	v_mul_f32_e32 v116, 0x3fb8aa3b, v117
	v_exp_f32_e32 v116, v116
	s_nop 0
	v_sub_f32_e32 v116, 1.0, v116
	s_andn2_saveexec_b64 s[0:1], s[0:1]
	v_fmamk_f32 v116, v117, 0x3c088888, v188
	v_fmaak_f32 v116, v117, v116, 0x3e2aaaab
	v_fma_f32 v116, v117, v116, 0.5
	v_fma_f32 v116, v117, v116, 1.0
	v_mul_f32_e64 v116, v116, -v117
	s_or_b64 exec, exec, s[0:1]
	v_add_f32_e32 v87, v87, v35
	v_mul_f32_e32 v87, 0xbfb8aa3b, v87
	v_exp_f32_e32 v87, v87
	s_nop 0
	v_add_f32_e32 v87, 1.0, v87
	v_rcp_f32_e32 v87, v87
	s_nop 0
	v_mul_f32_e32 v87, v19, v87
	v_add_f32_e32 v118, v87, v87
	v_cmp_nlt_f32_e32 vcc, s43, v118
	s_and_saveexec_b64 s[0:1], vcc
	s_xor_b64 s[0:1], exec, s[0:1]
	v_mul_f32_e32 v117, 0x3fb8aa3b, v118
	v_exp_f32_e32 v117, v117
	s_nop 0
	v_sub_f32_e32 v117, 1.0, v117
	s_andn2_saveexec_b64 s[0:1], s[0:1]
	v_fmamk_f32 v117, v118, 0x3c088888, v188
	v_fmaak_f32 v117, v118, v117, 0x3e2aaaab
	v_fma_f32 v117, v118, v117, 0.5
	v_fma_f32 v117, v118, v117, 1.0
	v_mul_f32_e64 v117, v117, -v118
	s_or_b64 exec, exec, s[0:1]
	v_max_f32_e32 v102, v102, v102
	v_add_f32_e32 v68, v68, v0
	v_max_f32_e32 v102, 0, v102
	v_mul_f32_e32 v68, 0xbfb8aa3b, v68
	v_mul_f32_e32 v119, 0x4f800000, v102
	v_cmp_gt_f32_e32 vcc, s44, v102
	v_exp_f32_e32 v68, v68
	v_add_f32_e32 v69, v69, v1
	v_cndmask_b32_e32 v102, v102, v119, vcc
	v_sqrt_f32_e32 v119, v102
	v_add_f32_e32 v68, 1.0, v68
	v_rcp_f32_e32 v162, v68
	v_mul_f32_e32 v68, 0x3fb8aa3b, v84
	v_add_u32_e32 v84, -1, v119
	v_fma_f32 v163, -v84, v119, v102
	v_cmp_ge_f32_e64 s[0:1], 0, v163
	v_add_u32_e32 v163, 1, v119
	v_mul_f32_e32 v69, 0xbfb8aa3b, v69
	v_cndmask_b32_e64 v84, v119, v84, s[0:1]
	v_fma_f32 v119, -v163, v119, v102
	v_exp_f32_e32 v69, v69
	v_cmp_lt_f32_e64 s[0:1], 0, v119
	s_waitcnt vmcnt(2)
	v_mov_b32_e32 v100, v210
	v_mov_b32_e32 v101, v211
	v_lshlrev_b32_e32 v118, 16, v100
	v_add_f32_e32 v70, v70, v2
	v_cndmask_b32_e64 v84, v84, v163, s[0:1]
	v_mul_f32_e32 v119, 0x37800000, v84
	v_cndmask_b32_e32 v84, v84, v119, vcc
	v_cmp_class_f32_e32 vcc, v102, v189
	v_add_f32_e32 v69, 1.0, v69
	v_mul_f32_e32 v70, 0xbfb8aa3b, v70
	v_cndmask_b32_e32 v84, v84, v102, vcc
	v_rcp_f32_e32 v102, v69
	v_max_f32_e32 v69, v103, v103
	v_max_f32_e32 v69, 0, v69
	v_mul_f32_e32 v103, 0x4f800000, v69
	v_cmp_gt_f32_e32 vcc, s44, v69
	v_mul_f32_e32 v84, v162, v84
	v_mul_f32_e32 v84, v84, v118
	v_cndmask_b32_e32 v103, v69, v103, vcc
	v_sqrt_f32_e32 v118, v103
	v_mul_f32_e32 v69, 0x3fb8aa3b, v85
	v_exp_f32_e32 v70, v70
	v_and_b32_e32 v100, 0xffff0000, v100
	v_add_u32_e32 v85, -1, v118
	v_fma_f32 v119, -v85, v118, v103
	v_cmp_ge_f32_e64 s[0:1], 0, v119
	v_add_u32_e32 v119, 1, v118
	v_add_f32_e32 v70, 1.0, v70
	v_cndmask_b32_e64 v85, v118, v85, s[0:1]
	v_fma_f32 v118, -v119, v118, v103
	v_cmp_lt_f32_e64 s[0:1], 0, v118
	v_add_f32_e32 v71, v71, v3
	v_mul_f32_e32 v71, 0xbfb8aa3b, v71
	v_cndmask_b32_e64 v85, v85, v119, s[0:1]
	v_mul_f32_e32 v118, 0x37800000, v85
	v_cndmask_b32_e32 v85, v85, v118, vcc
	v_cmp_class_f32_e32 vcc, v103, v189
	v_exp_f32_e32 v71, v71
	v_exp_f32_e32 v68, v68
	v_cndmask_b32_e32 v85, v85, v103, vcc
	v_mul_f32_e32 v85, v102, v85
	v_mul_f32_e32 v85, v85, v100
	v_rcp_f32_e32 v100, v70
	v_max_f32_e32 v70, v116, v116
	v_max_f32_e32 v70, 0, v70
	v_mul_f32_e32 v102, 0x4f800000, v70
	v_cmp_gt_f32_e32 vcc, s44, v70
	v_add_f32_e32 v71, 1.0, v71
	v_lshlrev_b32_e32 v116, 16, v101
	v_cndmask_b32_e32 v102, v70, v102, vcc
	v_sqrt_f32_e32 v103, v102
	v_mul_f32_e32 v70, 0x3fb8aa3b, v86
	v_exp_f32_e32 v69, v69
	v_exp_f32_e32 v70, v70
	v_add_u32_e32 v86, -1, v103
	v_fma_f32 v118, -v86, v103, v102
	v_cmp_ge_f32_e64 s[0:1], 0, v118
	v_add_u32_e32 v118, 1, v103
	v_and_b32_e32 v101, 0xffff0000, v101
	v_cndmask_b32_e64 v86, v103, v86, s[0:1]
	v_fma_f32 v103, -v118, v103, v102
	v_cmp_lt_f32_e64 s[0:1], 0, v103
	v_add_f32_e32 v52, v52, v32
	v_mul_f32_e32 v52, 0xbfb8aa3b, v52
	v_cndmask_b32_e64 v86, v86, v118, s[0:1]
	v_mul_f32_e32 v103, 0x37800000, v86
	v_cndmask_b32_e32 v86, v86, v103, vcc
	v_cmp_class_f32_e32 vcc, v102, v189
	v_exp_f32_e32 v52, v52
	s_nop 0
	v_cndmask_b32_e32 v86, v86, v102, vcc
	v_mul_f32_e32 v86, v100, v86
	v_rcp_f32_e32 v100, v71
	v_max_f32_e32 v71, v117, v117
	v_max_f32_e32 v71, 0, v71
	v_mul_f32_e32 v102, 0x4f800000, v71
	v_cmp_gt_f32_e32 vcc, s44, v71
	v_mul_f32_e32 v86, v86, v116
	v_add_f32_e32 v52, 1.0, v52
	v_cndmask_b32_e32 v102, v71, v102, vcc
	v_sqrt_f32_e32 v103, v102
	v_mul_f32_e32 v71, 0x3fb8aa3b, v87
	v_exp_f32_e32 v71, v71
	v_rcp_f32_e32 v52, v52
	v_add_u32_e32 v87, -1, v103
	v_fma_f32 v116, -v87, v103, v102
	v_cmp_ge_f32_e64 s[0:1], 0, v116
	v_add_u32_e32 v116, 1, v103
	v_mul_f32_e32 v52, v16, v52
	v_cndmask_b32_e64 v87, v103, v87, s[0:1]
	v_fma_f32 v103, -v116, v103, v102
	v_cmp_lt_f32_e64 s[0:1], 0, v103
	s_nop 1
	v_cndmask_b32_e64 v87, v87, v116, s[0:1]
	v_mul_f32_e32 v103, 0x37800000, v87
	v_cndmask_b32_e32 v87, v87, v103, vcc
	v_cmp_class_f32_e32 vcc, v102, v189
	s_nop 1
	v_cndmask_b32_e32 v87, v87, v102, vcc
	v_mul_f32_e32 v87, v100, v87
	v_mul_f32_e32 v87, v87, v101
	global_load_dwordx2 v[210:211], v[80:81], off offset:16
	global_store_dwordx4 v[64:65], v[68:71], off offset:32
	global_store_dwordx4 v[66:67], v[84:87], off offset:32
	v_add_f32_e32 v71, v52, v52
	v_cmp_nlt_f32_e32 vcc, s43, v71
	s_and_saveexec_b64 s[0:1], vcc
	s_xor_b64 s[0:1], exec, s[0:1]
	v_mul_f32_e32 v70, 0x3fb8aa3b, v71
	v_exp_f32_e32 v70, v70
	s_nop 0
	v_sub_f32_e32 v70, 1.0, v70
	s_andn2_saveexec_b64 s[0:1], s[0:1]
	v_fmamk_f32 v70, v71, 0x3c088888, v188
	v_fmaak_f32 v70, v71, v70, 0x3e2aaaab
	v_fma_f32 v70, v71, v70, 0.5
	v_fma_f32 v70, v71, v70, 1.0
	v_mul_f32_e64 v70, v70, -v71
	s_or_b64 exec, exec, s[0:1]
;   DI float* cf() const { return (float*)(ws + OFF_CF); }
;   DI void operator()(const f32x16 (&acc)[2][4], int mbase, int nbase, int l32, int g) const {
;     ...
;           const float gi = __builtin_amdgcn_rcpf(1.f + __expf(-(acc[0][mb][4 * j + i] + bx[i])));
;           const float gr = __builtin_amdgcn_rcpf(1.f + __expf(-(acc[1][mb][4 * j + i] + ba[i])));
;           const float la = cf[i] * gr;
;           const float x2 = 2.f * la;
;           const float ser = -x2 * (1.f + x2 * (0.5f + x2 * (0.16666667f + x2 * (0.041666668f + x2 * 0.0083333333f))));
;           const float m2 = (x2 > -0.3f) ? ser : (1.f - __expf(x2));
;           av[i] = __expf(la);
;           uv[i] = sqrtf(fmaxf(m2, 0.f)) * gi * xv[i];
;         }
;         *(f32x4*)(p->av() + tok * 1024 + ch) = av;
;         *(f32x4*)(p->uv() + tok * 1024 + ch) = uv;
	v_add_f32_e32 v53, v53, v33
	v_mul_f32_e32 v53, 0xbfb8aa3b, v53
	v_exp_f32_e32 v53, v53
	s_nop 0
	v_add_f32_e32 v53, 1.0, v53
	v_rcp_f32_e32 v53, v53
	s_nop 0
	v_mul_f32_e32 v53, v17, v53
	v_add_f32_e32 v84, v53, v53
	v_cmp_nlt_f32_e32 vcc, s43, v84
	s_and_saveexec_b64 s[0:1], vcc
	s_xor_b64 s[0:1], exec, s[0:1]
	v_mul_f32_e32 v71, 0x3fb8aa3b, v84
	v_exp_f32_e32 v71, v71
	s_nop 0
	v_sub_f32_e32 v71, 1.0, v71
	s_andn2_saveexec_b64 s[0:1], s[0:1]
	v_fmamk_f32 v71, v84, 0x3c088888, v188
	v_fmaak_f32 v71, v84, v71, 0x3e2aaaab
	v_fma_f32 v71, v84, v71, 0.5
	v_fma_f32 v71, v84, v71, 1.0
	v_mul_f32_e64 v71, v71, -v84
	s_or_b64 exec, exec, s[0:1]
	v_add_f32_e32 v54, v54, v34
	v_mul_f32_e32 v54, 0xbfb8aa3b, v54
	v_exp_f32_e32 v54, v54
	s_nop 0
	v_add_f32_e32 v54, 1.0, v54
	v_rcp_f32_e32 v54, v54
	s_nop 0
	v_mul_f32_e32 v54, v18, v54
	v_add_f32_e32 v85, v54, v54
	v_cmp_nlt_f32_e32 vcc, s43, v85
	s_and_saveexec_b64 s[0:1], vcc
	s_xor_b64 s[0:1], exec, s[0:1]
	v_mul_f32_e32 v84, 0x3fb8aa3b, v85
	v_exp_f32_e32 v84, v84
	s_nop 0
	v_sub_f32_e32 v84, 1.0, v84
	s_andn2_saveexec_b64 s[0:1], s[0:1]
	v_fmamk_f32 v84, v85, 0x3c088888, v188
	v_fmaak_f32 v84, v85, v84, 0x3e2aaaab
	v_fma_f32 v84, v85, v84, 0.5
	v_fma_f32 v84, v85, v84, 1.0
	v_mul_f32_e64 v84, v84, -v85
	s_or_b64 exec, exec, s[0:1]
	v_add_f32_e32 v55, v55, v35
	v_mul_f32_e32 v55, 0xbfb8aa3b, v55
	v_exp_f32_e32 v55, v55
	s_nop 0
	v_add_f32_e32 v55, 1.0, v55
	v_rcp_f32_e32 v55, v55
	s_nop 0
	v_mul_f32_e32 v55, v19, v55
	v_add_f32_e32 v86, v55, v55
	v_cmp_nlt_f32_e32 vcc, s43, v86
	s_and_saveexec_b64 s[0:1], vcc
	s_xor_b64 s[0:1], exec, s[0:1]
	v_mul_f32_e32 v85, 0x3fb8aa3b, v86
	v_exp_f32_e32 v85, v85
	s_nop 0
	v_sub_f32_e32 v85, 1.0, v85
	s_andn2_saveexec_b64 s[0:1], s[0:1]
	v_fmamk_f32 v85, v86, 0x3c088888, v188
	v_fmaak_f32 v85, v86, v85, 0x3e2aaaab
	v_fma_f32 v85, v86, v85, 0.5
	v_fma_f32 v85, v86, v85, 1.0
	v_mul_f32_e64 v85, v85, -v86
	s_or_b64 exec, exec, s[0:1]
	v_max_f32_e32 v70, v70, v70
	v_add_f32_e32 v36, v36, v0
	v_max_f32_e32 v70, 0, v70
	v_mul_f32_e32 v36, 0xbfb8aa3b, v36
	v_mul_f32_e32 v87, 0x4f800000, v70
	v_cmp_gt_f32_e32 vcc, s44, v70
	v_exp_f32_e32 v36, v36
	v_add_f32_e32 v37, v37, v1
	v_cndmask_b32_e32 v70, v70, v87, vcc
	v_sqrt_f32_e32 v87, v70
	v_add_f32_e32 v36, 1.0, v36
	v_rcp_f32_e32 v100, v36
	v_mul_f32_e32 v36, 0x3fb8aa3b, v52
	v_add_u32_e32 v52, -1, v87
	v_fma_f32 v101, -v52, v87, v70
	v_cmp_ge_f32_e64 s[0:1], 0, v101
	v_add_u32_e32 v101, 1, v87
	v_mul_f32_e32 v37, 0xbfb8aa3b, v37
	v_cndmask_b32_e64 v52, v87, v52, s[0:1]
	v_fma_f32 v87, -v101, v87, v70
	v_exp_f32_e32 v37, v37
	v_cmp_lt_f32_e64 s[0:1], 0, v87
	s_waitcnt vmcnt(2)
	v_mov_b32_e32 v68, v210
	v_mov_b32_e32 v69, v211
	v_lshlrev_b32_e32 v86, 16, v68
	v_add_f32_e32 v38, v38, v2
	v_cndmask_b32_e64 v52, v52, v101, s[0:1]
	v_mul_f32_e32 v87, 0x37800000, v52
	v_cndmask_b32_e32 v52, v52, v87, vcc
	v_cmp_class_f32_e32 vcc, v70, v189
	v_add_f32_e32 v37, 1.0, v37
	v_mul_f32_e32 v38, 0xbfb8aa3b, v38
	v_cndmask_b32_e32 v52, v52, v70, vcc
	v_rcp_f32_e32 v70, v37
	v_max_f32_e32 v37, v71, v71
	v_max_f32_e32 v37, 0, v37
	v_mul_f32_e32 v71, 0x4f800000, v37
	v_cmp_gt_f32_e32 vcc, s44, v37
	v_mul_f32_e32 v52, v100, v52
	v_mul_f32_e32 v52, v52, v86
	v_cndmask_b32_e32 v71, v37, v71, vcc
	v_sqrt_f32_e32 v86, v71
	v_mul_f32_e32 v37, 0x3fb8aa3b, v53
	v_exp_f32_e32 v38, v38
	v_and_b32_e32 v68, 0xffff0000, v68
	v_add_u32_e32 v53, -1, v86
	v_fma_f32 v87, -v53, v86, v71
	v_cmp_ge_f32_e64 s[0:1], 0, v87
	v_add_u32_e32 v87, 1, v86
	v_add_f32_e32 v38, 1.0, v38
	v_cndmask_b32_e64 v53, v86, v53, s[0:1]
	v_fma_f32 v86, -v87, v86, v71
	v_cmp_lt_f32_e64 s[0:1], 0, v86
	v_add_f32_e32 v39, v39, v3
	v_mul_f32_e32 v39, 0xbfb8aa3b, v39
	v_cndmask_b32_e64 v53, v53, v87, s[0:1]
	v_mul_f32_e32 v86, 0x37800000, v53
	v_cndmask_b32_e32 v53, v53, v86, vcc
	v_cmp_class_f32_e32 vcc, v71, v189
	v_exp_f32_e32 v39, v39
	v_exp_f32_e32 v36, v36
	v_cndmask_b32_e32 v53, v53, v71, vcc
	v_mul_f32_e32 v53, v70, v53
	v_mul_f32_e32 v53, v53, v68
	v_rcp_f32_e32 v68, v38
	v_max_f32_e32 v38, v84, v84
	v_max_f32_e32 v38, 0, v38
	v_mul_f32_e32 v70, 0x4f800000, v38
	v_cmp_gt_f32_e32 vcc, s44, v38
	v_add_f32_e32 v39, 1.0, v39
	v_lshlrev_b32_e32 v84, 16, v69
	v_cndmask_b32_e32 v70, v38, v70, vcc
	v_sqrt_f32_e32 v71, v70
	v_mul_f32_e32 v38, 0x3fb8aa3b, v54
	v_exp_f32_e32 v37, v37
	v_exp_f32_e32 v38, v38
	v_add_u32_e32 v54, -1, v71
	v_fma_f32 v86, -v54, v71, v70
	v_cmp_ge_f32_e64 s[0:1], 0, v86
	v_add_u32_e32 v86, 1, v71
	v_and_b32_e32 v69, 0xffff0000, v69
	v_cndmask_b32_e64 v54, v71, v54, s[0:1]
	v_fma_f32 v71, -v86, v71, v70
	v_cmp_lt_f32_e64 s[0:1], 0, v71
	v_add_f32_e32 v20, v20, v32
	v_mul_f32_e32 v20, 0xbfb8aa3b, v20
	v_cndmask_b32_e64 v54, v54, v86, s[0:1]
	v_mul_f32_e32 v71, 0x37800000, v54
	v_cndmask_b32_e32 v54, v54, v71, vcc
	v_cmp_class_f32_e32 vcc, v70, v189
	v_exp_f32_e32 v20, v20
	s_nop 0
	v_cndmask_b32_e32 v54, v54, v70, vcc
	v_mul_f32_e32 v54, v68, v54
	v_rcp_f32_e32 v68, v39
	v_max_f32_e32 v39, v85, v85
	v_max_f32_e32 v39, 0, v39
	v_mul_f32_e32 v70, 0x4f800000, v39
	v_cmp_gt_f32_e32 vcc, s44, v39
	v_mul_f32_e32 v54, v54, v84
	v_add_f32_e32 v20, 1.0, v20
	v_cndmask_b32_e32 v70, v39, v70, vcc
	v_sqrt_f32_e32 v71, v70
	v_mul_f32_e32 v39, 0x3fb8aa3b, v55
	v_exp_f32_e32 v39, v39
	v_rcp_f32_e32 v20, v20
	v_add_u32_e32 v55, -1, v71
	v_fma_f32 v84, -v55, v71, v70
	v_cmp_ge_f32_e64 s[0:1], 0, v84
	v_add_u32_e32 v84, 1, v71
	v_mul_f32_e32 v16, v16, v20
	v_cndmask_b32_e64 v55, v71, v55, s[0:1]
	v_fma_f32 v71, -v84, v71, v70
	v_cmp_lt_f32_e64 s[0:1], 0, v71
	v_add_f32_e32 v32, v16, v16
	s_nop 0
	v_cndmask_b32_e64 v55, v55, v84, s[0:1]
	v_mul_f32_e32 v71, 0x37800000, v55
;   DI bf16_t* xc() const { return (bf16_t*)(ws + OFF_Q1); }
;   DI float* cf() const { return (float*)(ws + OFF_CF); }
; DI float bflo(unsigned u) { return __uint_as_float(u << 16); }
; DI float bfhi(unsigned u) { return __uint_as_float(u & 0xffff0000u); }
;   DI void operator()(const f32x16 (&acc)[2][4], int mbase, int nbase, int l32, int g) const {
;     ...
;       const f32x4 bx = *(const f32x4*)(p->gx_b + ch), ba = *(const f32x4*)(p->ga_b + ch), cf = *(const f32x4*)(p->cf() + ch);
; #pragma unroll
;       for (int mb = 0; mb < 4; ++mb) {
;         const size_t tok = mbase + 32 * mb + l32;
;         const u32x2 xr = *(const u32x2*)(p->xc() + tok * 1024 + ch);
;         const float xv[4] = {bflo(xr.x), bfhi(xr.x), bflo(xr.y), bfhi(xr.y)};
;         f32x4 av, uv;
; #pragma unroll
;         for (int i = 0; i < 4; ++i) {
;           const float gi = __builtin_amdgcn_rcpf(1.f + __expf(-(acc[0][mb][4 * j + i] + bx[i])));
;           const float gr = __builtin_amdgcn_rcpf(1.f + __expf(-(acc[1][mb][4 * j + i] + ba[i])));
;           const float la = cf[i] * gr;
;           const float x2 = 2.f * la;
;           const float ser = -x2 * (1.f + x2 * (0.5f + x2 * (0.16666667f + x2 * (0.041666668f + x2 * 0.0083333333f))));
;           const float m2 = (x2 > -0.3f) ? ser : (1.f - __expf(x2));
;           av[i] = __expf(la);
;           uv[i] = sqrtf(fmaxf(m2, 0.f)) * gi * xv[i];
;         }
;         *(f32x4*)(p->av() + tok * 1024 + ch) = av;
;         *(f32x4*)(p->uv() + tok * 1024 + ch) = uv;
	v_cndmask_b32_e32 v55, v55, v71, vcc
	v_cmp_class_f32_e32 vcc, v70, v189
	s_nop 1
	v_cndmask_b32_e32 v55, v55, v70, vcc
	v_mul_f32_e32 v55, v68, v55
	v_mul_f32_e32 v55, v55, v69
	global_load_dwordx2 v[210:211], v[82:83], off offset:16
	global_store_dwordx4 v[48:49], v[36:39], off offset:32
	global_store_dwordx4 v[50:51], v[52:55], off offset:32
	v_cmp_nlt_f32_e32 vcc, s43, v32
	s_and_saveexec_b64 s[0:1], vcc
	s_xor_b64 s[0:1], exec, s[0:1]
	v_mul_f32_e32 v20, 0x3fb8aa3b, v32
	v_exp_f32_e32 v20, v20
	s_nop 0
	v_sub_f32_e32 v20, 1.0, v20
	s_andn2_saveexec_b64 s[0:1], s[0:1]
	v_fmamk_f32 v20, v32, 0x3c088888, v188
	v_fmaak_f32 v20, v32, v20, 0x3e2aaaab
	v_fma_f32 v20, v32, v20, 0.5
	v_fma_f32 v20, v32, v20, 1.0
	v_mul_f32_e64 v20, v20, -v32
	s_or_b64 exec, exec, s[0:1]
	v_add_f32_e32 v21, v21, v33
	v_mul_f32_e32 v21, 0xbfb8aa3b, v21
	v_exp_f32_e32 v21, v21
	s_nop 0
	v_add_f32_e32 v21, 1.0, v21
	v_rcp_f32_e32 v21, v21
	s_nop 0
	v_mul_f32_e32 v17, v17, v21
	v_add_f32_e32 v32, v17, v17
	v_cmp_nlt_f32_e32 vcc, s43, v32
	s_and_saveexec_b64 s[0:1], vcc
	s_xor_b64 s[0:1], exec, s[0:1]
	v_mul_f32_e32 v21, 0x3fb8aa3b, v32
	v_exp_f32_e32 v21, v21
	s_nop 0
	v_sub_f32_e32 v21, 1.0, v21
	s_andn2_saveexec_b64 s[0:1], s[0:1]
	v_fmamk_f32 v21, v32, 0x3c088888, v188
	v_fmaak_f32 v21, v32, v21, 0x3e2aaaab
	v_fma_f32 v21, v32, v21, 0.5
	v_fma_f32 v21, v32, v21, 1.0
	v_mul_f32_e64 v21, v21, -v32
	s_or_b64 exec, exec, s[0:1]
	v_add_f32_e32 v22, v22, v34
	v_mul_f32_e32 v22, 0xbfb8aa3b, v22
	v_exp_f32_e32 v22, v22
	s_nop 0
	v_add_f32_e32 v22, 1.0, v22
	v_rcp_f32_e32 v22, v22
	s_nop 0
	v_mul_f32_e32 v18, v18, v22
	v_add_f32_e32 v32, v18, v18
	v_cmp_nlt_f32_e32 vcc, s43, v32
	s_and_saveexec_b64 s[0:1], vcc
	s_xor_b64 s[0:1], exec, s[0:1]
	v_mul_f32_e32 v22, 0x3fb8aa3b, v32
	v_exp_f32_e32 v22, v22
	s_nop 0
	v_sub_f32_e32 v22, 1.0, v22
	s_andn2_saveexec_b64 s[0:1], s[0:1]
	v_fmamk_f32 v22, v32, 0x3c088888, v188
	v_fmaak_f32 v22, v32, v22, 0x3e2aaaab
	v_fma_f32 v22, v32, v22, 0.5
	v_fma_f32 v22, v32, v22, 1.0
	v_mul_f32_e64 v22, v22, -v32
	s_or_b64 exec, exec, s[0:1]
	v_add_f32_e32 v23, v23, v35
	v_mul_f32_e32 v23, 0xbfb8aa3b, v23
	v_exp_f32_e32 v23, v23
	s_nop 0
	v_add_f32_e32 v23, 1.0, v23
	v_rcp_f32_e32 v23, v23
	s_nop 0
	v_mul_f32_e32 v19, v19, v23
	v_add_f32_e32 v32, v19, v19
	v_cmp_nlt_f32_e32 vcc, s43, v32
	s_and_saveexec_b64 s[0:1], vcc
	s_xor_b64 s[0:1], exec, s[0:1]
	v_mul_f32_e32 v23, 0x3fb8aa3b, v32
	v_exp_f32_e32 v23, v23
	s_nop 0
	v_sub_f32_e32 v23, 1.0, v23
	s_andn2_saveexec_b64 s[0:1], s[0:1]
	v_fmamk_f32 v23, v32, 0x3c088888, v188
	v_fmaak_f32 v23, v32, v23, 0x3e2aaaab
	v_fma_f32 v23, v32, v23, 0.5
	v_fma_f32 v23, v32, v23, 1.0
	v_mul_f32_e64 v23, v23, -v32
	s_or_b64 exec, exec, s[0:1]
	v_max_f32_e32 v20, v20, v20
	v_add_f32_e32 v0, v4, v0
	v_max_f32_e32 v20, 0, v20
	v_mul_f32_e32 v0, 0xbfb8aa3b, v0
	v_mul_f32_e32 v32, 0x4f800000, v20
	v_cmp_gt_f32_e32 vcc, s44, v20
	v_exp_f32_e32 v0, v0
	v_add_f32_e32 v1, v5, v1
	v_cndmask_b32_e32 v20, v20, v32, vcc
	v_sqrt_f32_e32 v32, v20
	v_add_f32_e32 v0, 1.0, v0
	v_rcp_f32_e32 v33, v0
	v_mul_f32_e32 v0, 0x3fb8aa3b, v16
	v_add_u32_e32 v16, -1, v32
	v_fma_f32 v34, -v16, v32, v20
	v_cmp_ge_f32_e64 s[0:1], 0, v34
	v_add_u32_e32 v34, 1, v32
	v_mul_f32_e32 v1, 0xbfb8aa3b, v1
	v_cndmask_b32_e64 v16, v32, v16, s[0:1]
	v_fma_f32 v32, -v34, v32, v20
	v_cmp_lt_f32_e64 s[0:1], 0, v32
	v_exp_f32_e32 v1, v1
	s_waitcnt vmcnt(2)
	v_mov_b32_e32 v36, v210
	v_mov_b32_e32 v37, v211
	v_lshlrev_b32_e32 v4, 16, v36
	v_cndmask_b32_e64 v16, v16, v34, s[0:1]
	v_mul_f32_e32 v32, 0x37800000, v16
	v_cndmask_b32_e32 v16, v16, v32, vcc
	v_cmp_class_f32_e32 vcc, v20, v189
	v_add_f32_e32 v1, 1.0, v1
	v_add_f32_e32 v2, v6, v2
	v_cndmask_b32_e32 v5, v16, v20, vcc
	v_mul_f32_e32 v5, v33, v5
	v_mul_f32_e32 v4, v5, v4
	v_rcp_f32_e32 v5, v1
	v_max_f32_e32 v1, v21, v21
	v_max_f32_e32 v1, 0, v1
	v_mul_f32_e32 v16, 0x4f800000, v1
	v_cmp_gt_f32_e32 vcc, s44, v1
	v_mul_f32_e32 v2, 0xbfb8aa3b, v2
	v_exp_f32_e32 v2, v2
	v_cndmask_b32_e32 v16, v1, v16, vcc
	v_sqrt_f32_e32 v20, v16
	v_mul_f32_e32 v1, 0x3fb8aa3b, v17
	v_add_f32_e32 v2, 1.0, v2
	v_and_b32_e32 v21, 0xffff0000, v36
	v_add_u32_e32 v17, -1, v20
	v_fma_f32 v32, -v17, v20, v16
	v_cmp_ge_f32_e64 s[0:1], 0, v32
	v_add_u32_e32 v32, 1, v20
	v_add_f32_e32 v3, v7, v3
	v_cndmask_b32_e64 v17, v20, v17, s[0:1]
	v_fma_f32 v20, -v32, v20, v16
	v_cmp_lt_f32_e64 s[0:1], 0, v20
	v_mul_f32_e32 v3, 0xbfb8aa3b, v3
	v_exp_f32_e32 v3, v3
	v_cndmask_b32_e64 v17, v17, v32, s[0:1]
	v_mul_f32_e32 v20, 0x37800000, v17
	v_cndmask_b32_e32 v17, v17, v20, vcc
	v_cmp_class_f32_e32 vcc, v16, v189
	v_add_f32_e32 v3, 1.0, v3
	v_lshlrev_b32_e32 v20, 16, v37
	v_cndmask_b32_e32 v6, v17, v16, vcc
	v_mul_f32_e32 v5, v5, v6
	v_rcp_f32_e32 v6, v2
	v_max_f32_e32 v2, v22, v22
	v_max_f32_e32 v2, 0, v2
	v_mul_f32_e32 v16, 0x4f800000, v2
	v_cmp_gt_f32_e32 vcc, s44, v2
	v_mul_f32_e32 v5, v5, v21
	v_exp_f32_e32 v0, v0
	v_cndmask_b32_e32 v16, v2, v16, vcc
	v_sqrt_f32_e32 v17, v16
	v_mul_f32_e32 v2, 0x3fb8aa3b, v18
	v_exp_f32_e32 v1, v1
	v_exp_f32_e32 v2, v2
	v_add_u32_e32 v18, -1, v17
	v_fma_f32 v21, -v18, v17, v16
	v_cmp_ge_f32_e64 s[0:1], 0, v21
	v_add_u32_e32 v21, 1, v17
	s_nop 0
	v_cndmask_b32_e64 v18, v17, v18, s[0:1]
	v_fma_f32 v17, -v21, v17, v16
	v_cmp_lt_f32_e64 s[0:1], 0, v17
	s_nop 1
	v_cndmask_b32_e64 v17, v18, v21, s[0:1]
	v_mul_f32_e32 v18, 0x37800000, v17
	v_cndmask_b32_e32 v17, v17, v18, vcc
	v_cmp_class_f32_e32 vcc, v16, v189
	v_and_b32_e32 v18, 0xffff0000, v37
	s_nop 0
	v_cndmask_b32_e32 v7, v17, v16, vcc
	v_mul_f32_e32 v6, v6, v7
	v_rcp_f32_e32 v7, v3
	v_max_f32_e32 v3, v23, v23
	v_max_f32_e32 v3, 0, v3
	v_mul_f32_e32 v16, 0x4f800000, v3
	v_cmp_gt_f32_e32 vcc, s44, v3
	v_mul_f32_e32 v6, v6, v20
	s_nop 0
	v_cndmask_b32_e32 v16, v3, v16, vcc
	v_sqrt_f32_e32 v17, v16
	v_mul_f32_e32 v3, 0x3fb8aa3b, v19
	v_exp_f32_e32 v3, v3
	v_add_u32_e32 v19, -1, v17
	v_fma_f32 v20, -v19, v17, v16
	v_cmp_ge_f32_e64 s[0:1], 0, v20
	v_add_u32_e32 v20, 1, v17
	s_nop 0
	v_cndmask_b32_e64 v19, v17, v19, s[0:1]
	v_fma_f32 v17, -v20, v17, v16
	v_cmp_lt_f32_e64 s[0:1], 0, v17
	s_nop 1
	v_cndmask_b32_e64 v17, v19, v20, s[0:1]
	v_mul_f32_e32 v19, 0x37800000, v17
	v_cndmask_b32_e32 v17, v17, v19, vcc
	v_cmp_class_f32_e32 vcc, v16, v189
	s_nop 1
	v_cndmask_b32_e32 v16, v17, v16, vcc
	v_mul_f32_e32 v7, v7, v16
	v_mul_f32_e32 v7, v7, v18
	v_or_b32_e32 v226, 16, v172
	v_ashrrev_i32_e32 v227, 31, v226
	v_lshl_add_u64 v[226:227], v[226:227], 2, s[10:11]
	global_load_dwordx4 v[212:215], v[174:175], off offset:64
	global_load_dwordx4 v[216:219], v[226:227], off
	global_load_dwordx4 v[220:223], v[176:177], off offset:64
	global_load_dwordx2 v[224:225], v[178:179], off offset:32
	global_store_dwordx4 v[114:115], v[0:3], off offset:32
	global_store_dwordx4 v[160:161], v[4:7], off offset:32
	v_or_b32_e32 v0, 16, v172
	v_ashrrev_i32_e32 v1, 31, v0
	v_lshl_add_u64 v[0:1], v[0:1], 2, s[10:11]
	s_nop 0
	s_waitcnt vmcnt(5)
;   DI bf16_t* xc() const { return (bf16_t*)(ws + OFF_Q1); }
;   DI float* cf() const { return (float*)(ws + OFF_CF); }
; DI float bflo(unsigned u) { return __uint_as_float(u << 16); }
; DI float bfhi(unsigned u) { return __uint_as_float(u & 0xffff0000u); }
;   DI void operator()(const f32x16 (&acc)[2][4], int mbase, int nbase, int l32, int g) const {
;     ...
;       const f32x4 bx = *(const f32x4*)(p->gx_b + ch), ba = *(const f32x4*)(p->ga_b + ch), cf = *(const f32x4*)(p->cf() + ch);
; #pragma unroll
;       for (int mb = 0; mb < 4; ++mb) {
;         const size_t tok = mbase + 32 * mb + l32;
;         const u32x2 xr = *(const u32x2*)(p->xc() + tok * 1024 + ch);
;         const float xv[4] = {bflo(xr.x), bfhi(xr.x), bflo(xr.y), bfhi(xr.y)};
;         f32x4 av, uv;
; #pragma unroll
;         for (int i = 0; i < 4; ++i) {
;           const float gi = __builtin_amdgcn_rcpf(1.f + __expf(-(acc[0][mb][4 * j + i] + bx[i])));
;           const float gr = __builtin_amdgcn_rcpf(1.f + __expf(-(acc[1][mb][4 * j + i] + ba[i])));
;           const float la = cf[i] * gr;
;           const float x2 = 2.f * la;
;           const float ser = -x2 * (1.f + x2 * (0.5f + x2 * (0.16666667f + x2 * (0.041666668f + x2 * 0.0083333333f))));
;           const float m2 = (x2 > -0.3f) ? ser : (1.f - __expf(x2));
;           av[i] = __expf(la);
;           uv[i] = sqrtf(fmaxf(m2, 0.f)) * gi * xv[i];
;         }
;         *(f32x4*)(p->av() + tok * 1024 + ch) = av;
;         *(f32x4*)(p->uv() + tok * 1024 + ch) = uv;
	v_mov_b32_e32 v16, v212
	v_mov_b32_e32 v17, v213
	v_mov_b32_e32 v18, v214
	v_mov_b32_e32 v19, v215
	v_add_f32_e32 v22, v120, v16
	v_mul_f32_e32 v22, 0xbfb8aa3b, v22
	v_exp_f32_e32 v22, v22
	s_nop 0
	v_add_f32_e32 v22, 1.0, v22
	v_rcp_f32_e32 v22, v22
	s_waitcnt vmcnt(4)
	v_mov_b32_e32 v4, v216
	v_mov_b32_e32 v5, v217
	v_mov_b32_e32 v6, v218
	v_mov_b32_e32 v7, v219
	v_mul_f32_e32 v22, v4, v22
	v_add_f32_e32 v23, v22, v22
	v_cmp_nlt_f32_e32 vcc, s43, v23
	s_and_saveexec_b64 s[0:1], vcc
	s_xor_b64 s[0:1], exec, s[0:1]
	v_mul_f32_e32 v23, 0x3fb8aa3b, v23
	v_exp_f32_e32 v23, v23
	s_nop 0
	v_sub_f32_e32 v34, 1.0, v23
	s_andn2_saveexec_b64 s[0:1], s[0:1]
	v_fmamk_f32 v32, v23, 0x3c088888, v188
	v_fmaak_f32 v32, v23, v32, 0x3e2aaaab
	v_fma_f32 v32, v23, v32, 0.5
	v_fma_f32 v32, v23, v32, 1.0
	v_mul_f32_e64 v34, v32, -v23
	s_or_b64 exec, exec, s[0:1]
	v_add_f32_e32 v23, v121, v17
	v_mul_f32_e32 v23, 0xbfb8aa3b, v23
	v_exp_f32_e32 v23, v23
	s_nop 0
	v_add_f32_e32 v23, 1.0, v23
	v_rcp_f32_e32 v23, v23
	s_nop 0
	v_mul_f32_e32 v23, v5, v23
	v_add_f32_e32 v32, v23, v23
	v_cmp_nlt_f32_e32 vcc, s43, v32
	s_and_saveexec_b64 s[0:1], vcc
	s_xor_b64 s[0:1], exec, s[0:1]
	v_mul_f32_e32 v32, 0x3fb8aa3b, v32
	v_exp_f32_e32 v32, v32
	s_nop 0
	v_sub_f32_e32 v35, 1.0, v32
	s_andn2_saveexec_b64 s[0:1], s[0:1]
	v_fmamk_f32 v33, v32, 0x3c088888, v188
	v_fmaak_f32 v33, v32, v33, 0x3e2aaaab
	v_fma_f32 v33, v32, v33, 0.5
	v_fma_f32 v33, v32, v33, 1.0
	v_mul_f32_e64 v35, v33, -v32
	s_or_b64 exec, exec, s[0:1]
	v_add_f32_e32 v32, v122, v18
	v_mul_f32_e32 v32, 0xbfb8aa3b, v32
	v_exp_f32_e32 v32, v32
	s_nop 0
	v_add_f32_e32 v32, 1.0, v32
	v_rcp_f32_e32 v32, v32
	s_nop 0
	v_mul_f32_e32 v32, v6, v32
	v_add_f32_e32 v33, v32, v32
	v_cmp_nlt_f32_e32 vcc, s43, v33
	s_and_saveexec_b64 s[0:1], vcc
	s_xor_b64 s[0:1], exec, s[0:1]
	v_mul_f32_e32 v33, 0x3fb8aa3b, v33
	v_exp_f32_e32 v33, v33
	s_nop 0
	v_sub_f32_e32 v36, 1.0, v33
	s_andn2_saveexec_b64 s[0:1], s[0:1]
	v_fmamk_f32 v36, v33, 0x3c088888, v188
	v_fmaak_f32 v36, v33, v36, 0x3e2aaaab
	v_fma_f32 v36, v33, v36, 0.5
	v_fma_f32 v36, v33, v36, 1.0
	v_mul_f32_e64 v36, v36, -v33
	s_or_b64 exec, exec, s[0:1]
	v_add_f32_e32 v33, v123, v19
	v_mul_f32_e32 v33, 0xbfb8aa3b, v33
	v_exp_f32_e32 v33, v33
	s_nop 0
	v_add_f32_e32 v33, 1.0, v33
	v_rcp_f32_e32 v33, v33
	s_nop 0
	v_mul_f32_e32 v33, v7, v33
	v_add_f32_e32 v38, v33, v33
	v_cmp_nlt_f32_e32 vcc, s43, v38
	s_and_saveexec_b64 s[0:1], vcc
	s_xor_b64 s[0:1], exec, s[0:1]
	v_mul_f32_e32 v37, 0x3fb8aa3b, v38
	v_exp_f32_e32 v37, v37
	s_nop 0
	v_sub_f32_e32 v37, 1.0, v37
	s_andn2_saveexec_b64 s[0:1], s[0:1]
	v_fmamk_f32 v37, v38, 0x3c088888, v188
	v_fmaak_f32 v37, v38, v37, 0x3e2aaaab
	v_fma_f32 v37, v38, v37, 0.5
	v_fma_f32 v37, v38, v37, 1.0
	v_mul_f32_e64 v37, v37, -v38
	s_or_b64 exec, exec, s[0:1]
	v_max_f32_e32 v34, v34, v34
	v_max_f32_e32 v34, 0, v34
	v_mul_f32_e32 v52, 0x4f800000, v34
	v_cmp_gt_f32_e32 vcc, s44, v34
	s_waitcnt vmcnt(3)
	v_mov_b32_e32 v0, v220
	v_mov_b32_e32 v1, v221
	v_mov_b32_e32 v2, v222
	v_mov_b32_e32 v3, v223
	v_add_f32_e32 v38, v104, v0
	v_mul_f32_e32 v38, 0xbfb8aa3b, v38
	v_cndmask_b32_e32 v52, v34, v52, vcc
	v_sqrt_f32_e32 v53, v52
	v_mul_f32_e32 v22, 0x3fb8aa3b, v22
	v_exp_f32_e32 v38, v38
	v_exp_f32_e32 v34, v22
	v_add_u32_e32 v22, -1, v53
	v_fma_f32 v54, -v22, v53, v52
	v_cmp_ge_f32_e64 s[0:1], 0, v54
	v_add_u32_e32 v54, 1, v53
	v_add_f32_e32 v38, 1.0, v38
	v_cndmask_b32_e64 v22, v53, v22, s[0:1]
	v_fma_f32 v53, -v54, v53, v52
	v_cmp_lt_f32_e64 s[0:1], 0, v53
	v_rcp_f32_e32 v38, v38
	v_max_f32_e32 v35, v35, v35
	v_cndmask_b32_e64 v22, v22, v54, s[0:1]
	v_mul_f32_e32 v53, 0x37800000, v22
	v_cndmask_b32_e32 v22, v22, v53, vcc
	v_cmp_class_f32_e32 vcc, v52, v189
	v_max_f32_e32 v35, 0, v35
	s_waitcnt vmcnt(2)
	v_mov_b32_e32 v20, v224
	v_mov_b32_e32 v21, v225
	v_lshlrev_b32_e32 v39, 16, v20
	v_cndmask_b32_e32 v22, v22, v52, vcc
	v_mul_f32_e32 v22, v38, v22
	v_mul_f32_e32 v38, 0x4f800000, v35
	v_cmp_gt_f32_e32 vcc, s44, v35
	v_add_f32_e32 v53, v105, v1
	v_mul_f32_e32 v53, 0xbfb8aa3b, v53
	v_cndmask_b32_e32 v38, v35, v38, vcc
	v_mul_f32_e32 v52, v22, v39
	v_sqrt_f32_e32 v39, v38
	v_exp_f32_e32 v53, v53
	v_mul_f32_e32 v23, 0x3fb8aa3b, v23
	v_exp_f32_e32 v35, v23
	v_add_u32_e32 v23, -1, v39
	v_add_f32_e32 v22, 1.0, v53
	v_fma_f32 v53, -v23, v39, v38
	v_cmp_ge_f32_e64 s[0:1], 0, v53
	v_add_u32_e32 v53, 1, v39
	v_rcp_f32_e32 v22, v22
	v_cndmask_b32_e64 v23, v39, v23, s[0:1]
	v_fma_f32 v39, -v53, v39, v38
	v_cmp_lt_f32_e64 s[0:1], 0, v39
	v_and_b32_e32 v20, 0xffff0000, v20
	v_mul_f32_e32 v32, 0x3fb8aa3b, v32
	v_cndmask_b32_e64 v23, v23, v53, s[0:1]
	v_mul_f32_e32 v39, 0x37800000, v23
	v_cndmask_b32_e32 v23, v23, v39, vcc
	v_cmp_class_f32_e32 vcc, v38, v189
	v_add_f32_e32 v39, v106, v2
	v_mul_f32_e32 v39, 0xbfb8aa3b, v39
	v_cndmask_b32_e32 v23, v23, v38, vcc
	v_mul_f32_e32 v22, v22, v23
	v_mul_f32_e32 v53, v22, v20
	v_max_f32_e32 v22, v36, v36
	v_max_f32_e32 v22, 0, v22
	v_mul_f32_e32 v23, 0x4f800000, v22
	v_cmp_gt_f32_e32 vcc, s44, v22
	v_exp_f32_e32 v39, v39
	v_exp_f32_e32 v36, v32
	v_cndmask_b32_e32 v22, v22, v23, vcc
	v_sqrt_f32_e32 v23, v22
	v_add_f32_e32 v20, 1.0, v39
	v_rcp_f32_e32 v20, v20
	v_lshlrev_b32_e32 v38, 16, v21
	v_add_u32_e32 v32, -1, v23
	v_fma_f32 v39, -v32, v23, v22
	v_cmp_ge_f32_e64 s[0:1], 0, v39
	v_add_u32_e32 v39, 1, v23
	v_and_b32_e32 v21, 0xffff0000, v21
	v_cndmask_b32_e64 v32, v23, v32, s[0:1]
	v_fma_f32 v23, -v39, v23, v22
	v_cmp_lt_f32_e64 s[0:1], 0, v23
	s_nop 1
	v_cndmask_b32_e64 v23, v32, v39, s[0:1]
	v_mul_f32_e32 v32, 0x37800000, v23
	v_cndmask_b32_e32 v23, v23, v32, vcc
	v_cmp_class_f32_e32 vcc, v22, v189
	v_add_f32_e32 v32, v107, v3
;   DI float* cf() const { return (float*)(ws + OFF_CF); }
;   DI void operator()(const f32x16 (&acc)[2][4], int mbase, int nbase, int l32, int g) const {
;     ...
;           const float gi = __builtin_amdgcn_rcpf(1.f + __expf(-(acc[0][mb][4 * j + i] + bx[i])));
;           const float gr = __builtin_amdgcn_rcpf(1.f + __expf(-(acc[1][mb][4 * j + i] + ba[i])));
;           const float la = cf[i] * gr;
;           const float x2 = 2.f * la;
;           const float ser = -x2 * (1.f + x2 * (0.5f + x2 * (0.16666667f + x2 * (0.041666668f + x2 * 0.0083333333f))));
;           const float m2 = (x2 > -0.3f) ? ser : (1.f - __expf(x2));
;           av[i] = __expf(la);
;           uv[i] = sqrtf(fmaxf(m2, 0.f)) * gi * xv[i];
;         }
;         *(f32x4*)(p->av() + tok * 1024 + ch) = av;
;         *(f32x4*)(p->uv() + tok * 1024 + ch) = uv;
	v_mul_f32_e32 v32, 0xbfb8aa3b, v32
	v_cndmask_b32_e32 v22, v23, v22, vcc
	v_mul_f32_e32 v20, v20, v22
	v_max_f32_e32 v22, v37, v37
	v_max_f32_e32 v22, 0, v22
	v_mul_f32_e32 v23, 0x4f800000, v22
	v_cmp_gt_f32_e32 vcc, s44, v22
	v_exp_f32_e32 v32, v32
	v_mul_f32_e32 v54, v20, v38
	v_cndmask_b32_e32 v22, v22, v23, vcc
	v_sqrt_f32_e32 v23, v22
	v_add_f32_e32 v20, 1.0, v32
	v_mul_f32_e32 v32, 0x3fb8aa3b, v33
	v_exp_f32_e32 v37, v32
	v_add_u32_e32 v32, -1, v23
	v_fma_f32 v33, -v32, v23, v22
	v_cmp_ge_f32_e64 s[0:1], 0, v33
	v_add_u32_e32 v33, 1, v23
	v_rcp_f32_e32 v20, v20
	v_cndmask_b32_e64 v32, v23, v32, s[0:1]
	v_fma_f32 v23, -v33, v23, v22
	v_cmp_lt_f32_e64 s[0:1], 0, v23
	s_nop 1
	v_cndmask_b32_e64 v23, v32, v33, s[0:1]
	v_mul_f32_e32 v32, 0x37800000, v23
	v_cndmask_b32_e32 v23, v23, v32, vcc
	v_cmp_class_f32_e32 vcc, v22, v189
	s_nop 1
	v_cndmask_b32_e32 v22, v23, v22, vcc
	v_mul_f32_e32 v20, v20, v22
	v_mul_f32_e32 v55, v20, v21
	global_load_dwordx2 v[210:211], v[112:113], off offset:32
	global_store_dwordx4 v[96:97], v[34:37], off offset:64
	global_store_dwordx4 v[98:99], v[52:55], off offset:64
	v_add_f32_e32 v22, v88, v16
	v_mul_f32_e32 v22, 0xbfb8aa3b, v22
	v_exp_f32_e32 v22, v22
	s_nop 0
	v_add_f32_e32 v22, 1.0, v22
	v_rcp_f32_e32 v22, v22
	s_nop 0
	v_mul_f32_e32 v22, v4, v22
	v_add_f32_e32 v23, v22, v22
	v_cmp_nlt_f32_e32 vcc, s43, v23
	s_and_saveexec_b64 s[0:1], vcc
	s_xor_b64 s[0:1], exec, s[0:1]
	v_mul_f32_e32 v23, 0x3fb8aa3b, v23
	v_exp_f32_e32 v23, v23
	s_nop 0
	v_sub_f32_e32 v34, 1.0, v23
	s_andn2_saveexec_b64 s[0:1], s[0:1]
	v_fmamk_f32 v32, v23, 0x3c088888, v188
	v_fmaak_f32 v32, v23, v32, 0x3e2aaaab
	v_fma_f32 v32, v23, v32, 0.5
	v_fma_f32 v32, v23, v32, 1.0
	v_mul_f32_e64 v34, v32, -v23
	s_or_b64 exec, exec, s[0:1]
	v_add_f32_e32 v23, v89, v17
	v_mul_f32_e32 v23, 0xbfb8aa3b, v23
	v_exp_f32_e32 v23, v23
	s_nop 0
	v_add_f32_e32 v23, 1.0, v23
	v_rcp_f32_e32 v23, v23
	s_nop 0
	v_mul_f32_e32 v23, v5, v23
	v_add_f32_e32 v32, v23, v23
	v_cmp_nlt_f32_e32 vcc, s43, v32
	s_and_saveexec_b64 s[0:1], vcc
	s_xor_b64 s[0:1], exec, s[0:1]
	v_mul_f32_e32 v32, 0x3fb8aa3b, v32
	v_exp_f32_e32 v32, v32
	s_nop 0
	v_sub_f32_e32 v35, 1.0, v32
	s_andn2_saveexec_b64 s[0:1], s[0:1]
	v_fmamk_f32 v33, v32, 0x3c088888, v188
	v_fmaak_f32 v33, v32, v33, 0x3e2aaaab
	v_fma_f32 v33, v32, v33, 0.5
	v_fma_f32 v33, v32, v33, 1.0
	v_mul_f32_e64 v35, v33, -v32
	s_or_b64 exec, exec, s[0:1]
	v_add_f32_e32 v32, v90, v18
	v_mul_f32_e32 v32, 0xbfb8aa3b, v32
	v_exp_f32_e32 v32, v32
	s_nop 0
	v_add_f32_e32 v32, 1.0, v32
	v_rcp_f32_e32 v32, v32
	s_nop 0
	v_mul_f32_e32 v32, v6, v32
	v_add_f32_e32 v33, v32, v32
	v_cmp_nlt_f32_e32 vcc, s43, v33
	s_and_saveexec_b64 s[0:1], vcc
	s_xor_b64 s[0:1], exec, s[0:1]
	v_mul_f32_e32 v33, 0x3fb8aa3b, v33
	v_exp_f32_e32 v33, v33
	s_nop 0
	v_sub_f32_e32 v36, 1.0, v33
	s_andn2_saveexec_b64 s[0:1], s[0:1]
	v_fmamk_f32 v36, v33, 0x3c088888, v188
	v_fmaak_f32 v36, v33, v36, 0x3e2aaaab
	v_fma_f32 v36, v33, v36, 0.5
	v_fma_f32 v36, v33, v36, 1.0
	v_mul_f32_e64 v36, v36, -v33
	s_or_b64 exec, exec, s[0:1]
	v_add_f32_e32 v33, v91, v19
	v_mul_f32_e32 v33, 0xbfb8aa3b, v33
	v_exp_f32_e32 v33, v33
	s_nop 0
	v_add_f32_e32 v33, 1.0, v33
	v_rcp_f32_e32 v33, v33
	s_nop 0
	v_mul_f32_e32 v33, v7, v33
	v_add_f32_e32 v38, v33, v33
	v_cmp_nlt_f32_e32 vcc, s43, v38
	s_and_saveexec_b64 s[0:1], vcc
	s_xor_b64 s[0:1], exec, s[0:1]
	v_mul_f32_e32 v37, 0x3fb8aa3b, v38
	v_exp_f32_e32 v37, v37
	s_nop 0
	v_sub_f32_e32 v37, 1.0, v37
	s_andn2_saveexec_b64 s[0:1], s[0:1]
	v_fmamk_f32 v37, v38, 0x3c088888, v188
	v_fmaak_f32 v37, v38, v37, 0x3e2aaaab
	v_fma_f32 v37, v38, v37, 0.5
	v_fma_f32 v37, v38, v37, 1.0
	v_mul_f32_e64 v37, v37, -v38
	s_or_b64 exec, exec, s[0:1]
	v_max_f32_e32 v34, v34, v34
	v_max_f32_e32 v34, 0, v34
	v_mul_f32_e32 v52, 0x4f800000, v34
	v_cmp_gt_f32_e32 vcc, s44, v34
	v_add_f32_e32 v38, v72, v0
	v_mul_f32_e32 v38, 0xbfb8aa3b, v38
	v_cndmask_b32_e32 v52, v34, v52, vcc
	v_sqrt_f32_e32 v53, v52
	v_mul_f32_e32 v22, 0x3fb8aa3b, v22
	v_exp_f32_e32 v38, v38
	v_exp_f32_e32 v34, v22
	v_add_u32_e32 v22, -1, v53
	v_fma_f32 v54, -v22, v53, v52
	v_cmp_ge_f32_e64 s[0:1], 0, v54
	v_add_u32_e32 v54, 1, v53
	v_add_f32_e32 v38, 1.0, v38
	v_cndmask_b32_e64 v22, v53, v22, s[0:1]
	v_fma_f32 v53, -v54, v53, v52
	v_cmp_lt_f32_e64 s[0:1], 0, v53
	v_rcp_f32_e32 v38, v38
	v_max_f32_e32 v35, v35, v35
	v_cndmask_b32_e64 v22, v22, v54, s[0:1]
	v_mul_f32_e32 v53, 0x37800000, v22
	v_cndmask_b32_e32 v22, v22, v53, vcc
	v_cmp_class_f32_e32 vcc, v52, v189
	v_max_f32_e32 v35, 0, v35
	s_waitcnt vmcnt(2)
;   DI float* cf() const { return (float*)(ws + OFF_CF); }
;   DI void operator()(const f32x16 (&acc)[2][4], int mbase, int nbase, int l32, int g) const {
;     ...
;           const float gi = __builtin_amdgcn_rcpf(1.f + __expf(-(acc[0][mb][4 * j + i] + bx[i])));
;           const float gr = __builtin_amdgcn_rcpf(1.f + __expf(-(acc[1][mb][4 * j + i] + ba[i])));
;           const float la = cf[i] * gr;
;           const float x2 = 2.f * la;
;           const float ser = -x2 * (1.f + x2 * (0.5f + x2 * (0.16666667f + x2 * (0.041666668f + x2 * 0.0083333333f))));
;           const float m2 = (x2 > -0.3f) ? ser : (1.f - __expf(x2));
;           av[i] = __expf(la);
;           uv[i] = sqrtf(fmaxf(m2, 0.f)) * gi * xv[i];
;         }
;         *(f32x4*)(p->av() + tok * 1024 + ch) = av;
;         *(f32x4*)(p->uv() + tok * 1024 + ch) = uv;
	v_mov_b32_e32 v20, v210
	v_mov_b32_e32 v21, v211
	v_lshlrev_b32_e32 v39, 16, v20
	v_cndmask_b32_e32 v22, v22, v52, vcc
	v_mul_f32_e32 v22, v38, v22
	v_mul_f32_e32 v38, 0x4f800000, v35
	v_cmp_gt_f32_e32 vcc, s44, v35
	v_add_f32_e32 v53, v73, v1
	v_mul_f32_e32 v53, 0xbfb8aa3b, v53
	v_cndmask_b32_e32 v38, v35, v38, vcc
	v_mul_f32_e32 v52, v22, v39
	v_sqrt_f32_e32 v39, v38
	v_exp_f32_e32 v53, v53
	v_mul_f32_e32 v23, 0x3fb8aa3b, v23
	v_exp_f32_e32 v35, v23
	v_add_u32_e32 v23, -1, v39
	v_add_f32_e32 v22, 1.0, v53
	v_fma_f32 v53, -v23, v39, v38
	v_cmp_ge_f32_e64 s[0:1], 0, v53
	v_add_u32_e32 v53, 1, v39
	v_rcp_f32_e32 v22, v22
	v_cndmask_b32_e64 v23, v39, v23, s[0:1]
	v_fma_f32 v39, -v53, v39, v38
	v_cmp_lt_f32_e64 s[0:1], 0, v39
	v_and_b32_e32 v20, 0xffff0000, v20
	v_mul_f32_e32 v32, 0x3fb8aa3b, v32
	v_cndmask_b32_e64 v23, v23, v53, s[0:1]
	v_mul_f32_e32 v39, 0x37800000, v23
	v_cndmask_b32_e32 v23, v23, v39, vcc
	v_cmp_class_f32_e32 vcc, v38, v189
	v_add_f32_e32 v39, v74, v2
	v_mul_f32_e32 v39, 0xbfb8aa3b, v39
	v_cndmask_b32_e32 v23, v23, v38, vcc
	v_mul_f32_e32 v22, v22, v23
	v_mul_f32_e32 v53, v22, v20
	v_max_f32_e32 v22, v36, v36
	v_max_f32_e32 v22, 0, v22
	v_mul_f32_e32 v23, 0x4f800000, v22
	v_cmp_gt_f32_e32 vcc, s44, v22
	v_exp_f32_e32 v39, v39
	v_exp_f32_e32 v36, v32
	v_cndmask_b32_e32 v22, v22, v23, vcc
	v_sqrt_f32_e32 v23, v22
	v_add_f32_e32 v20, 1.0, v39
	v_rcp_f32_e32 v20, v20
	v_lshlrev_b32_e32 v38, 16, v21
	v_add_u32_e32 v32, -1, v23
	v_fma_f32 v39, -v32, v23, v22
	v_cmp_ge_f32_e64 s[0:1], 0, v39
	v_add_u32_e32 v39, 1, v23
	v_and_b32_e32 v21, 0xffff0000, v21
	v_cndmask_b32_e64 v32, v23, v32, s[0:1]
	v_fma_f32 v23, -v39, v23, v22
	v_cmp_lt_f32_e64 s[0:1], 0, v23
	s_nop 1
	v_cndmask_b32_e64 v23, v32, v39, s[0:1]
	v_mul_f32_e32 v32, 0x37800000, v23
	v_cndmask_b32_e32 v23, v23, v32, vcc
	v_cmp_class_f32_e32 vcc, v22, v189
	v_add_f32_e32 v32, v75, v3
	v_mul_f32_e32 v32, 0xbfb8aa3b, v32
	v_cndmask_b32_e32 v22, v23, v22, vcc
	v_mul_f32_e32 v20, v20, v22
	v_max_f32_e32 v22, v37, v37
	v_max_f32_e32 v22, 0, v22
	v_mul_f32_e32 v23, 0x4f800000, v22
	v_cmp_gt_f32_e32 vcc, s44, v22
	v_exp_f32_e32 v32, v32
	v_mul_f32_e32 v54, v20, v38
	v_cndmask_b32_e32 v22, v22, v23, vcc
	v_sqrt_f32_e32 v23, v22
	v_add_f32_e32 v20, 1.0, v32
	v_mul_f32_e32 v32, 0x3fb8aa3b, v33
	v_exp_f32_e32 v37, v32
	v_add_u32_e32 v32, -1, v23
	v_fma_f32 v33, -v32, v23, v22
	v_cmp_ge_f32_e64 s[0:1], 0, v33
	v_add_u32_e32 v33, 1, v23
	v_rcp_f32_e32 v20, v20
	v_cndmask_b32_e64 v32, v23, v32, s[0:1]
	v_fma_f32 v23, -v33, v23, v22
	v_cmp_lt_f32_e64 s[0:1], 0, v23
	s_nop 1
	v_cndmask_b32_e64 v23, v32, v33, s[0:1]
	v_mul_f32_e32 v32, 0x37800000, v23
	v_cndmask_b32_e32 v23, v23, v32, vcc
	v_cmp_class_f32_e32 vcc, v22, v189
	s_nop 1
	v_cndmask_b32_e32 v22, v23, v22, vcc
	v_mul_f32_e32 v20, v20, v22
	v_mul_f32_e32 v55, v20, v21
	global_load_dwordx2 v[210:211], v[80:81], off offset:32
	global_store_dwordx4 v[64:65], v[34:37], off offset:64
	global_store_dwordx4 v[66:67], v[52:55], off offset:64
	v_add_f32_e32 v22, v56, v16
	v_mul_f32_e32 v22, 0xbfb8aa3b, v22
	v_exp_f32_e32 v22, v22
	s_nop 0
	v_add_f32_e32 v22, 1.0, v22
	v_rcp_f32_e32 v22, v22
	s_nop 0
	v_mul_f32_e32 v22, v4, v22
	v_add_f32_e32 v23, v22, v22
	v_cmp_nlt_f32_e32 vcc, s43, v23
	s_and_saveexec_b64 s[0:1], vcc
	s_xor_b64 s[0:1], exec, s[0:1]
	v_mul_f32_e32 v23, 0x3fb8aa3b, v23
	v_exp_f32_e32 v23, v23
	s_nop 0
	v_sub_f32_e32 v34, 1.0, v23
	s_andn2_saveexec_b64 s[0:1], s[0:1]
	v_fmamk_f32 v32, v23, 0x3c088888, v188
	v_fmaak_f32 v32, v23, v32, 0x3e2aaaab
	v_fma_f32 v32, v23, v32, 0.5
	v_fma_f32 v32, v23, v32, 1.0
	v_mul_f32_e64 v34, v32, -v23
	s_or_b64 exec, exec, s[0:1]
	v_add_f32_e32 v23, v57, v17
	v_mul_f32_e32 v23, 0xbfb8aa3b, v23
	v_exp_f32_e32 v23, v23
	s_nop 0
	v_add_f32_e32 v23, 1.0, v23
	v_rcp_f32_e32 v23, v23
	s_nop 0
	v_mul_f32_e32 v23, v5, v23
	v_add_f32_e32 v32, v23, v23
	v_cmp_nlt_f32_e32 vcc, s43, v32
	s_and_saveexec_b64 s[0:1], vcc
	s_xor_b64 s[0:1], exec, s[0:1]
	v_mul_f32_e32 v32, 0x3fb8aa3b, v32
	v_exp_f32_e32 v32, v32
	s_nop 0
	v_sub_f32_e32 v35, 1.0, v32
	s_andn2_saveexec_b64 s[0:1], s[0:1]
	v_fmamk_f32 v33, v32, 0x3c088888, v188
	v_fmaak_f32 v33, v32, v33, 0x3e2aaaab
	v_fma_f32 v33, v32, v33, 0.5
	v_fma_f32 v33, v32, v33, 1.0
	v_mul_f32_e64 v35, v33, -v32
	s_or_b64 exec, exec, s[0:1]
	v_add_f32_e32 v32, v58, v18
	v_mul_f32_e32 v32, 0xbfb8aa3b, v32
	v_exp_f32_e32 v32, v32
	s_nop 0
	v_add_f32_e32 v32, 1.0, v32
	v_rcp_f32_e32 v32, v32
	s_nop 0
	v_mul_f32_e32 v32, v6, v32
	v_add_f32_e32 v33, v32, v32
	v_cmp_nlt_f32_e32 vcc, s43, v33
	s_and_saveexec_b64 s[0:1], vcc
	s_xor_b64 s[0:1], exec, s[0:1]
	v_mul_f32_e32 v33, 0x3fb8aa3b, v33
	v_exp_f32_e32 v33, v33
	s_nop 0
	v_sub_f32_e32 v36, 1.0, v33
	s_andn2_saveexec_b64 s[0:1], s[0:1]
	v_fmamk_f32 v36, v33, 0x3c088888, v188
	v_fmaak_f32 v36, v33, v36, 0x3e2aaaab
	v_fma_f32 v36, v33, v36, 0.5
	v_fma_f32 v36, v33, v36, 1.0
	v_mul_f32_e64 v36, v36, -v33
	s_or_b64 exec, exec, s[0:1]
	v_add_f32_e32 v33, v59, v19
	v_mul_f32_e32 v33, 0xbfb8aa3b, v33
	v_exp_f32_e32 v33, v33
	s_nop 0
	v_add_f32_e32 v33, 1.0, v33
	v_rcp_f32_e32 v33, v33
	s_nop 0
	v_mul_f32_e32 v33, v7, v33
	v_add_f32_e32 v38, v33, v33
	v_cmp_nlt_f32_e32 vcc, s43, v38
	s_and_saveexec_b64 s[0:1], vcc
	s_xor_b64 s[0:1], exec, s[0:1]
	v_mul_f32_e32 v37, 0x3fb8aa3b, v38
	v_exp_f32_e32 v37, v37
	s_nop 0
	v_sub_f32_e32 v37, 1.0, v37
	s_andn2_saveexec_b64 s[0:1], s[0:1]
	v_fmamk_f32 v37, v38, 0x3c088888, v188
	v_fmaak_f32 v37, v38, v37, 0x3e2aaaab
	v_fma_f32 v37, v38, v37, 0.5
	v_fma_f32 v37, v38, v37, 1.0
	v_mul_f32_e64 v37, v37, -v38
	s_or_b64 exec, exec, s[0:1]
	v_max_f32_e32 v34, v34, v34
	v_max_f32_e32 v34, 0, v34
	v_add_f32_e32 v38, v40, v0
	v_mul_f32_e32 v40, 0x4f800000, v34
	v_cmp_gt_f32_e32 vcc, s44, v34
	v_mul_f32_e32 v38, 0xbfb8aa3b, v38
	v_mul_f32_e32 v22, 0x3fb8aa3b, v22
	v_cndmask_b32_e32 v40, v34, v40, vcc
	v_sqrt_f32_e32 v52, v40
	v_exp_f32_e32 v38, v38
	v_exp_f32_e32 v34, v22
	v_max_f32_e32 v35, v35, v35
	v_add_u32_e32 v22, -1, v52
	v_fma_f32 v53, -v22, v52, v40
	v_cmp_ge_f32_e64 s[0:1], 0, v53
	v_add_u32_e32 v53, 1, v52
	v_add_f32_e32 v38, 1.0, v38
	v_cndmask_b32_e64 v22, v52, v22, s[0:1]
	v_fma_f32 v52, -v53, v52, v40
	v_cmp_lt_f32_e64 s[0:1], 0, v52
	v_rcp_f32_e32 v38, v38
	s_waitcnt vmcnt(2)
;   DI float* cf() const { return (float*)(ws + OFF_CF); }
;   DI void operator()(const f32x16 (&acc)[2][4], int mbase, int nbase, int l32, int g) const {
;     ...
;           const float gi = __builtin_amdgcn_rcpf(1.f + __expf(-(acc[0][mb][4 * j + i] + bx[i])));
;           const float gr = __builtin_amdgcn_rcpf(1.f + __expf(-(acc[1][mb][4 * j + i] + ba[i])));
;           const float la = cf[i] * gr;
;           const float x2 = 2.f * la;
;           const float ser = -x2 * (1.f + x2 * (0.5f + x2 * (0.16666667f + x2 * (0.041666668f + x2 * 0.0083333333f))));
;           const float m2 = (x2 > -0.3f) ? ser : (1.f - __expf(x2));
;           av[i] = __expf(la);
;           uv[i] = sqrtf(fmaxf(m2, 0.f)) * gi * xv[i];
;         }
;         *(f32x4*)(p->av() + tok * 1024 + ch) = av;
;         *(f32x4*)(p->uv() + tok * 1024 + ch) = uv;
	v_mov_b32_e32 v20, v210
	v_mov_b32_e32 v21, v211
	v_lshlrev_b32_e32 v39, 16, v20
	v_cndmask_b32_e64 v22, v22, v53, s[0:1]
	v_mul_f32_e32 v52, 0x37800000, v22
	v_cndmask_b32_e32 v22, v22, v52, vcc
	v_cmp_class_f32_e32 vcc, v40, v189
	v_max_f32_e32 v35, 0, v35
	v_add_f32_e32 v41, v41, v1
	v_cndmask_b32_e32 v22, v22, v40, vcc
	v_mul_f32_e32 v22, v38, v22
	v_mul_f32_e32 v38, v22, v39
	v_mul_f32_e32 v39, 0x4f800000, v35
	v_cmp_gt_f32_e32 vcc, s44, v35
	v_mul_f32_e32 v41, 0xbfb8aa3b, v41
	v_exp_f32_e32 v41, v41
	v_cndmask_b32_e32 v39, v35, v39, vcc
	v_sqrt_f32_e32 v40, v39
	v_mul_f32_e32 v23, 0x3fb8aa3b, v23
	v_exp_f32_e32 v35, v23
	v_add_f32_e32 v22, 1.0, v41
	v_add_u32_e32 v23, -1, v40
	v_fma_f32 v41, -v23, v40, v39
	v_cmp_ge_f32_e64 s[0:1], 0, v41
	v_add_u32_e32 v41, 1, v40
	v_rcp_f32_e32 v22, v22
	v_cndmask_b32_e64 v23, v40, v23, s[0:1]
	v_fma_f32 v40, -v41, v40, v39
	v_cmp_lt_f32_e64 s[0:1], 0, v40
	v_and_b32_e32 v20, 0xffff0000, v20
	v_mul_f32_e32 v32, 0x3fb8aa3b, v32
	v_cndmask_b32_e64 v23, v23, v41, s[0:1]
	v_mul_f32_e32 v40, 0x37800000, v23
	v_cndmask_b32_e32 v23, v23, v40, vcc
	v_cmp_class_f32_e32 vcc, v39, v189
	v_add_f32_e32 v40, v42, v2
	v_mul_f32_e32 v40, 0xbfb8aa3b, v40
	v_cndmask_b32_e32 v23, v23, v39, vcc
	v_mul_f32_e32 v22, v22, v23
	v_mul_f32_e32 v39, v22, v20
	v_max_f32_e32 v22, v36, v36
	v_max_f32_e32 v22, 0, v22
	v_mul_f32_e32 v23, 0x4f800000, v22
	v_cmp_gt_f32_e32 vcc, s44, v22
	v_exp_f32_e32 v40, v40
	v_exp_f32_e32 v36, v32
	v_cndmask_b32_e32 v22, v22, v23, vcc
	v_sqrt_f32_e32 v23, v22
	v_add_f32_e32 v20, 1.0, v40
	v_rcp_f32_e32 v20, v20
	v_lshlrev_b32_e32 v40, 16, v21
	v_add_u32_e32 v32, -1, v23
	v_fma_f32 v41, -v32, v23, v22
	v_cmp_ge_f32_e64 s[0:1], 0, v41
	v_add_u32_e32 v41, 1, v23
	v_and_b32_e32 v21, 0xffff0000, v21
	v_cndmask_b32_e64 v32, v23, v32, s[0:1]
	v_fma_f32 v23, -v41, v23, v22
	v_cmp_lt_f32_e64 s[0:1], 0, v23
	v_add_f32_e32 v16, v24, v16
	v_mul_f32_e32 v16, 0xbfb8aa3b, v16
	v_cndmask_b32_e64 v23, v32, v41, s[0:1]
	v_mul_f32_e32 v32, 0x37800000, v23
	v_cndmask_b32_e32 v23, v23, v32, vcc
	v_cmp_class_f32_e32 vcc, v22, v189
	v_add_f32_e32 v32, v43, v3
	v_mul_f32_e32 v32, 0xbfb8aa3b, v32
	v_cndmask_b32_e32 v22, v23, v22, vcc
	v_mul_f32_e32 v20, v20, v22
	v_max_f32_e32 v22, v37, v37
	v_max_f32_e32 v22, 0, v22
	v_mul_f32_e32 v23, 0x4f800000, v22
	v_cmp_gt_f32_e32 vcc, s44, v22
	v_exp_f32_e32 v32, v32
	v_mul_f32_e32 v40, v20, v40
	v_cndmask_b32_e32 v22, v22, v23, vcc
	v_sqrt_f32_e32 v23, v22
	v_add_f32_e32 v20, 1.0, v32
	v_mul_f32_e32 v32, 0x3fb8aa3b, v33
	v_exp_f32_e32 v37, v32
	v_add_u32_e32 v32, -1, v23
	v_fma_f32 v33, -v32, v23, v22
	v_cmp_ge_f32_e64 s[0:1], 0, v33
	v_add_u32_e32 v33, 1, v23
	v_rcp_f32_e32 v20, v20
	v_cndmask_b32_e64 v32, v23, v32, s[0:1]
	v_fma_f32 v23, -v33, v23, v22
	v_cmp_lt_f32_e64 s[0:1], 0, v23
	v_exp_f32_e32 v16, v16
	s_nop 0
	v_cndmask_b32_e64 v23, v32, v33, s[0:1]
	v_mul_f32_e32 v32, 0x37800000, v23
	v_cndmask_b32_e32 v23, v23, v32, vcc
	v_cmp_class_f32_e32 vcc, v22, v189
	v_add_f32_e32 v16, 1.0, v16
	v_rcp_f32_e32 v16, v16
	v_cndmask_b32_e32 v22, v23, v22, vcc
	v_mul_f32_e32 v20, v20, v22
	v_mul_f32_e32 v41, v20, v21
	global_load_dwordx2 v[210:211], v[82:83], off offset:32
	global_store_dwordx4 v[48:49], v[34:37], off offset:64
	global_store_dwordx4 v[50:51], v[38:41], off offset:64
	v_mul_f32_e32 v4, v4, v16
	v_add_f32_e32 v22, v4, v4
	v_cmp_nlt_f32_e32 vcc, s43, v22
	s_and_saveexec_b64 s[0:1], vcc
	s_xor_b64 s[0:1], exec, s[0:1]
	v_mul_f32_e32 v16, 0x3fb8aa3b, v22
	v_exp_f32_e32 v16, v16
	s_nop 0
	v_sub_f32_e32 v16, 1.0, v16
	s_andn2_saveexec_b64 s[0:1], s[0:1]
	v_fmamk_f32 v16, v22, 0x3c088888, v188
	v_fmaak_f32 v16, v22, v16, 0x3e2aaaab
	v_fma_f32 v16, v22, v16, 0.5
	v_fma_f32 v16, v22, v16, 1.0
	v_mul_f32_e64 v16, v16, -v22
	s_or_b64 exec, exec, s[0:1]
	v_add_f32_e32 v17, v25, v17
	v_mul_f32_e32 v17, 0xbfb8aa3b, v17
	v_exp_f32_e32 v17, v17
	s_nop 0
	v_add_f32_e32 v17, 1.0, v17
	v_rcp_f32_e32 v17, v17
	s_nop 0
	v_mul_f32_e32 v5, v5, v17
	v_add_f32_e32 v22, v5, v5
	v_cmp_nlt_f32_e32 vcc, s43, v22
	s_and_saveexec_b64 s[0:1], vcc
	s_xor_b64 s[0:1], exec, s[0:1]
	v_mul_f32_e32 v17, 0x3fb8aa3b, v22
	v_exp_f32_e32 v17, v17
	s_nop 0
	v_sub_f32_e32 v17, 1.0, v17
	s_andn2_saveexec_b64 s[0:1], s[0:1]
	v_fmamk_f32 v17, v22, 0x3c088888, v188
	v_fmaak_f32 v17, v22, v17, 0x3e2aaaab
	v_fma_f32 v17, v22, v17, 0.5
	v_fma_f32 v17, v22, v17, 1.0
	v_mul_f32_e64 v17, v17, -v22
	s_or_b64 exec, exec, s[0:1]
	v_add_f32_e32 v18, v26, v18
	v_mul_f32_e32 v18, 0xbfb8aa3b, v18
	v_exp_f32_e32 v18, v18
	s_nop 0
	v_add_f32_e32 v18, 1.0, v18
	v_rcp_f32_e32 v18, v18
	s_nop 0
	v_mul_f32_e32 v6, v6, v18
	v_add_f32_e32 v22, v6, v6
	v_cmp_nlt_f32_e32 vcc, s43, v22
	s_and_saveexec_b64 s[0:1], vcc
	s_xor_b64 s[0:1], exec, s[0:1]
	v_mul_f32_e32 v18, 0x3fb8aa3b, v22
	v_exp_f32_e32 v18, v18
	s_nop 0
	v_sub_f32_e32 v18, 1.0, v18
	s_andn2_saveexec_b64 s[0:1], s[0:1]
	v_fmamk_f32 v18, v22, 0x3c088888, v188
	v_fmaak_f32 v18, v22, v18, 0x3e2aaaab
	v_fma_f32 v18, v22, v18, 0.5
	v_fma_f32 v18, v22, v18, 1.0
	v_mul_f32_e64 v18, v18, -v22
	s_or_b64 exec, exec, s[0:1]
	v_add_f32_e32 v19, v27, v19
	v_mul_f32_e32 v19, 0xbfb8aa3b, v19
	v_exp_f32_e32 v19, v19
	s_nop 0
	v_add_f32_e32 v19, 1.0, v19
	v_rcp_f32_e32 v19, v19
	s_nop 0
	v_mul_f32_e32 v7, v7, v19
	v_add_f32_e32 v22, v7, v7
	v_cmp_nlt_f32_e32 vcc, s43, v22
	s_and_saveexec_b64 s[0:1], vcc
	s_xor_b64 s[0:1], exec, s[0:1]
	v_mul_f32_e32 v19, 0x3fb8aa3b, v22
	v_exp_f32_e32 v19, v19
	s_nop 0
	v_sub_f32_e32 v19, 1.0, v19
	s_andn2_saveexec_b64 s[0:1], s[0:1]
	v_fmamk_f32 v19, v22, 0x3c088888, v188
	v_fmaak_f32 v19, v22, v19, 0x3e2aaaab
	v_fma_f32 v19, v22, v19, 0.5
	v_fma_f32 v19, v22, v19, 1.0
	v_mul_f32_e64 v19, v19, -v22
	s_or_b64 exec, exec, s[0:1]
	v_max_f32_e32 v16, v16, v16
	v_add_f32_e32 v0, v8, v0
	v_max_f32_e32 v16, 0, v16
	v_mul_f32_e32 v0, 0xbfb8aa3b, v0
	v_mul_f32_e32 v22, 0x4f800000, v16
	v_cmp_gt_f32_e32 vcc, s44, v16
	v_exp_f32_e32 v0, v0
	v_add_f32_e32 v1, v9, v1
	v_cndmask_b32_e32 v16, v16, v22, vcc
	v_sqrt_f32_e32 v22, v16
	v_add_f32_e32 v0, 1.0, v0
	v_rcp_f32_e32 v23, v0
	v_mul_f32_e32 v0, 0x3fb8aa3b, v4
	v_add_u32_e32 v4, -1, v22
	v_fma_f32 v24, -v4, v22, v16
	v_cmp_ge_f32_e64 s[0:1], 0, v24
	v_add_u32_e32 v24, 1, v22
	v_mul_f32_e32 v1, 0xbfb8aa3b, v1
	v_cndmask_b32_e64 v4, v22, v4, s[0:1]
	v_fma_f32 v22, -v24, v22, v16
	v_cmp_lt_f32_e64 s[0:1], 0, v22
	v_exp_f32_e32 v1, v1
	s_waitcnt vmcnt(2)
;   DI bf16_t* xc() const { return (bf16_t*)(ws + OFF_Q1); }
;   DI float* cf() const { return (float*)(ws + OFF_CF); }
; DI float bflo(unsigned u) { return __uint_as_float(u << 16); }
; DI float bfhi(unsigned u) { return __uint_as_float(u & 0xffff0000u); }
;   DI void operator()(const f32x16 (&acc)[2][4], int mbase, int nbase, int l32, int g) const {
;     ...
;       const f32x4 bx = *(const f32x4*)(p->gx_b + ch), ba = *(const f32x4*)(p->ga_b + ch), cf = *(const f32x4*)(p->cf() + ch);
; #pragma unroll
;       for (int mb = 0; mb < 4; ++mb) {
;         const size_t tok = mbase + 32 * mb + l32;
;         const u32x2 xr = *(const u32x2*)(p->xc() + tok * 1024 + ch);
;         const float xv[4] = {bflo(xr.x), bfhi(xr.x), bflo(xr.y), bfhi(xr.y)};
;         f32x4 av, uv;
; #pragma unroll
;         for (int i = 0; i < 4; ++i) {
;           const float gi = __builtin_amdgcn_rcpf(1.f + __expf(-(acc[0][mb][4 * j + i] + bx[i])));
;           const float gr = __builtin_amdgcn_rcpf(1.f + __expf(-(acc[1][mb][4 * j + i] + ba[i])));
;           const float la = cf[i] * gr;
;           const float x2 = 2.f * la;
;           const float ser = -x2 * (1.f + x2 * (0.5f + x2 * (0.16666667f + x2 * (0.041666668f + x2 * 0.0083333333f))));
;           const float m2 = (x2 > -0.3f) ? ser : (1.f - __expf(x2));
;           av[i] = __expf(la);
;           uv[i] = sqrtf(fmaxf(m2, 0.f)) * gi * xv[i];
;         }
;         *(f32x4*)(p->av() + tok * 1024 + ch) = av;
;         *(f32x4*)(p->uv() + tok * 1024 + ch) = uv;
	v_mov_b32_e32 v20, v210
	v_mov_b32_e32 v21, v211
	v_lshlrev_b32_e32 v8, 16, v20
	v_cndmask_b32_e64 v4, v4, v24, s[0:1]
	v_mul_f32_e32 v22, 0x37800000, v4
	v_cndmask_b32_e32 v4, v4, v22, vcc
	v_cmp_class_f32_e32 vcc, v16, v189
	v_add_f32_e32 v1, 1.0, v1
	v_add_f32_e32 v2, v10, v2
	v_cndmask_b32_e32 v4, v4, v16, vcc
	v_mul_f32_e32 v4, v23, v4
	v_mul_f32_e32 v4, v4, v8
	v_rcp_f32_e32 v8, v1
	v_max_f32_e32 v1, v17, v17
	v_max_f32_e32 v1, 0, v1
	v_mul_f32_e32 v9, 0x4f800000, v1
	v_cmp_gt_f32_e32 vcc, s44, v1
	v_and_b32_e32 v17, 0xffff0000, v20
	v_mul_f32_e32 v2, 0xbfb8aa3b, v2
	v_cndmask_b32_e32 v9, v1, v9, vcc
	v_sqrt_f32_e32 v16, v9
	v_mul_f32_e32 v1, 0x3fb8aa3b, v5
	v_exp_f32_e32 v2, v2
	v_add_f32_e32 v3, v11, v3
	v_add_u32_e32 v5, -1, v16
	v_fma_f32 v20, -v5, v16, v9
	v_cmp_ge_f32_e64 s[0:1], 0, v20
	v_add_u32_e32 v20, 1, v16
	v_add_f32_e32 v2, 1.0, v2
	v_cndmask_b32_e64 v5, v16, v5, s[0:1]
	v_fma_f32 v16, -v20, v16, v9
	v_cmp_lt_f32_e64 s[0:1], 0, v16
	v_mul_f32_e32 v3, 0xbfb8aa3b, v3
	v_exp_f32_e32 v3, v3
	v_cndmask_b32_e64 v5, v5, v20, s[0:1]
	v_mul_f32_e32 v16, 0x37800000, v5
	v_cndmask_b32_e32 v5, v5, v16, vcc
	v_cmp_class_f32_e32 vcc, v9, v189
	v_add_f32_e32 v3, 1.0, v3
	v_lshlrev_b32_e32 v16, 16, v21
	v_cndmask_b32_e32 v5, v5, v9, vcc
	v_mul_f32_e32 v5, v8, v5
	v_rcp_f32_e32 v8, v2
	v_max_f32_e32 v2, v18, v18
	v_max_f32_e32 v2, 0, v2
	v_mul_f32_e32 v9, 0x4f800000, v2
	v_cmp_gt_f32_e32 vcc, s44, v2
	v_mul_f32_e32 v5, v5, v17
	v_exp_f32_e32 v0, v0
	v_cndmask_b32_e32 v9, v2, v9, vcc
	v_sqrt_f32_e32 v10, v9
	v_mul_f32_e32 v2, 0x3fb8aa3b, v6
	v_exp_f32_e32 v1, v1
	v_exp_f32_e32 v2, v2
	v_add_u32_e32 v6, -1, v10
	v_fma_f32 v17, -v6, v10, v9
	v_cmp_ge_f32_e64 s[0:1], 0, v17
	v_add_u32_e32 v17, 1, v10
	v_and_b32_e32 v11, 0xffff0000, v21
	v_cndmask_b32_e64 v6, v10, v6, s[0:1]
	v_fma_f32 v10, -v17, v10, v9
	v_cmp_lt_f32_e64 s[0:1], 0, v10
	s_nop 1
	v_cndmask_b32_e64 v6, v6, v17, s[0:1]
	v_mul_f32_e32 v10, 0x37800000, v6
	v_cndmask_b32_e32 v6, v6, v10, vcc
	v_cmp_class_f32_e32 vcc, v9, v189
	s_nop 1
	v_cndmask_b32_e32 v6, v6, v9, vcc
	v_mul_f32_e32 v6, v8, v6
	v_rcp_f32_e32 v8, v3
	v_max_f32_e32 v3, v19, v19
	v_max_f32_e32 v3, 0, v3
	v_mul_f32_e32 v9, 0x4f800000, v3
	v_cmp_gt_f32_e32 vcc, s44, v3
	v_mul_f32_e32 v6, v6, v16
	s_nop 0
	v_cndmask_b32_e32 v9, v3, v9, vcc
	v_sqrt_f32_e32 v10, v9
	v_mul_f32_e32 v3, 0x3fb8aa3b, v7
	v_exp_f32_e32 v3, v3
	v_add_u32_e32 v7, -1, v10
	v_fma_f32 v16, -v7, v10, v9
	v_cmp_ge_f32_e64 s[0:1], 0, v16
	v_add_u32_e32 v16, 1, v10
	s_nop 0
	v_cndmask_b32_e64 v7, v10, v7, s[0:1]
	v_fma_f32 v10, -v16, v10, v9
	v_cmp_lt_f32_e64 s[0:1], 0, v10
	s_nop 1
	v_cndmask_b32_e64 v7, v7, v16, s[0:1]
	v_mul_f32_e32 v10, 0x37800000, v7
	v_cndmask_b32_e32 v7, v7, v10, vcc
	v_cmp_class_f32_e32 vcc, v9, v189
	s_nop 1
	v_cndmask_b32_e32 v7, v7, v9, vcc
	v_mul_f32_e32 v7, v8, v7
	v_mul_f32_e32 v7, v7, v11
	v_or_b32_e32 v226, 24, v172
	v_ashrrev_i32_e32 v227, 31, v226
	v_lshl_add_u64 v[226:227], v[226:227], 2, s[10:11]
	global_load_dwordx4 v[212:215], v[174:175], off offset:96
	global_load_dwordx4 v[216:219], v[226:227], off
	global_load_dwordx4 v[220:223], v[176:177], off offset:96
	global_load_dwordx2 v[224:225], v[178:179], off offset:48
	global_store_dwordx4 v[114:115], v[0:3], off offset:64
	global_store_dwordx4 v[160:161], v[4:7], off offset:64
	v_or_b32_e32 v0, 24, v172
	v_ashrrev_i32_e32 v1, 31, v0
	v_lshl_add_u64 v[0:1], v[0:1], 2, s[10:11]
	s_nop 0
	s_waitcnt vmcnt(5)
	v_mov_b32_e32 v8, v212
	v_mov_b32_e32 v9, v213
	v_mov_b32_e32 v10, v214
	v_mov_b32_e32 v11, v215
	v_add_f32_e32 v18, v124, v8
	v_mul_f32_e32 v18, 0xbfb8aa3b, v18
	v_exp_f32_e32 v18, v18
	s_nop 0
	v_add_f32_e32 v18, 1.0, v18
	v_rcp_f32_e32 v18, v18
	s_waitcnt vmcnt(4)
	v_mov_b32_e32 v4, v216
	v_mov_b32_e32 v5, v217
	v_mov_b32_e32 v6, v218
	v_mov_b32_e32 v7, v219
	v_mul_f32_e32 v18, v4, v18
	v_add_f32_e32 v19, v18, v18
	v_cmp_nlt_f32_e32 vcc, s43, v19
	s_and_saveexec_b64 s[0:1], vcc
	s_xor_b64 s[0:1], exec, s[0:1]
	v_mul_f32_e32 v19, 0x3fb8aa3b, v19
	v_exp_f32_e32 v19, v19
	s_nop 0
	v_sub_f32_e32 v22, 1.0, v19
	s_andn2_saveexec_b64 s[0:1], s[0:1]
	v_fmamk_f32 v20, v19, 0x3c088888, v188
	v_fmaak_f32 v20, v19, v20, 0x3e2aaaab
	v_fma_f32 v20, v19, v20, 0.5
	v_fma_f32 v20, v19, v20, 1.0
	v_mul_f32_e64 v22, v20, -v19
	s_or_b64 exec, exec, s[0:1]
	v_add_f32_e32 v19, v125, v9
	v_mul_f32_e32 v19, 0xbfb8aa3b, v19
	v_exp_f32_e32 v19, v19
	s_nop 0
	v_add_f32_e32 v19, 1.0, v19
	v_rcp_f32_e32 v19, v19
	s_nop 0
	v_mul_f32_e32 v19, v5, v19
	v_add_f32_e32 v20, v19, v19
	v_cmp_nlt_f32_e32 vcc, s43, v20
	s_and_saveexec_b64 s[0:1], vcc
	s_xor_b64 s[0:1], exec, s[0:1]
	v_mul_f32_e32 v20, 0x3fb8aa3b, v20
	v_exp_f32_e32 v20, v20
	s_nop 0
	v_sub_f32_e32 v23, 1.0, v20
	s_andn2_saveexec_b64 s[0:1], s[0:1]
	v_fmamk_f32 v21, v20, 0x3c088888, v188
	v_fmaak_f32 v21, v20, v21, 0x3e2aaaab
	v_fma_f32 v21, v20, v21, 0.5
	v_fma_f32 v21, v20, v21, 1.0
	v_mul_f32_e64 v23, v21, -v20
	s_or_b64 exec, exec, s[0:1]
	v_add_f32_e32 v20, v126, v10
	v_mul_f32_e32 v20, 0xbfb8aa3b, v20
	v_exp_f32_e32 v20, v20
	s_nop 0
	v_add_f32_e32 v20, 1.0, v20
	v_rcp_f32_e32 v20, v20
	s_nop 0
	v_mul_f32_e32 v20, v6, v20
	v_add_f32_e32 v21, v20, v20
	v_cmp_nlt_f32_e32 vcc, s43, v21
	s_and_saveexec_b64 s[0:1], vcc
	s_xor_b64 s[0:1], exec, s[0:1]
	v_mul_f32_e32 v21, 0x3fb8aa3b, v21
	v_exp_f32_e32 v21, v21
	s_nop 0
	v_sub_f32_e32 v24, 1.0, v21
	s_andn2_saveexec_b64 s[0:1], s[0:1]
	v_fmamk_f32 v24, v21, 0x3c088888, v188
	v_fmaak_f32 v24, v21, v24, 0x3e2aaaab
	v_fma_f32 v24, v21, v24, 0.5
	v_fma_f32 v24, v21, v24, 1.0
	v_mul_f32_e64 v24, v24, -v21
	s_or_b64 exec, exec, s[0:1]
	v_add_f32_e32 v21, v127, v11
	v_mul_f32_e32 v21, 0xbfb8aa3b, v21
	v_exp_f32_e32 v21, v21
	s_nop 0
	v_add_f32_e32 v21, 1.0, v21
	v_rcp_f32_e32 v21, v21
	s_nop 0
	v_mul_f32_e32 v21, v7, v21
	v_add_f32_e32 v26, v21, v21
	v_cmp_nlt_f32_e32 vcc, s43, v26
	s_and_saveexec_b64 s[0:1], vcc
	s_xor_b64 s[0:1], exec, s[0:1]
	v_mul_f32_e32 v25, 0x3fb8aa3b, v26
	v_exp_f32_e32 v25, v25
	s_nop 0
	v_sub_f32_e32 v25, 1.0, v25
	s_andn2_saveexec_b64 s[0:1], s[0:1]
	v_fmamk_f32 v25, v26, 0x3c088888, v188
	v_fmaak_f32 v25, v26, v25, 0x3e2aaaab
	v_fma_f32 v25, v26, v25, 0.5
	v_fma_f32 v25, v26, v25, 1.0
	v_mul_f32_e64 v25, v25, -v26
	s_or_b64 exec, exec, s[0:1]
	v_max_f32_e32 v22, v22, v22
	v_max_f32_e32 v22, 0, v22
	v_mul_f32_e32 v32, 0x4f800000, v22
	v_cmp_gt_f32_e32 vcc, s44, v22
	s_waitcnt vmcnt(3)
;   DI bf16_t* xc() const { return (bf16_t*)(ws + OFF_Q1); }
;   DI float* cf() const { return (float*)(ws + OFF_CF); }
; DI float bflo(unsigned u) { return __uint_as_float(u << 16); }
; DI float bfhi(unsigned u) { return __uint_as_float(u & 0xffff0000u); }
;   DI void operator()(const f32x16 (&acc)[2][4], int mbase, int nbase, int l32, int g) const {
;     ...
;       const f32x4 bx = *(const f32x4*)(p->gx_b + ch), ba = *(const f32x4*)(p->ga_b + ch), cf = *(const f32x4*)(p->cf() + ch);
; #pragma unroll
;       for (int mb = 0; mb < 4; ++mb) {
;         const size_t tok = mbase + 32 * mb + l32;
;         const u32x2 xr = *(const u32x2*)(p->xc() + tok * 1024 + ch);
;         const float xv[4] = {bflo(xr.x), bfhi(xr.x), bflo(xr.y), bfhi(xr.y)};
;         f32x4 av, uv;
; #pragma unroll
;         for (int i = 0; i < 4; ++i) {
;           const float gi = __builtin_amdgcn_rcpf(1.f + __expf(-(acc[0][mb][4 * j + i] + bx[i])));
;           const float gr = __builtin_amdgcn_rcpf(1.f + __expf(-(acc[1][mb][4 * j + i] + ba[i])));
;           const float la = cf[i] * gr;
;           const float x2 = 2.f * la;
;           const float ser = -x2 * (1.f + x2 * (0.5f + x2 * (0.16666667f + x2 * (0.041666668f + x2 * 0.0083333333f))));
;           const float m2 = (x2 > -0.3f) ? ser : (1.f - __expf(x2));
;           av[i] = __expf(la);
;           uv[i] = sqrtf(fmaxf(m2, 0.f)) * gi * xv[i];
;         }
;         *(f32x4*)(p->av() + tok * 1024 + ch) = av;
;         *(f32x4*)(p->uv() + tok * 1024 + ch) = uv;
	v_mov_b32_e32 v0, v220
	v_mov_b32_e32 v1, v221
	v_mov_b32_e32 v2, v222
	v_mov_b32_e32 v3, v223
	v_add_f32_e32 v26, v108, v0
	v_mul_f32_e32 v26, 0xbfb8aa3b, v26
	v_cndmask_b32_e32 v22, v22, v32, vcc
	v_sqrt_f32_e32 v32, v22
	v_exp_f32_e32 v26, v26
	v_max_f32_e32 v23, v23, v23
	s_waitcnt vmcnt(2)
	v_mov_b32_e32 v16, v224
	v_mov_b32_e32 v17, v225
	v_lshlrev_b32_e32 v27, 16, v16
	v_add_u32_e32 v33, -1, v32
	v_fma_f32 v34, -v33, v32, v22
	v_cmp_ge_f32_e64 s[0:1], 0, v34
	v_add_u32_e32 v34, 1, v32
	v_add_f32_e32 v26, 1.0, v26
	v_cndmask_b32_e64 v33, v32, v33, s[0:1]
	v_fma_f32 v32, -v34, v32, v22
	v_cmp_lt_f32_e64 s[0:1], 0, v32
	v_rcp_f32_e32 v26, v26
	v_max_f32_e32 v23, 0, v23
	v_cndmask_b32_e64 v32, v33, v34, s[0:1]
	v_mul_f32_e32 v33, 0x37800000, v32
	v_cndmask_b32_e32 v32, v32, v33, vcc
	v_cmp_class_f32_e32 vcc, v22, v189
	v_add_f32_e32 v33, v109, v1
	v_mul_f32_e32 v33, 0xbfb8aa3b, v33
	v_cndmask_b32_e32 v22, v32, v22, vcc
	v_mul_f32_e32 v22, v26, v22
	v_mul_f32_e32 v22, v22, v27
	v_mul_f32_e32 v27, 0x4f800000, v23
	v_cmp_gt_f32_e32 vcc, s44, v23
	v_exp_f32_e32 v33, v33
	v_max_f32_e32 v24, v24, v24
	v_cndmask_b32_e32 v23, v23, v27, vcc
	v_sqrt_f32_e32 v27, v23
	v_add_f32_e32 v26, 1.0, v33
	v_rcp_f32_e32 v26, v26
	v_max_f32_e32 v24, 0, v24
	v_add_u32_e32 v32, -1, v27
	v_fma_f32 v33, -v32, v27, v23
	v_cmp_ge_f32_e64 s[0:1], 0, v33
	v_add_u32_e32 v33, 1, v27
	v_and_b32_e32 v16, 0xffff0000, v16
	v_cndmask_b32_e64 v32, v27, v32, s[0:1]
	v_fma_f32 v27, -v33, v27, v23
	v_cmp_lt_f32_e64 s[0:1], 0, v27
	v_max_f32_e32 v25, v25, v25
	v_max_f32_e32 v25, 0, v25
	v_cndmask_b32_e64 v27, v32, v33, s[0:1]
	v_mul_f32_e32 v32, 0x37800000, v27
	v_cndmask_b32_e32 v27, v27, v32, vcc
	v_cmp_class_f32_e32 vcc, v23, v189
	v_add_f32_e32 v32, v110, v2
	v_mul_f32_e32 v32, 0xbfb8aa3b, v32
	v_cndmask_b32_e32 v23, v27, v23, vcc
	v_mul_f32_e32 v23, v26, v23
	v_mul_f32_e32 v26, 0x4f800000, v24
	v_cmp_gt_f32_e32 vcc, s44, v24
	v_exp_f32_e32 v32, v32
	v_mul_f32_e32 v23, v23, v16
	v_cndmask_b32_e32 v24, v24, v26, vcc
	v_sqrt_f32_e32 v26, v24
	v_add_f32_e32 v16, 1.0, v32
	v_rcp_f32_e32 v16, v16
	v_lshlrev_b32_e32 v27, 16, v17
	v_add_u32_e32 v32, -1, v26
	v_fma_f32 v33, -v32, v26, v24
	v_cmp_ge_f32_e64 s[0:1], 0, v33
	v_add_u32_e32 v33, 1, v26
	v_mul_f32_e32 v18, 0x3fb8aa3b, v18
	v_cndmask_b32_e64 v32, v26, v32, s[0:1]
	v_fma_f32 v26, -v33, v26, v24
	v_cmp_lt_f32_e64 s[0:1], 0, v26
	v_mul_f32_e32 v19, 0x3fb8aa3b, v19
	v_mul_f32_e32 v20, 0x3fb8aa3b, v20
	v_cndmask_b32_e64 v26, v32, v33, s[0:1]
	v_mul_f32_e32 v32, 0x37800000, v26
	v_cndmask_b32_e32 v26, v26, v32, vcc
	v_cmp_class_f32_e32 vcc, v24, v189
	v_add_f32_e32 v32, v111, v3
	v_mul_f32_e32 v32, 0xbfb8aa3b, v32
	v_cndmask_b32_e32 v24, v26, v24, vcc
	v_mul_f32_e32 v26, 0x4f800000, v25
	v_cmp_gt_f32_e32 vcc, s44, v25
	v_exp_f32_e32 v32, v32
	v_mul_f32_e32 v16, v16, v24
	v_cndmask_b32_e32 v25, v25, v26, vcc
	v_sqrt_f32_e32 v26, v25
	v_mul_f32_e32 v24, v16, v27
	v_add_f32_e32 v16, 1.0, v32
	v_rcp_f32_e32 v16, v16
	v_add_u32_e32 v27, -1, v26
	v_fma_f32 v32, -v27, v26, v25
	v_cmp_ge_f32_e64 s[0:1], 0, v32
	v_add_u32_e32 v32, 1, v26
	v_mul_f32_e32 v21, 0x3fb8aa3b, v21
	v_cndmask_b32_e64 v27, v26, v27, s[0:1]
	v_fma_f32 v26, -v32, v26, v25
	v_cmp_lt_f32_e64 s[0:1], 0, v26
	v_exp_f32_e32 v18, v18
	v_exp_f32_e32 v19, v19
	v_cndmask_b32_e64 v26, v27, v32, s[0:1]
	v_exp_f32_e32 v20, v20
	v_exp_f32_e32 v21, v21
	v_mul_f32_e32 v27, 0x37800000, v26
	v_cndmask_b32_e32 v26, v26, v27, vcc
	v_cmp_class_f32_e32 vcc, v25, v189
	v_and_b32_e32 v17, 0xffff0000, v17
	s_nop 0
	v_cndmask_b32_e32 v25, v26, v25, vcc
	v_mul_f32_e32 v16, v16, v25
	v_mul_f32_e32 v25, v16, v17
	global_load_dwordx2 v[210:211], v[112:113], off offset:48
	global_store_dwordx4 v[96:97], v[18:21], off offset:96
	global_store_dwordx4 v[98:99], v[22:25], off offset:96
	v_add_f32_e32 v18, v92, v8
	v_mul_f32_e32 v18, 0xbfb8aa3b, v18
	v_exp_f32_e32 v18, v18
	s_nop 0
	v_add_f32_e32 v18, 1.0, v18
	v_rcp_f32_e32 v18, v18
	s_nop 0
	v_mul_f32_e32 v18, v4, v18
	v_add_f32_e32 v19, v18, v18
	v_cmp_nlt_f32_e32 vcc, s43, v19
	s_and_saveexec_b64 s[0:1], vcc
	s_xor_b64 s[0:1], exec, s[0:1]
	v_mul_f32_e32 v19, 0x3fb8aa3b, v19
	v_exp_f32_e32 v19, v19
	s_nop 0
	v_sub_f32_e32 v22, 1.0, v19
	s_andn2_saveexec_b64 s[0:1], s[0:1]
	v_fmamk_f32 v20, v19, 0x3c088888, v188
	v_fmaak_f32 v20, v19, v20, 0x3e2aaaab
	v_fma_f32 v20, v19, v20, 0.5
	v_fma_f32 v20, v19, v20, 1.0
	v_mul_f32_e64 v22, v20, -v19
	s_or_b64 exec, exec, s[0:1]
	v_add_f32_e32 v19, v93, v9
	v_mul_f32_e32 v19, 0xbfb8aa3b, v19
	v_exp_f32_e32 v19, v19
	s_nop 0
	v_add_f32_e32 v19, 1.0, v19
	v_rcp_f32_e32 v19, v19
	s_nop 0
	v_mul_f32_e32 v19, v5, v19
	v_add_f32_e32 v20, v19, v19
	v_cmp_nlt_f32_e32 vcc, s43, v20
	s_and_saveexec_b64 s[0:1], vcc
	s_xor_b64 s[0:1], exec, s[0:1]
	v_mul_f32_e32 v20, 0x3fb8aa3b, v20
	v_exp_f32_e32 v20, v20
	s_nop 0
	v_sub_f32_e32 v23, 1.0, v20
	s_andn2_saveexec_b64 s[0:1], s[0:1]
	v_fmamk_f32 v21, v20, 0x3c088888, v188
	v_fmaak_f32 v21, v20, v21, 0x3e2aaaab
	v_fma_f32 v21, v20, v21, 0.5
	v_fma_f32 v21, v20, v21, 1.0
	v_mul_f32_e64 v23, v21, -v20
	s_or_b64 exec, exec, s[0:1]
	v_add_f32_e32 v20, v94, v10
	v_mul_f32_e32 v20, 0xbfb8aa3b, v20
	v_exp_f32_e32 v20, v20
	s_nop 0
	v_add_f32_e32 v20, 1.0, v20
	v_rcp_f32_e32 v20, v20
	s_nop 0
	v_mul_f32_e32 v20, v6, v20
	v_add_f32_e32 v21, v20, v20
	v_cmp_nlt_f32_e32 vcc, s43, v21
	s_and_saveexec_b64 s[0:1], vcc
	s_xor_b64 s[0:1], exec, s[0:1]
	v_mul_f32_e32 v21, 0x3fb8aa3b, v21
	v_exp_f32_e32 v21, v21
	s_nop 0
	v_sub_f32_e32 v24, 1.0, v21
	s_andn2_saveexec_b64 s[0:1], s[0:1]
	v_fmamk_f32 v24, v21, 0x3c088888, v188
	v_fmaak_f32 v24, v21, v24, 0x3e2aaaab
	v_fma_f32 v24, v21, v24, 0.5
	v_fma_f32 v24, v21, v24, 1.0
	v_mul_f32_e64 v24, v24, -v21
	s_or_b64 exec, exec, s[0:1]
	v_add_f32_e32 v21, v95, v11
	v_mul_f32_e32 v21, 0xbfb8aa3b, v21
	v_exp_f32_e32 v21, v21
	s_nop 0
	v_add_f32_e32 v21, 1.0, v21
	v_rcp_f32_e32 v21, v21
	s_nop 0
	v_mul_f32_e32 v21, v7, v21
	v_add_f32_e32 v26, v21, v21
	v_cmp_nlt_f32_e32 vcc, s43, v26
	s_and_saveexec_b64 s[0:1], vcc
	s_xor_b64 s[0:1], exec, s[0:1]
	v_mul_f32_e32 v25, 0x3fb8aa3b, v26
	v_exp_f32_e32 v25, v25
	s_nop 0
	v_sub_f32_e32 v25, 1.0, v25
	s_andn2_saveexec_b64 s[0:1], s[0:1]
	v_fmamk_f32 v25, v26, 0x3c088888, v188
	v_fmaak_f32 v25, v26, v25, 0x3e2aaaab
	v_fma_f32 v25, v26, v25, 0.5
	v_fma_f32 v25, v26, v25, 1.0
	v_mul_f32_e64 v25, v25, -v26
	s_or_b64 exec, exec, s[0:1]
	v_max_f32_e32 v22, v22, v22
	v_max_f32_e32 v22, 0, v22
	v_mul_f32_e32 v32, 0x4f800000, v22
	v_cmp_gt_f32_e32 vcc, s44, v22
	v_add_f32_e32 v26, v76, v0
	v_mul_f32_e32 v26, 0xbfb8aa3b, v26
	v_cndmask_b32_e32 v22, v22, v32, vcc
	v_sqrt_f32_e32 v32, v22
	v_exp_f32_e32 v26, v26
	v_max_f32_e32 v23, v23, v23
	s_waitcnt vmcnt(2)
;   DI float* cf() const { return (float*)(ws + OFF_CF); }
;   DI void operator()(const f32x16 (&acc)[2][4], int mbase, int nbase, int l32, int g) const {
;     ...
;           const float gi = __builtin_amdgcn_rcpf(1.f + __expf(-(acc[0][mb][4 * j + i] + bx[i])));
;           const float gr = __builtin_amdgcn_rcpf(1.f + __expf(-(acc[1][mb][4 * j + i] + ba[i])));
;           const float la = cf[i] * gr;
;           const float x2 = 2.f * la;
;           const float ser = -x2 * (1.f + x2 * (0.5f + x2 * (0.16666667f + x2 * (0.041666668f + x2 * 0.0083333333f))));
;           const float m2 = (x2 > -0.3f) ? ser : (1.f - __expf(x2));
;           av[i] = __expf(la);
;           uv[i] = sqrtf(fmaxf(m2, 0.f)) * gi * xv[i];
;         }
;         *(f32x4*)(p->av() + tok * 1024 + ch) = av;
;         *(f32x4*)(p->uv() + tok * 1024 + ch) = uv;
	v_mov_b32_e32 v16, v210
	v_mov_b32_e32 v17, v211
	v_lshlrev_b32_e32 v27, 16, v16
	v_add_u32_e32 v33, -1, v32
	v_fma_f32 v34, -v33, v32, v22
	v_cmp_ge_f32_e64 s[0:1], 0, v34
	v_add_u32_e32 v34, 1, v32
	v_add_f32_e32 v26, 1.0, v26
	v_cndmask_b32_e64 v33, v32, v33, s[0:1]
	v_fma_f32 v32, -v34, v32, v22
	v_cmp_lt_f32_e64 s[0:1], 0, v32
	v_rcp_f32_e32 v26, v26
	v_max_f32_e32 v23, 0, v23
	v_cndmask_b32_e64 v32, v33, v34, s[0:1]
	v_mul_f32_e32 v33, 0x37800000, v32
	v_cndmask_b32_e32 v32, v32, v33, vcc
	v_cmp_class_f32_e32 vcc, v22, v189
	v_add_f32_e32 v33, v77, v1
	v_mul_f32_e32 v33, 0xbfb8aa3b, v33
	v_cndmask_b32_e32 v22, v32, v22, vcc
	v_mul_f32_e32 v22, v26, v22
	v_mul_f32_e32 v22, v22, v27
	v_mul_f32_e32 v27, 0x4f800000, v23
	v_cmp_gt_f32_e32 vcc, s44, v23
	v_exp_f32_e32 v33, v33
	v_max_f32_e32 v24, v24, v24
	v_cndmask_b32_e32 v23, v23, v27, vcc
	v_sqrt_f32_e32 v27, v23
	v_add_f32_e32 v26, 1.0, v33
	v_rcp_f32_e32 v26, v26
	v_max_f32_e32 v24, 0, v24
	v_add_u32_e32 v32, -1, v27
	v_fma_f32 v33, -v32, v27, v23
	v_cmp_ge_f32_e64 s[0:1], 0, v33
	v_add_u32_e32 v33, 1, v27
	v_and_b32_e32 v16, 0xffff0000, v16
	v_cndmask_b32_e64 v32, v27, v32, s[0:1]
	v_fma_f32 v27, -v33, v27, v23
	v_cmp_lt_f32_e64 s[0:1], 0, v27
	v_max_f32_e32 v25, v25, v25
	v_max_f32_e32 v25, 0, v25
	v_cndmask_b32_e64 v27, v32, v33, s[0:1]
	v_mul_f32_e32 v32, 0x37800000, v27
	v_cndmask_b32_e32 v27, v27, v32, vcc
	v_cmp_class_f32_e32 vcc, v23, v189
	v_add_f32_e32 v32, v78, v2
	v_mul_f32_e32 v32, 0xbfb8aa3b, v32
	v_cndmask_b32_e32 v23, v27, v23, vcc
	v_mul_f32_e32 v23, v26, v23
	v_mul_f32_e32 v26, 0x4f800000, v24
	v_cmp_gt_f32_e32 vcc, s44, v24
	v_exp_f32_e32 v32, v32
	v_mul_f32_e32 v23, v23, v16
	v_cndmask_b32_e32 v24, v24, v26, vcc
	v_sqrt_f32_e32 v26, v24
	v_add_f32_e32 v16, 1.0, v32
	v_rcp_f32_e32 v16, v16
	v_lshlrev_b32_e32 v27, 16, v17
	v_add_u32_e32 v32, -1, v26
	v_fma_f32 v33, -v32, v26, v24
	v_cmp_ge_f32_e64 s[0:1], 0, v33
	v_add_u32_e32 v33, 1, v26
	v_mul_f32_e32 v18, 0x3fb8aa3b, v18
	v_cndmask_b32_e64 v32, v26, v32, s[0:1]
	v_fma_f32 v26, -v33, v26, v24
	v_cmp_lt_f32_e64 s[0:1], 0, v26
	v_mul_f32_e32 v19, 0x3fb8aa3b, v19
	v_mul_f32_e32 v20, 0x3fb8aa3b, v20
	v_cndmask_b32_e64 v26, v32, v33, s[0:1]
	v_mul_f32_e32 v32, 0x37800000, v26
	v_cndmask_b32_e32 v26, v26, v32, vcc
	v_cmp_class_f32_e32 vcc, v24, v189
	v_add_f32_e32 v32, v79, v3
	v_mul_f32_e32 v32, 0xbfb8aa3b, v32
	v_cndmask_b32_e32 v24, v26, v24, vcc
	v_mul_f32_e32 v26, 0x4f800000, v25
	v_cmp_gt_f32_e32 vcc, s44, v25
	v_exp_f32_e32 v32, v32
	v_mul_f32_e32 v16, v16, v24
	v_cndmask_b32_e32 v25, v25, v26, vcc
	v_sqrt_f32_e32 v26, v25
	v_mul_f32_e32 v24, v16, v27
	v_add_f32_e32 v16, 1.0, v32
	v_rcp_f32_e32 v16, v16
	v_add_u32_e32 v27, -1, v26
	v_fma_f32 v32, -v27, v26, v25
	v_cmp_ge_f32_e64 s[0:1], 0, v32
	v_add_u32_e32 v32, 1, v26
	v_mul_f32_e32 v21, 0x3fb8aa3b, v21
	v_cndmask_b32_e64 v27, v26, v27, s[0:1]
	v_fma_f32 v26, -v32, v26, v25
	v_cmp_lt_f32_e64 s[0:1], 0, v26
	v_exp_f32_e32 v18, v18
	v_exp_f32_e32 v19, v19
	v_cndmask_b32_e64 v26, v27, v32, s[0:1]
	v_exp_f32_e32 v20, v20
	v_exp_f32_e32 v21, v21
	v_mul_f32_e32 v27, 0x37800000, v26
	v_cndmask_b32_e32 v26, v26, v27, vcc
	v_cmp_class_f32_e32 vcc, v25, v189
	v_and_b32_e32 v17, 0xffff0000, v17
	s_nop 0
	v_cndmask_b32_e32 v25, v26, v25, vcc
	v_mul_f32_e32 v16, v16, v25
	v_mul_f32_e32 v25, v16, v17
	global_load_dwordx2 v[210:211], v[80:81], off offset:48
	global_store_dwordx4 v[64:65], v[18:21], off offset:96
	global_store_dwordx4 v[66:67], v[22:25], off offset:96
	v_add_f32_e32 v18, v60, v8
	v_mul_f32_e32 v18, 0xbfb8aa3b, v18
	v_exp_f32_e32 v18, v18
	s_nop 0
	v_add_f32_e32 v18, 1.0, v18
	v_rcp_f32_e32 v18, v18
	s_nop 0
	v_mul_f32_e32 v18, v4, v18
	v_add_f32_e32 v19, v18, v18
	v_cmp_nlt_f32_e32 vcc, s43, v19
	s_and_saveexec_b64 s[0:1], vcc
	s_xor_b64 s[0:1], exec, s[0:1]
	v_mul_f32_e32 v19, 0x3fb8aa3b, v19
	v_exp_f32_e32 v19, v19
	s_nop 0
	v_sub_f32_e32 v22, 1.0, v19
	s_andn2_saveexec_b64 s[0:1], s[0:1]
	v_fmamk_f32 v20, v19, 0x3c088888, v188
	v_fmaak_f32 v20, v19, v20, 0x3e2aaaab
	v_fma_f32 v20, v19, v20, 0.5
	v_fma_f32 v20, v19, v20, 1.0
	v_mul_f32_e64 v22, v20, -v19
	s_or_b64 exec, exec, s[0:1]
	v_add_f32_e32 v19, v61, v9
	v_mul_f32_e32 v19, 0xbfb8aa3b, v19
	v_exp_f32_e32 v19, v19
	s_nop 0
	v_add_f32_e32 v19, 1.0, v19
	v_rcp_f32_e32 v19, v19
	s_nop 0
	v_mul_f32_e32 v19, v5, v19
	v_add_f32_e32 v20, v19, v19
	v_cmp_nlt_f32_e32 vcc, s43, v20
	s_and_saveexec_b64 s[0:1], vcc
	s_xor_b64 s[0:1], exec, s[0:1]
	v_mul_f32_e32 v20, 0x3fb8aa3b, v20
	v_exp_f32_e32 v20, v20
	s_nop 0
	v_sub_f32_e32 v23, 1.0, v20
	s_andn2_saveexec_b64 s[0:1], s[0:1]
	v_fmamk_f32 v21, v20, 0x3c088888, v188
	v_fmaak_f32 v21, v20, v21, 0x3e2aaaab
	v_fma_f32 v21, v20, v21, 0.5
	v_fma_f32 v21, v20, v21, 1.0
	v_mul_f32_e64 v23, v21, -v20
	s_or_b64 exec, exec, s[0:1]
	v_add_f32_e32 v20, v62, v10
	v_mul_f32_e32 v20, 0xbfb8aa3b, v20
	v_exp_f32_e32 v20, v20
	s_nop 0
	v_add_f32_e32 v20, 1.0, v20
	v_rcp_f32_e32 v20, v20
	s_nop 0
	v_mul_f32_e32 v20, v6, v20
	v_add_f32_e32 v21, v20, v20
	v_cmp_nlt_f32_e32 vcc, s43, v21
	s_and_saveexec_b64 s[0:1], vcc
	s_xor_b64 s[0:1], exec, s[0:1]
	v_mul_f32_e32 v21, 0x3fb8aa3b, v21
	v_exp_f32_e32 v21, v21
	s_nop 0
	v_sub_f32_e32 v24, 1.0, v21
	s_andn2_saveexec_b64 s[0:1], s[0:1]
	v_fmamk_f32 v24, v21, 0x3c088888, v188
	v_fmaak_f32 v24, v21, v24, 0x3e2aaaab
	v_fma_f32 v24, v21, v24, 0.5
	v_fma_f32 v24, v21, v24, 1.0
	v_mul_f32_e64 v24, v24, -v21
	s_or_b64 exec, exec, s[0:1]
	v_add_f32_e32 v21, v63, v11
	v_mul_f32_e32 v21, 0xbfb8aa3b, v21
	v_exp_f32_e32 v21, v21
	s_nop 0
	v_add_f32_e32 v21, 1.0, v21
	v_rcp_f32_e32 v21, v21
	s_nop 0
	v_mul_f32_e32 v21, v7, v21
	v_add_f32_e32 v26, v21, v21
	v_cmp_nlt_f32_e32 vcc, s43, v26
	s_and_saveexec_b64 s[0:1], vcc
	s_xor_b64 s[0:1], exec, s[0:1]
	v_mul_f32_e32 v25, 0x3fb8aa3b, v26
	v_exp_f32_e32 v25, v25
	s_nop 0
	v_sub_f32_e32 v25, 1.0, v25
	s_andn2_saveexec_b64 s[0:1], s[0:1]
	v_fmamk_f32 v25, v26, 0x3c088888, v188
	v_fmaak_f32 v25, v26, v25, 0x3e2aaaab
	v_fma_f32 v25, v26, v25, 0.5
	v_fma_f32 v25, v26, v25, 1.0
	v_mul_f32_e64 v25, v25, -v26
	s_or_b64 exec, exec, s[0:1]
	v_max_f32_e32 v22, v22, v22
	v_max_f32_e32 v22, 0, v22
	v_mul_f32_e32 v32, 0x4f800000, v22
	v_cmp_gt_f32_e32 vcc, s44, v22
	v_add_f32_e32 v26, v44, v0
	v_mul_f32_e32 v26, 0xbfb8aa3b, v26
	v_cndmask_b32_e32 v22, v22, v32, vcc
	v_sqrt_f32_e32 v32, v22
	v_exp_f32_e32 v26, v26
	v_max_f32_e32 v23, v23, v23
	s_waitcnt vmcnt(2)
;   DI float* cf() const { return (float*)(ws + OFF_CF); }
;   DI void operator()(const f32x16 (&acc)[2][4], int mbase, int nbase, int l32, int g) const {
;     ...
;           const float gi = __builtin_amdgcn_rcpf(1.f + __expf(-(acc[0][mb][4 * j + i] + bx[i])));
;           const float gr = __builtin_amdgcn_rcpf(1.f + __expf(-(acc[1][mb][4 * j + i] + ba[i])));
;           const float la = cf[i] * gr;
;           const float x2 = 2.f * la;
;           const float ser = -x2 * (1.f + x2 * (0.5f + x2 * (0.16666667f + x2 * (0.041666668f + x2 * 0.0083333333f))));
;           const float m2 = (x2 > -0.3f) ? ser : (1.f - __expf(x2));
;           av[i] = __expf(la);
;           uv[i] = sqrtf(fmaxf(m2, 0.f)) * gi * xv[i];
;         }
;         *(f32x4*)(p->av() + tok * 1024 + ch) = av;
;         *(f32x4*)(p->uv() + tok * 1024 + ch) = uv;
	v_mov_b32_e32 v16, v210
	v_mov_b32_e32 v17, v211
	v_lshlrev_b32_e32 v27, 16, v16
	v_add_u32_e32 v33, -1, v32
	v_fma_f32 v34, -v33, v32, v22
	v_cmp_ge_f32_e64 s[0:1], 0, v34
	v_add_u32_e32 v34, 1, v32
	v_add_f32_e32 v26, 1.0, v26
	v_cndmask_b32_e64 v33, v32, v33, s[0:1]
	v_fma_f32 v32, -v34, v32, v22
	v_cmp_lt_f32_e64 s[0:1], 0, v32
	v_rcp_f32_e32 v26, v26
	v_max_f32_e32 v23, 0, v23
	v_cndmask_b32_e64 v32, v33, v34, s[0:1]
	v_mul_f32_e32 v33, 0x37800000, v32
	v_cndmask_b32_e32 v32, v32, v33, vcc
	v_cmp_class_f32_e32 vcc, v22, v189
	v_add_f32_e32 v33, v45, v1
	v_mul_f32_e32 v33, 0xbfb8aa3b, v33
	v_cndmask_b32_e32 v22, v32, v22, vcc
	v_mul_f32_e32 v22, v26, v22
	v_mul_f32_e32 v22, v22, v27
	v_mul_f32_e32 v27, 0x4f800000, v23
	v_cmp_gt_f32_e32 vcc, s44, v23
	v_exp_f32_e32 v33, v33
	v_max_f32_e32 v24, v24, v24
	v_cndmask_b32_e32 v23, v23, v27, vcc
	v_sqrt_f32_e32 v27, v23
	v_add_f32_e32 v26, 1.0, v33
	v_rcp_f32_e32 v26, v26
	v_max_f32_e32 v24, 0, v24
	v_add_u32_e32 v32, -1, v27
	v_fma_f32 v33, -v32, v27, v23
	v_cmp_ge_f32_e64 s[0:1], 0, v33
	v_add_u32_e32 v33, 1, v27
	v_and_b32_e32 v16, 0xffff0000, v16
	v_cndmask_b32_e64 v32, v27, v32, s[0:1]
	v_fma_f32 v27, -v33, v27, v23
	v_cmp_lt_f32_e64 s[0:1], 0, v27
	v_max_f32_e32 v25, v25, v25
	v_max_f32_e32 v25, 0, v25
	v_cndmask_b32_e64 v27, v32, v33, s[0:1]
	v_mul_f32_e32 v32, 0x37800000, v27
	v_cndmask_b32_e32 v27, v27, v32, vcc
	v_cmp_class_f32_e32 vcc, v23, v189
	v_add_f32_e32 v32, v46, v2
	v_mul_f32_e32 v32, 0xbfb8aa3b, v32
	v_cndmask_b32_e32 v23, v27, v23, vcc
	v_mul_f32_e32 v23, v26, v23
	v_mul_f32_e32 v26, 0x4f800000, v24
	v_cmp_gt_f32_e32 vcc, s44, v24
	v_exp_f32_e32 v32, v32
	v_mul_f32_e32 v23, v23, v16
	v_cndmask_b32_e32 v24, v24, v26, vcc
	v_sqrt_f32_e32 v26, v24
	v_add_f32_e32 v16, 1.0, v32
	v_rcp_f32_e32 v16, v16
	v_lshlrev_b32_e32 v27, 16, v17
	v_add_u32_e32 v32, -1, v26
	v_fma_f32 v33, -v32, v26, v24
	v_cmp_ge_f32_e64 s[0:1], 0, v33
	v_add_u32_e32 v33, 1, v26
	v_mul_f32_e32 v18, 0x3fb8aa3b, v18
	v_cndmask_b32_e64 v32, v26, v32, s[0:1]
	v_fma_f32 v26, -v33, v26, v24
	v_cmp_lt_f32_e64 s[0:1], 0, v26
	v_mul_f32_e32 v19, 0x3fb8aa3b, v19
	v_mul_f32_e32 v20, 0x3fb8aa3b, v20
	v_cndmask_b32_e64 v26, v32, v33, s[0:1]
	v_mul_f32_e32 v32, 0x37800000, v26
	v_cndmask_b32_e32 v26, v26, v32, vcc
	v_cmp_class_f32_e32 vcc, v24, v189
	v_add_f32_e32 v32, v47, v3
	v_mul_f32_e32 v32, 0xbfb8aa3b, v32
	v_cndmask_b32_e32 v24, v26, v24, vcc
	v_mul_f32_e32 v26, 0x4f800000, v25
	v_cmp_gt_f32_e32 vcc, s44, v25
	v_exp_f32_e32 v32, v32
	v_mul_f32_e32 v16, v16, v24
	v_cndmask_b32_e32 v25, v25, v26, vcc
	v_sqrt_f32_e32 v26, v25
	v_mul_f32_e32 v24, v16, v27
	v_add_f32_e32 v16, 1.0, v32
	v_rcp_f32_e32 v16, v16
	v_add_u32_e32 v27, -1, v26
	v_fma_f32 v32, -v27, v26, v25
	v_cmp_ge_f32_e64 s[0:1], 0, v32
	v_add_u32_e32 v32, 1, v26
	v_mul_f32_e32 v21, 0x3fb8aa3b, v21
	v_cndmask_b32_e64 v27, v26, v27, s[0:1]
	v_fma_f32 v26, -v32, v26, v25
	v_cmp_lt_f32_e64 s[0:1], 0, v26
	v_exp_f32_e32 v18, v18
	v_exp_f32_e32 v19, v19
	v_cndmask_b32_e64 v26, v27, v32, s[0:1]
	v_exp_f32_e32 v20, v20
	v_exp_f32_e32 v21, v21
	v_mul_f32_e32 v27, 0x37800000, v26
	v_cndmask_b32_e32 v26, v26, v27, vcc
	v_cmp_class_f32_e32 vcc, v25, v189
	v_and_b32_e32 v17, 0xffff0000, v17
	v_add_f32_e32 v8, v28, v8
	v_cndmask_b32_e32 v25, v26, v25, vcc
	v_mul_f32_e32 v16, v16, v25
	v_mul_f32_e32 v25, v16, v17
	global_store_dwordx4 v[48:49], v[18:21], off offset:96
	global_store_dwordx4 v[50:51], v[22:25], off offset:96
	global_load_dwordx2 v[16:17], v[82:83], off offset:48
	v_mul_f32_e32 v8, 0xbfb8aa3b, v8
	v_exp_f32_e32 v8, v8
	s_nop 0
	v_add_f32_e32 v8, 1.0, v8
	v_rcp_f32_e32 v8, v8
	s_nop 0
	v_mul_f32_e32 v4, v4, v8
	v_add_f32_e32 v18, v4, v4
	v_cmp_nlt_f32_e32 vcc, s43, v18
	s_and_saveexec_b64 s[0:1], vcc
	s_xor_b64 s[0:1], exec, s[0:1]
	v_mul_f32_e32 v8, 0x3fb8aa3b, v18
	v_exp_f32_e32 v8, v8
	s_nop 0
	v_sub_f32_e32 v8, 1.0, v8
	s_andn2_saveexec_b64 s[0:1], s[0:1]
	v_fmamk_f32 v8, v18, 0x3c088888, v188
	v_fmaak_f32 v8, v18, v8, 0x3e2aaaab
	v_fma_f32 v8, v18, v8, 0.5
	v_fma_f32 v8, v18, v8, 1.0
	v_mul_f32_e64 v8, v8, -v18
	s_or_b64 exec, exec, s[0:1]
	v_add_f32_e32 v9, v29, v9
	v_mul_f32_e32 v9, 0xbfb8aa3b, v9
	v_exp_f32_e32 v9, v9
	s_nop 0
	v_add_f32_e32 v9, 1.0, v9
	v_rcp_f32_e32 v9, v9
	s_nop 0
	v_mul_f32_e32 v5, v5, v9
	v_add_f32_e32 v18, v5, v5
	v_cmp_nlt_f32_e32 vcc, s43, v18
	s_and_saveexec_b64 s[0:1], vcc
	s_xor_b64 s[0:1], exec, s[0:1]
	v_mul_f32_e32 v9, 0x3fb8aa3b, v18
	v_exp_f32_e32 v9, v9
	s_nop 0
	v_sub_f32_e32 v9, 1.0, v9
	s_andn2_saveexec_b64 s[0:1], s[0:1]
	v_fmamk_f32 v9, v18, 0x3c088888, v188
	v_fmaak_f32 v9, v18, v9, 0x3e2aaaab
	v_fma_f32 v9, v18, v9, 0.5
	v_fma_f32 v9, v18, v9, 1.0
	v_mul_f32_e64 v9, v9, -v18
	s_or_b64 exec, exec, s[0:1]
	v_add_f32_e32 v10, v30, v10
	v_mul_f32_e32 v10, 0xbfb8aa3b, v10
	v_exp_f32_e32 v10, v10
	s_nop 0
	v_add_f32_e32 v10, 1.0, v10
	v_rcp_f32_e32 v10, v10
	s_nop 0
	v_mul_f32_e32 v6, v6, v10
	v_add_f32_e32 v18, v6, v6
	v_cmp_nlt_f32_e32 vcc, s43, v18
	s_and_saveexec_b64 s[0:1], vcc
	s_xor_b64 s[0:1], exec, s[0:1]
	v_mul_f32_e32 v10, 0x3fb8aa3b, v18
	v_exp_f32_e32 v10, v10
	s_nop 0
	v_sub_f32_e32 v10, 1.0, v10
	s_andn2_saveexec_b64 s[0:1], s[0:1]
	v_fmamk_f32 v10, v18, 0x3c088888, v188
	v_fmaak_f32 v10, v18, v10, 0x3e2aaaab
	v_fma_f32 v10, v18, v10, 0.5
	v_fma_f32 v10, v18, v10, 1.0
	v_mul_f32_e64 v10, v10, -v18
	s_or_b64 exec, exec, s[0:1]
	v_add_f32_e32 v11, v31, v11
	v_mul_f32_e32 v11, 0xbfb8aa3b, v11
	v_exp_f32_e32 v11, v11
	s_nop 0
	v_add_f32_e32 v11, 1.0, v11
	v_rcp_f32_e32 v11, v11
	s_nop 0
	v_mul_f32_e32 v7, v7, v11
	v_add_f32_e32 v18, v7, v7
	v_cmp_nlt_f32_e32 vcc, s43, v18
	s_and_saveexec_b64 s[0:1], vcc
	s_xor_b64 s[0:1], exec, s[0:1]
	v_mul_f32_e32 v11, 0x3fb8aa3b, v18
	v_exp_f32_e32 v11, v11
	s_nop 0
	v_sub_f32_e32 v11, 1.0, v11
	s_andn2_saveexec_b64 s[0:1], s[0:1]
	s_cbranch_execz .LBB0_286
	v_fmamk_f32 v11, v18, 0x3c088888, v188
	v_fmaak_f32 v11, v18, v11, 0x3e2aaaab
	v_fma_f32 v11, v18, v11, 0.5
	v_fma_f32 v11, v18, v11, 1.0
	v_mul_f32_e64 v11, v11, -v18
	s_branch .LBB0_286
